# inproj exact-GELU epilogue re-emitted branch-free and two-way interleaved (same arithmetic); sg_prompt item: the 16 serialized w_s operand loads hoisted in front of the two-pass MFMA loop
# speedup vs baseline: 1.1667x; 1.0065x over previous
.LBB0_112:
	s_or_b64 exec, exec, s[0:1]
	s_mov_b32 s3, 0x2aaaaaab
	v_mul_hi_i32 v3, v2, s3
	v_lshrrev_b32_e32 v4, 31, v3
	v_ashrrev_i32_e32 v3, 2, v3
	v_add_u32_e32 v71, v3, v4
	v_mul_lo_u32 v3, v71, 24
	v_mov_b32_e32 v1, v80
	v_sub_u32_e32 v72, v2, v3
	v_add_u32_e32 v3, s8, v71
	v_mov_b64_e32 v[4:5], s[4:5]
	v_mad_i64_i32 v[6:7], s[0:1], v3, s46, v[4:5]
	v_lshlrev_b64 v[48:49], 1, v[0:1]
	v_lshl_add_u64 v[0:1], v[6:7], 0, v[48:49]
	v_lshlrev_b32_e32 v6, 3, v72
	v_ashrrev_i32_e32 v7, 31, v6
	v_add_u32_e32 v3, 0x100, v2
	v_lshl_add_u64 v[0:1], v[6:7], 1, v[0:1]
	v_mul_hi_i32 v6, v3, s3
	v_lshrrev_b32_e32 v7, 31, v6
	v_ashrrev_i32_e32 v6, 2, v6
	v_add_u32_e32 v81, v6, v7
	v_mul_lo_u32 v6, v81, 24
	v_sub_u32_e32 v86, v3, v6
	v_add_u32_e32 v3, s8, v81
	v_mad_i64_i32 v[6:7], s[0:1], v3, s46, v[4:5]
	v_lshlrev_b32_e32 v8, 3, v86
	v_lshl_add_u64 v[6:7], v[6:7], 0, v[48:49]
	v_ashrrev_i32_e32 v9, 31, v8
	s_waitcnt lgkmcnt(0)
	s_barrier
	v_lshl_add_u64 v[6:7], v[8:9], 1, v[6:7]
	global_load_dwordx4 v[44:47], v[0:1], off offset:1536
	global_load_dwordx4 v[40:43], v[6:7], off offset:1536
	v_add_u32_e32 v0, 0x200, v2
	v_mul_hi_i32 v1, v0, s3
	v_lshrrev_b32_e32 v3, 31, v1
	v_ashrrev_i32_e32 v1, 2, v1
	v_add_u32_e32 v87, v1, v3
	v_mul_lo_u32 v1, v87, 24
	v_sub_u32_e32 v88, v0, v1
	v_add_u32_e32 v0, s8, v87
	v_mad_i64_i32 v[0:1], s[0:1], v0, s46, v[4:5]
	v_lshlrev_b32_e32 v6, 3, v88
	v_lshl_add_u64 v[0:1], v[0:1], 0, v[48:49]
	v_ashrrev_i32_e32 v7, 31, v6
	v_add_u32_e32 v3, 0x300, v2
	v_lshl_add_u64 v[0:1], v[6:7], 1, v[0:1]
	v_mul_hi_i32 v6, v3, s3
	v_lshrrev_b32_e32 v7, 31, v6
	v_ashrrev_i32_e32 v6, 2, v6
	v_add_u32_e32 v89, v6, v7
	v_mul_lo_u32 v6, v89, 24
	v_sub_u32_e32 v90, v3, v6
	v_add_u32_e32 v3, s8, v89
	v_mad_i64_i32 v[6:7], s[0:1], v3, s46, v[4:5]
	v_lshlrev_b32_e32 v8, 3, v90
	v_lshl_add_u64 v[6:7], v[6:7], 0, v[48:49]
	v_ashrrev_i32_e32 v9, 31, v8
	v_lshl_add_u64 v[6:7], v[8:9], 1, v[6:7]
	global_load_dwordx4 v[36:39], v[0:1], off offset:1536
	global_load_dwordx4 v[32:35], v[6:7], off offset:1536
	v_add_u32_e32 v0, 0x400, v2
	v_mul_hi_i32 v1, v0, s3
	v_lshrrev_b32_e32 v3, 31, v1
	v_ashrrev_i32_e32 v1, 2, v1
	v_add_u32_e32 v69, v1, v3
	v_mul_lo_u32 v1, v69, 24
	v_sub_u32_e32 v70, v0, v1
	v_add_u32_e32 v0, s8, v69
	v_mad_i64_i32 v[0:1], s[0:1], v0, s46, v[4:5]
	v_lshlrev_b32_e32 v6, 3, v70
	v_lshl_add_u64 v[0:1], v[0:1], 0, v[48:49]
	v_ashrrev_i32_e32 v7, 31, v6
	v_add_u32_e32 v3, 0x500, v2
	v_lshl_add_u64 v[0:1], v[6:7], 1, v[0:1]
	v_mul_hi_i32 v6, v3, s3
	v_lshrrev_b32_e32 v7, 31, v6
	v_ashrrev_i32_e32 v6, 2, v6
	v_add_u32_e32 v67, v6, v7
	v_mul_lo_u32 v6, v67, 24
	v_sub_u32_e32 v68, v3, v6
	v_add_u32_e32 v3, s8, v67
	v_mad_i64_i32 v[6:7], s[0:1], v3, s46, v[4:5]
	v_lshlrev_b32_e32 v8, 3, v68
	v_lshl_add_u64 v[6:7], v[6:7], 0, v[48:49]
	v_ashrrev_i32_e32 v9, 31, v8
	v_lshl_add_u64 v[6:7], v[8:9], 1, v[6:7]
	global_load_dwordx4 v[28:31], v[0:1], off offset:1536
	global_load_dwordx4 v[24:27], v[6:7], off offset:1536
	v_add_u32_e32 v0, 0x600, v2
	v_mul_hi_i32 v1, v0, s3
	v_lshrrev_b32_e32 v3, 31, v1
	v_ashrrev_i32_e32 v1, 2, v1
	v_add_u32_e32 v65, v1, v3
	v_mul_lo_u32 v1, v65, 24
	v_sub_u32_e32 v66, v0, v1
	v_add_u32_e32 v0, s8, v65
	v_mad_i64_i32 v[0:1], s[0:1], v0, s46, v[4:5]
	v_lshlrev_b32_e32 v6, 3, v66
	v_lshl_add_u64 v[0:1], v[0:1], 0, v[48:49]
	v_ashrrev_i32_e32 v7, 31, v6
	v_add_u32_e32 v3, 0x700, v2
	v_lshl_add_u64 v[0:1], v[6:7], 1, v[0:1]
	v_mul_hi_i32 v6, v3, s3
	v_lshrrev_b32_e32 v7, 31, v6
	v_ashrrev_i32_e32 v6, 2, v6
	v_add_u32_e32 v63, v6, v7
	v_mul_lo_u32 v6, v63, 24
	v_sub_u32_e32 v64, v3, v6
	v_add_u32_e32 v3, s8, v63
	v_mad_i64_i32 v[6:7], s[0:1], v3, s46, v[4:5]
	v_lshlrev_b32_e32 v8, 3, v64
	v_lshl_add_u64 v[6:7], v[6:7], 0, v[48:49]
	v_ashrrev_i32_e32 v9, 31, v8
	v_lshl_add_u64 v[6:7], v[8:9], 1, v[6:7]
	global_load_dwordx4 v[20:23], v[0:1], off offset:1536
	global_load_dwordx4 v[16:19], v[6:7], off offset:1536
	v_add_u32_e32 v0, 0x800, v2
	v_mul_hi_i32 v1, v0, s3
	v_lshrrev_b32_e32 v3, 31, v1
	v_ashrrev_i32_e32 v1, 2, v1
	v_add_u32_e32 v61, v1, v3
	v_mul_lo_u32 v1, v61, 24
	v_sub_u32_e32 v62, v0, v1
	v_add_u32_e32 v0, s8, v61
	v_mad_i64_i32 v[0:1], s[0:1], v0, s46, v[4:5]
	v_lshlrev_b32_e32 v6, 3, v62
	v_lshl_add_u64 v[0:1], v[0:1], 0, v[48:49]
	v_ashrrev_i32_e32 v7, 31, v6
	v_add_u32_e32 v3, 0x900, v2
	v_lshl_add_u64 v[0:1], v[6:7], 1, v[0:1]
	v_mul_hi_i32 v6, v3, s3
	v_lshrrev_b32_e32 v7, 31, v6
	v_ashrrev_i32_e32 v6, 2, v6
	v_add_u32_e32 v59, v6, v7
	v_mul_lo_u32 v6, v59, 24
	v_sub_u32_e32 v60, v3, v6
	v_add_u32_e32 v3, s8, v59
	v_mad_i64_i32 v[6:7], s[0:1], v3, s46, v[4:5]
	v_lshlrev_b32_e32 v8, 3, v60
	v_lshl_add_u64 v[6:7], v[6:7], 0, v[48:49]
	v_ashrrev_i32_e32 v9, 31, v8
	v_lshl_add_u64 v[6:7], v[8:9], 1, v[6:7]
	global_load_dwordx4 v[12:15], v[0:1], off offset:1536
	global_load_dwordx4 v[8:11], v[6:7], off offset:1536
	v_add_u32_e32 v0, 0xa00, v2
	v_mul_hi_i32 v1, v0, s3
	v_lshrrev_b32_e32 v3, 31, v1
	v_ashrrev_i32_e32 v1, 2, v1
	v_add_u32_e32 v57, v1, v3
	v_mul_lo_u32 v1, v57, 24
	v_sub_u32_e32 v58, v0, v1
	v_add_u32_e32 v0, s8, v57
	v_and_b32_e32 v56, 15, v2
	v_mad_i64_i32 v[0:1], s[0:1], v0, s46, v[4:5]
	v_lshlrev_b32_e32 v6, 3, v58
	v_add_u32_e32 v2, 0xb00, v2
	v_lshl_add_u64 v[0:1], v[0:1], 0, v[48:49]
	v_ashrrev_i32_e32 v7, 31, v6
	v_mul_hi_i32 v3, v2, s3
	v_lshl_add_u64 v[0:1], v[6:7], 1, v[0:1]
	v_lshrrev_b32_e32 v6, 31, v3
	v_ashrrev_i32_e32 v3, 2, v3
	v_add_u32_e32 v54, v3, v6
	v_mul_lo_u32 v3, v54, 24
	v_sub_u32_e32 v55, v2, v3
	v_add_u32_e32 v2, s8, v54
	v_mad_i64_i32 v[2:3], s[0:1], v2, s46, v[4:5]
	v_lshlrev_b32_e32 v4, 3, v55
	v_lshl_add_u64 v[2:3], v[2:3], 0, v[48:49]
	v_ashrrev_i32_e32 v5, 31, v4
	v_lshl_add_u64 v[2:3], v[4:5], 1, v[2:3]
	v_lshlrev_b32_e32 v73, 3, v71
	global_load_dwordx4 v[4:7], v[0:1], off offset:1536
	s_nop 0
	global_load_dwordx4 v[0:3], v[2:3], off offset:1536
	ds_read_b64 v[82:83], v73
	s_movk_i32 s0, 0x840
	v_lshlrev_b32_e32 v84, 6, v72
	v_mul_lo_u32 v72, v72, s0
	v_lshlrev_b32_e32 v71, 1, v71
	v_add3_u32 v71, v84, v72, v71
	ds_read_b128 v[72:75], v84 offset:1024
	s_waitcnt vmcnt(11)
	v_lshlrev_b32_e32 v76, 16, v44
	v_and_b32_e32 v44, 0xffff0000, v44
	s_waitcnt lgkmcnt(1)
	v_sub_f32_e32 v44, v44, v82
	v_sub_f32_e32 v76, v76, v82
	v_mul_f32_e32 v44, v83, v44
	v_mul_f32_e32 v85, v83, v76
	ds_read_b128 v[76:79], v84 offset:1040
	s_waitcnt lgkmcnt(1)
	v_fmac_f32_e32 v75, v44, v74
	v_bfe_u32 v44, v75, 16, 1
	v_add3_u32 v44, v75, v44, s33
	ds_write_b16_d16_hi v71, v44 offset:2832
	v_lshlrev_b32_e32 v44, 16, v45
	v_sub_f32_e32 v44, v44, v82
	v_mul_f32_e32 v44, v83, v44
	s_waitcnt lgkmcnt(1)
	v_fma_f32 v44, v44, v76, v77
	v_bfe_u32 v76, v44, 16, 1
	v_add3_u32 v44, v44, v76, s33
	ds_write_b16_d16_hi v71, v44 offset:3104
	v_and_b32_e32 v44, 0xffff0000, v45
	v_fma_f32 v72, v72, v85, v73
	v_sub_f32_e32 v44, v44, v82
	v_bfe_u32 v73, v72, 16, 1
	v_mul_f32_e32 v44, v83, v44
	v_add3_u32 v72, v72, v73, s33
	v_fmac_f32_e32 v79, v44, v78
	ds_write_b16_d16_hi v71, v72 offset:2560
	ds_read_b128 v[72:75], v84 offset:1056
	v_bfe_u32 v44, v79, 16, 1
	v_add3_u32 v44, v79, v44, s33
	ds_write_b16_d16_hi v71, v44 offset:3376
	v_lshlrev_b32_e32 v44, 16, v46
	v_sub_f32_e32 v44, v44, v82
	v_mul_f32_e32 v44, v83, v44
	ds_read_b128 v[76:79], v84 offset:1072
	s_waitcnt lgkmcnt(2)
	v_fma_f32 v44, v44, v72, v73
	v_bfe_u32 v45, v44, 16, 1
	v_add3_u32 v44, v44, v45, s33
	ds_write_b16_d16_hi v71, v44 offset:3648
	v_and_b32_e32 v44, 0xffff0000, v46
	v_sub_f32_e32 v44, v44, v82
	v_mul_f32_e32 v44, v83, v44
	v_fmac_f32_e32 v75, v44, v74
	v_bfe_u32 v44, v75, 16, 1
	v_add3_u32 v44, v75, v44, s33
	ds_write_b16_d16_hi v71, v44 offset:3920
	v_lshlrev_b32_e32 v44, 16, v47
	v_sub_f32_e32 v44, v44, v82
	v_mul_f32_e32 v44, v83, v44
	v_lshlrev_b32_e32 v45, 3, v81
	s_waitcnt lgkmcnt(2)
	v_fma_f32 v44, v44, v76, v77
	ds_read_b64 v[84:85], v45
	v_bfe_u32 v45, v44, 16, 1
	v_add3_u32 v44, v44, v45, s33
	ds_write_b16_d16_hi v71, v44 offset:4192
	v_and_b32_e32 v44, 0xffff0000, v47
	v_sub_f32_e32 v44, v44, v82
	v_mul_f32_e32 v44, v83, v44
	v_fmac_f32_e32 v79, v44, v78
	v_bfe_u32 v44, v79, 16, 1
	v_add3_u32 v44, v79, v44, s33
	ds_write_b16_d16_hi v71, v44 offset:4464
	v_lshlrev_b32_e32 v71, 6, v86
	v_mul_lo_u32 v44, v86, s0
	v_lshlrev_b32_e32 v45, 1, v81
	v_add3_u32 v76, v71, v44, v45
	ds_read_b128 v[44:47], v71 offset:1024
	s_waitcnt vmcnt(10)
	v_lshlrev_b32_e32 v72, 16, v40
	v_and_b32_e32 v40, 0xffff0000, v40
	s_waitcnt lgkmcnt(3)
	v_sub_f32_e32 v40, v40, v84
	v_sub_f32_e32 v72, v72, v84
	v_mul_f32_e32 v40, v85, v40
	v_mul_f32_e32 v77, v85, v72
	ds_read_b128 v[72:75], v71 offset:1040
	s_waitcnt lgkmcnt(1)
	v_fmac_f32_e32 v47, v40, v46
	v_bfe_u32 v40, v47, 16, 1
	v_add3_u32 v40, v47, v40, s33
	ds_write_b16_d16_hi v76, v40 offset:2832
	v_lshlrev_b32_e32 v40, 16, v41
	v_fma_f32 v44, v44, v77, v45
	v_sub_f32_e32 v40, v40, v84
	v_bfe_u32 v45, v44, 16, 1
	v_mul_f32_e32 v40, v85, v40
	v_add3_u32 v44, v44, v45, s33
	s_waitcnt lgkmcnt(1)
	v_fma_f32 v40, v40, v72, v73
	ds_write_b16_d16_hi v76, v44 offset:2560
	v_bfe_u32 v44, v40, 16, 1
	v_add3_u32 v40, v40, v44, s33
	ds_write_b16_d16_hi v76, v40 offset:3104
	v_and_b32_e32 v40, 0xffff0000, v41
	v_sub_f32_e32 v40, v40, v84
	v_mul_f32_e32 v40, v85, v40
	v_fmac_f32_e32 v75, v40, v74
	v_bfe_u32 v40, v75, 16, 1
	ds_read_b128 v[44:47], v71 offset:1056
	v_add3_u32 v40, v75, v40, s33
	ds_write_b16_d16_hi v76, v40 offset:3376
	v_lshlrev_b32_e32 v40, 16, v42
	v_sub_f32_e32 v40, v40, v84
	v_mul_f32_e32 v40, v85, v40
	ds_read_b128 v[72:75], v71 offset:1072
	s_waitcnt lgkmcnt(2)
	v_fma_f32 v40, v40, v44, v45
	v_bfe_u32 v41, v40, 16, 1
	v_add3_u32 v40, v40, v41, s33
	ds_write_b16_d16_hi v76, v40 offset:3648
	v_and_b32_e32 v40, 0xffff0000, v42
	v_sub_f32_e32 v40, v40, v84
	v_mul_f32_e32 v40, v85, v40
	v_fmac_f32_e32 v47, v40, v46
	v_bfe_u32 v40, v47, 16, 1
	v_add3_u32 v40, v47, v40, s33
	ds_write_b16_d16_hi v76, v40 offset:3920
	v_lshlrev_b32_e32 v40, 16, v43
	v_sub_f32_e32 v40, v40, v84
	v_mul_f32_e32 v40, v85, v40
	s_waitcnt lgkmcnt(2)
	v_fma_f32 v40, v40, v72, v73
	v_bfe_u32 v41, v40, 16, 1
	v_add3_u32 v40, v40, v41, s33
	ds_write_b16_d16_hi v76, v40 offset:4192
	v_and_b32_e32 v40, 0xffff0000, v43
	v_sub_f32_e32 v40, v40, v84
	v_mul_f32_e32 v40, v85, v40
	v_fmac_f32_e32 v75, v40, v74
	v_bfe_u32 v40, v75, 16, 1
	v_add3_u32 v40, v75, v40, s33
	ds_write_b16_d16_hi v76, v40 offset:4464
	v_lshlrev_b32_e32 v40, 3, v87
	ds_read_b64 v[72:73], v40
	v_lshlrev_b32_e32 v71, 6, v88
	ds_read_b128 v[40:43], v71 offset:1024
	v_mul_lo_u32 v44, v88, s0
	v_lshlrev_b32_e32 v45, 1, v87
	v_add3_u32 v74, v71, v44, v45
	s_waitcnt vmcnt(9)
	v_lshlrev_b32_e32 v44, 16, v36
	s_waitcnt lgkmcnt(1)
	v_sub_f32_e32 v44, v44, v72
	v_and_b32_e32 v36, 0xffff0000, v36
	v_mul_f32_e32 v44, v73, v44
	v_sub_f32_e32 v36, v36, v72
	s_waitcnt lgkmcnt(0)
	v_fma_f32 v40, v40, v44, v41
	v_mul_f32_e32 v36, v73, v36
	v_bfe_u32 v41, v40, 16, 1
	v_fmac_f32_e32 v43, v36, v42
	v_add3_u32 v40, v40, v41, s33
	v_bfe_u32 v36, v43, 16, 1
	ds_write_b16_d16_hi v74, v40 offset:2560
	v_add3_u32 v36, v43, v36, s33
	ds_read_b128 v[40:43], v71 offset:1040
	ds_read_b128 v[44:47], v71 offset:1056
	ds_write_b16_d16_hi v74, v36 offset:2832
	v_lshlrev_b32_e32 v36, 16, v37
	v_sub_f32_e32 v36, v36, v72
	v_mul_f32_e32 v36, v73, v36
	s_waitcnt lgkmcnt(2)
	v_fma_f32 v36, v36, v40, v41
	v_bfe_u32 v40, v36, 16, 1
	v_add3_u32 v36, v36, v40, s33
	ds_write_b16_d16_hi v74, v36 offset:3104
	v_and_b32_e32 v36, 0xffff0000, v37
	v_sub_f32_e32 v36, v36, v72
	v_mul_f32_e32 v36, v73, v36
	v_fmac_f32_e32 v43, v36, v42
	v_bfe_u32 v36, v43, 16, 1
	v_add3_u32 v36, v43, v36, s33
	ds_write_b16_d16_hi v74, v36 offset:3376
	v_lshlrev_b32_e32 v36, 16, v38
	v_sub_f32_e32 v36, v36, v72
	v_mul_f32_e32 v36, v73, v36
	s_waitcnt lgkmcnt(3)
	v_fma_f32 v36, v36, v44, v45
	v_bfe_u32 v37, v36, 16, 1
	v_add3_u32 v36, v36, v37, s33
	ds_write_b16_d16_hi v74, v36 offset:3648
	v_and_b32_e32 v36, 0xffff0000, v38
	v_sub_f32_e32 v36, v36, v72
	v_mul_f32_e32 v36, v73, v36
	v_fmac_f32_e32 v47, v36, v46
	v_bfe_u32 v36, v47, 16, 1
	ds_read_b128 v[40:43], v71 offset:1072
	v_add3_u32 v36, v47, v36, s33
	ds_write_b16_d16_hi v74, v36 offset:3920
	v_lshlrev_b32_e32 v36, 16, v39
	v_sub_f32_e32 v36, v36, v72
	v_mul_f32_e32 v36, v73, v36
	v_lshlrev_b32_e32 v37, 3, v89
	ds_read_b64 v[44:45], v37
	s_waitcnt lgkmcnt(2)
	v_fma_f32 v36, v36, v40, v41
	v_bfe_u32 v37, v36, 16, 1
	v_add3_u32 v36, v36, v37, s33
	ds_write_b16_d16_hi v74, v36 offset:4192
	v_and_b32_e32 v36, 0xffff0000, v39
	v_sub_f32_e32 v36, v36, v72
	v_mul_f32_e32 v36, v73, v36
	v_fmac_f32_e32 v43, v36, v42
	v_bfe_u32 v36, v43, 16, 1
	v_add3_u32 v36, v43, v36, s33
	ds_write_b16_d16_hi v74, v36 offset:4464
	v_lshlrev_b32_e32 v46, 6, v90
	v_mul_lo_u32 v36, v90, s0
	v_lshlrev_b32_e32 v37, 1, v89
	v_add3_u32 v47, v46, v36, v37
	ds_read_b128 v[36:39], v46 offset:1024
	s_waitcnt vmcnt(8)
	v_lshlrev_b32_e32 v40, 16, v32
	v_and_b32_e32 v32, 0xffff0000, v32
	s_waitcnt lgkmcnt(3)
	v_sub_f32_e32 v32, v32, v44
	v_sub_f32_e32 v40, v40, v44
	v_mul_f32_e32 v32, v45, v32
	v_mul_f32_e32 v71, v45, v40
	ds_read_b128 v[40:43], v46 offset:1040
	s_waitcnt lgkmcnt(1)
	v_fmac_f32_e32 v39, v32, v38
	v_bfe_u32 v32, v39, 16, 1
	v_add3_u32 v32, v39, v32, s33
	ds_write_b16_d16_hi v47, v32 offset:2832
	v_lshlrev_b32_e32 v32, 16, v33
	v_fma_f32 v36, v36, v71, v37
	v_sub_f32_e32 v32, v32, v44
	v_bfe_u32 v37, v36, 16, 1
	v_mul_f32_e32 v32, v45, v32
	v_add3_u32 v36, v36, v37, s33
	s_waitcnt lgkmcnt(1)
	v_fma_f32 v32, v32, v40, v41
	ds_write_b16_d16_hi v47, v36 offset:2560
	v_bfe_u32 v36, v32, 16, 1
	v_add3_u32 v32, v32, v36, s33
	ds_write_b16_d16_hi v47, v32 offset:3104
	v_and_b32_e32 v32, 0xffff0000, v33
	v_sub_f32_e32 v32, v32, v44
	v_mul_f32_e32 v32, v45, v32
	v_fmac_f32_e32 v43, v32, v42
	v_bfe_u32 v32, v43, 16, 1
	ds_read_b128 v[36:39], v46 offset:1056
	v_add3_u32 v32, v43, v32, s33
	ds_write_b16_d16_hi v47, v32 offset:3376
	v_lshlrev_b32_e32 v32, 16, v34
	v_sub_f32_e32 v32, v32, v44
	v_mul_f32_e32 v32, v45, v32
	ds_read_b128 v[40:43], v46 offset:1072
	s_waitcnt lgkmcnt(2)
	v_fma_f32 v32, v32, v36, v37
	v_bfe_u32 v33, v32, 16, 1
	v_add3_u32 v32, v32, v33, s33
	ds_write_b16_d16_hi v47, v32 offset:3648
	v_and_b32_e32 v32, 0xffff0000, v34
	v_sub_f32_e32 v32, v32, v44
	v_mul_f32_e32 v32, v45, v32
	v_fmac_f32_e32 v39, v32, v38
	v_bfe_u32 v32, v39, 16, 1
	v_add3_u32 v32, v39, v32, s33
	ds_write_b16_d16_hi v47, v32 offset:3920
	v_lshlrev_b32_e32 v32, 16, v35
	v_sub_f32_e32 v32, v32, v44
	v_mul_f32_e32 v32, v45, v32
	s_waitcnt lgkmcnt(2)
	v_fma_f32 v32, v32, v40, v41
	v_bfe_u32 v33, v32, 16, 1
	v_add3_u32 v32, v32, v33, s33
	ds_write_b16_d16_hi v47, v32 offset:4192
	v_and_b32_e32 v32, 0xffff0000, v35
	v_sub_f32_e32 v32, v32, v44
	v_mul_f32_e32 v32, v45, v32
	v_fmac_f32_e32 v43, v32, v42
	v_bfe_u32 v32, v43, 16, 1
	v_add3_u32 v32, v43, v32, s33
	ds_write_b16_d16_hi v47, v32 offset:4464
	v_lshlrev_b32_e32 v32, 3, v69
	ds_read_b64 v[40:41], v32
	v_lshlrev_b32_e32 v42, 6, v70
	ds_read_b128 v[32:35], v42 offset:1024
	v_mul_lo_u32 v36, v70, s0
	v_lshlrev_b32_e32 v37, 1, v69
	v_add3_u32 v43, v42, v36, v37
	s_waitcnt vmcnt(7)
	v_lshlrev_b32_e32 v36, 16, v28
	s_waitcnt lgkmcnt(1)
	v_sub_f32_e32 v36, v36, v40
	v_and_b32_e32 v28, 0xffff0000, v28
	v_mul_f32_e32 v36, v41, v36
	v_sub_f32_e32 v28, v28, v40
	s_waitcnt lgkmcnt(0)
	v_fma_f32 v32, v32, v36, v33
	v_mul_f32_e32 v28, v41, v28
	v_bfe_u32 v33, v32, 16, 1
	v_fmac_f32_e32 v35, v28, v34
	v_add3_u32 v32, v32, v33, s33
	v_bfe_u32 v28, v35, 16, 1
	ds_write_b16_d16_hi v43, v32 offset:2560
	v_add3_u32 v28, v35, v28, s33
	ds_read_b128 v[32:35], v42 offset:1040
	ds_read_b128 v[36:39], v42 offset:1056
	ds_write_b16_d16_hi v43, v28 offset:2832
	v_lshlrev_b32_e32 v28, 16, v29
	v_sub_f32_e32 v28, v28, v40
	v_mul_f32_e32 v28, v41, v28
	s_waitcnt lgkmcnt(2)
	v_fma_f32 v28, v28, v32, v33
	v_bfe_u32 v32, v28, 16, 1
	v_add3_u32 v28, v28, v32, s33
	ds_write_b16_d16_hi v43, v28 offset:3104
	v_and_b32_e32 v28, 0xffff0000, v29
	v_sub_f32_e32 v28, v28, v40
	v_mul_f32_e32 v28, v41, v28
	v_fmac_f32_e32 v35, v28, v34
	v_bfe_u32 v28, v35, 16, 1
	v_add3_u32 v28, v35, v28, s33
	ds_write_b16_d16_hi v43, v28 offset:3376
	v_lshlrev_b32_e32 v28, 16, v30
	v_sub_f32_e32 v28, v28, v40
	v_mul_f32_e32 v28, v41, v28
	s_waitcnt lgkmcnt(3)
	v_fma_f32 v28, v28, v36, v37
	v_bfe_u32 v29, v28, 16, 1
	v_add3_u32 v28, v28, v29, s33
	ds_write_b16_d16_hi v43, v28 offset:3648
	v_and_b32_e32 v28, 0xffff0000, v30
	v_sub_f32_e32 v28, v28, v40
	v_mul_f32_e32 v28, v41, v28
	v_fmac_f32_e32 v39, v28, v38
	v_bfe_u32 v28, v39, 16, 1
	ds_read_b128 v[32:35], v42 offset:1072
	v_add3_u32 v28, v39, v28, s33
	ds_write_b16_d16_hi v43, v28 offset:3920
	v_lshlrev_b32_e32 v28, 16, v31
	v_sub_f32_e32 v28, v28, v40
	v_mul_f32_e32 v28, v41, v28
	v_lshlrev_b32_e32 v29, 3, v67
	ds_read_b64 v[36:37], v29
	s_waitcnt lgkmcnt(2)
	v_fma_f32 v28, v28, v32, v33
	v_bfe_u32 v29, v28, 16, 1
	v_add3_u32 v28, v28, v29, s33
	ds_write_b16_d16_hi v43, v28 offset:4192
	v_and_b32_e32 v28, 0xffff0000, v31
	v_sub_f32_e32 v28, v28, v40
	v_mul_f32_e32 v28, v41, v28
	v_fmac_f32_e32 v35, v28, v34
	v_bfe_u32 v28, v35, 16, 1
	v_add3_u32 v28, v35, v28, s33
	ds_write_b16_d16_hi v43, v28 offset:4464
	v_lshlrev_b32_e32 v38, 6, v68
	v_mul_lo_u32 v28, v68, s0
	v_lshlrev_b32_e32 v29, 1, v67
	v_add3_u32 v39, v38, v28, v29
	ds_read_b128 v[28:31], v38 offset:1024
	s_waitcnt vmcnt(6)
	v_lshlrev_b32_e32 v32, 16, v24
	v_and_b32_e32 v24, 0xffff0000, v24
	s_waitcnt lgkmcnt(3)
	v_sub_f32_e32 v24, v24, v36
	v_sub_f32_e32 v32, v32, v36
	v_mul_f32_e32 v24, v37, v24
	v_mul_f32_e32 v40, v37, v32
	ds_read_b128 v[32:35], v38 offset:1040
	s_waitcnt lgkmcnt(1)
	v_fmac_f32_e32 v31, v24, v30
	v_bfe_u32 v24, v31, 16, 1
	v_add3_u32 v24, v31, v24, s33
	ds_write_b16_d16_hi v39, v24 offset:2832
	v_lshlrev_b32_e32 v24, 16, v25
	v_fma_f32 v28, v28, v40, v29
	v_sub_f32_e32 v24, v24, v36
	v_bfe_u32 v29, v28, 16, 1
	v_mul_f32_e32 v24, v37, v24
	v_add3_u32 v28, v28, v29, s33
	s_waitcnt lgkmcnt(1)
	v_fma_f32 v24, v24, v32, v33
	ds_write_b16_d16_hi v39, v28 offset:2560
	v_bfe_u32 v28, v24, 16, 1
	v_add3_u32 v24, v24, v28, s33
	ds_write_b16_d16_hi v39, v24 offset:3104
	v_and_b32_e32 v24, 0xffff0000, v25
	v_sub_f32_e32 v24, v24, v36
	v_mul_f32_e32 v24, v37, v24
	v_fmac_f32_e32 v35, v24, v34
	v_bfe_u32 v24, v35, 16, 1
	ds_read_b128 v[28:31], v38 offset:1056
	v_add3_u32 v24, v35, v24, s33
	ds_write_b16_d16_hi v39, v24 offset:3376
	v_lshlrev_b32_e32 v24, 16, v26
	v_sub_f32_e32 v24, v24, v36
	v_mul_f32_e32 v24, v37, v24
	ds_read_b128 v[32:35], v38 offset:1072
	s_waitcnt lgkmcnt(2)
	v_fma_f32 v24, v24, v28, v29
	v_bfe_u32 v25, v24, 16, 1
	v_add3_u32 v24, v24, v25, s33
	ds_write_b16_d16_hi v39, v24 offset:3648
	v_and_b32_e32 v24, 0xffff0000, v26
	v_sub_f32_e32 v24, v24, v36
	v_mul_f32_e32 v24, v37, v24
	v_fmac_f32_e32 v31, v24, v30
	v_bfe_u32 v24, v31, 16, 1
	v_add3_u32 v24, v31, v24, s33
	ds_write_b16_d16_hi v39, v24 offset:3920
	v_lshlrev_b32_e32 v24, 16, v27
	v_sub_f32_e32 v24, v24, v36
	v_mul_f32_e32 v24, v37, v24
	s_waitcnt lgkmcnt(2)
	v_fma_f32 v24, v24, v32, v33
	v_bfe_u32 v25, v24, 16, 1
	v_add3_u32 v24, v24, v25, s33
	ds_write_b16_d16_hi v39, v24 offset:4192
	v_and_b32_e32 v24, 0xffff0000, v27
	v_sub_f32_e32 v24, v24, v36
	v_mul_f32_e32 v24, v37, v24
	v_fmac_f32_e32 v35, v24, v34
	v_bfe_u32 v24, v35, 16, 1
	v_add3_u32 v24, v35, v24, s33
	ds_write_b16_d16_hi v39, v24 offset:4464
	v_lshlrev_b32_e32 v24, 3, v65
	ds_read_b64 v[32:33], v24
	v_lshlrev_b32_e32 v34, 6, v66
	ds_read_b128 v[24:27], v34 offset:1024
	v_mul_lo_u32 v28, v66, s0
	v_lshlrev_b32_e32 v29, 1, v65
	v_add3_u32 v35, v34, v28, v29
	s_waitcnt vmcnt(5)
	v_lshlrev_b32_e32 v28, 16, v20
	s_waitcnt lgkmcnt(1)
	v_sub_f32_e32 v28, v28, v32
	v_and_b32_e32 v20, 0xffff0000, v20
	v_mul_f32_e32 v28, v33, v28
	v_sub_f32_e32 v20, v20, v32
	s_waitcnt lgkmcnt(0)
	v_fma_f32 v24, v24, v28, v25
	v_mul_f32_e32 v20, v33, v20
	v_bfe_u32 v25, v24, 16, 1
	v_fmac_f32_e32 v27, v20, v26
	v_add3_u32 v24, v24, v25, s33
	v_bfe_u32 v20, v27, 16, 1
	ds_write_b16_d16_hi v35, v24 offset:2560
	v_add3_u32 v20, v27, v20, s33
	ds_read_b128 v[24:27], v34 offset:1040
	ds_read_b128 v[28:31], v34 offset:1056
	ds_write_b16_d16_hi v35, v20 offset:2832
	v_lshlrev_b32_e32 v20, 16, v21
	v_sub_f32_e32 v20, v20, v32
	v_mul_f32_e32 v20, v33, v20
	s_waitcnt lgkmcnt(2)
	v_fma_f32 v20, v20, v24, v25
	v_bfe_u32 v24, v20, 16, 1
	v_add3_u32 v20, v20, v24, s33
	ds_write_b16_d16_hi v35, v20 offset:3104
	v_and_b32_e32 v20, 0xffff0000, v21
	v_sub_f32_e32 v20, v20, v32
	v_mul_f32_e32 v20, v33, v20
	v_fmac_f32_e32 v27, v20, v26
	v_bfe_u32 v20, v27, 16, 1
	v_add3_u32 v20, v27, v20, s33
	ds_write_b16_d16_hi v35, v20 offset:3376
	v_lshlrev_b32_e32 v20, 16, v22
	v_sub_f32_e32 v20, v20, v32
	v_mul_f32_e32 v20, v33, v20
	s_waitcnt lgkmcnt(3)
	v_fma_f32 v20, v20, v28, v29
	v_bfe_u32 v21, v20, 16, 1
	v_add3_u32 v20, v20, v21, s33
	ds_write_b16_d16_hi v35, v20 offset:3648
	v_and_b32_e32 v20, 0xffff0000, v22
	v_sub_f32_e32 v20, v20, v32
	v_mul_f32_e32 v20, v33, v20
	v_fmac_f32_e32 v31, v20, v30
	v_bfe_u32 v20, v31, 16, 1
	ds_read_b128 v[24:27], v34 offset:1072
	v_add3_u32 v20, v31, v20, s33
	ds_write_b16_d16_hi v35, v20 offset:3920
	v_lshlrev_b32_e32 v20, 16, v23
	v_sub_f32_e32 v20, v20, v32
	v_mul_f32_e32 v20, v33, v20
	v_lshlrev_b32_e32 v21, 3, v63
	ds_read_b64 v[28:29], v21
	s_waitcnt lgkmcnt(2)
	v_fma_f32 v20, v20, v24, v25
	v_bfe_u32 v21, v20, 16, 1
	v_add3_u32 v20, v20, v21, s33
	ds_write_b16_d16_hi v35, v20 offset:4192
	v_and_b32_e32 v20, 0xffff0000, v23
	v_sub_f32_e32 v20, v20, v32
	v_mul_f32_e32 v20, v33, v20
	v_fmac_f32_e32 v27, v20, v26
	v_bfe_u32 v20, v27, 16, 1
	v_add3_u32 v20, v27, v20, s33
	ds_write_b16_d16_hi v35, v20 offset:4464
	v_lshlrev_b32_e32 v30, 6, v64
	v_mul_lo_u32 v20, v64, s0
	v_lshlrev_b32_e32 v21, 1, v63
	v_add3_u32 v31, v30, v20, v21
	ds_read_b128 v[20:23], v30 offset:1024
	s_waitcnt vmcnt(4)
	v_lshlrev_b32_e32 v24, 16, v16
	v_and_b32_e32 v16, 0xffff0000, v16
	s_waitcnt lgkmcnt(3)
	v_sub_f32_e32 v16, v16, v28
	v_sub_f32_e32 v24, v24, v28
	v_mul_f32_e32 v16, v29, v16
	v_mul_f32_e32 v32, v29, v24
	ds_read_b128 v[24:27], v30 offset:1040
	s_waitcnt lgkmcnt(1)
	v_fmac_f32_e32 v23, v16, v22
	v_bfe_u32 v16, v23, 16, 1
	v_add3_u32 v16, v23, v16, s33
	ds_write_b16_d16_hi v31, v16 offset:2832
	v_lshlrev_b32_e32 v16, 16, v17
	v_fma_f32 v20, v20, v32, v21
	v_sub_f32_e32 v16, v16, v28
	v_bfe_u32 v21, v20, 16, 1
	v_mul_f32_e32 v16, v29, v16
	v_add3_u32 v20, v20, v21, s33
	s_waitcnt lgkmcnt(1)
	v_fma_f32 v16, v16, v24, v25
	ds_write_b16_d16_hi v31, v20 offset:2560
	v_bfe_u32 v20, v16, 16, 1
	v_add3_u32 v16, v16, v20, s33
	ds_write_b16_d16_hi v31, v16 offset:3104
	v_and_b32_e32 v16, 0xffff0000, v17
	v_sub_f32_e32 v16, v16, v28
	v_mul_f32_e32 v16, v29, v16
	v_fmac_f32_e32 v27, v16, v26
	v_bfe_u32 v16, v27, 16, 1
	ds_read_b128 v[20:23], v30 offset:1056
	v_add3_u32 v16, v27, v16, s33
	ds_write_b16_d16_hi v31, v16 offset:3376
	v_lshlrev_b32_e32 v16, 16, v18
	v_sub_f32_e32 v16, v16, v28
	v_mul_f32_e32 v16, v29, v16
	ds_read_b128 v[24:27], v30 offset:1072
	s_waitcnt lgkmcnt(2)
	v_fma_f32 v16, v16, v20, v21
	v_bfe_u32 v17, v16, 16, 1
	v_add3_u32 v16, v16, v17, s33
	ds_write_b16_d16_hi v31, v16 offset:3648
	v_and_b32_e32 v16, 0xffff0000, v18
	v_sub_f32_e32 v16, v16, v28
	v_mul_f32_e32 v16, v29, v16
	v_fmac_f32_e32 v23, v16, v22
	v_bfe_u32 v16, v23, 16, 1
	v_add3_u32 v16, v23, v16, s33
	ds_write_b16_d16_hi v31, v16 offset:3920
	v_lshlrev_b32_e32 v16, 16, v19
	v_sub_f32_e32 v16, v16, v28
	v_mul_f32_e32 v16, v29, v16
	s_waitcnt lgkmcnt(2)
	v_fma_f32 v16, v16, v24, v25
	v_bfe_u32 v17, v16, 16, 1
	v_add3_u32 v16, v16, v17, s33
	ds_write_b16_d16_hi v31, v16 offset:4192
	v_and_b32_e32 v16, 0xffff0000, v19
	v_sub_f32_e32 v16, v16, v28
	v_mul_f32_e32 v16, v29, v16
	v_fmac_f32_e32 v27, v16, v26
	v_bfe_u32 v16, v27, 16, 1
	v_add3_u32 v16, v27, v16, s33
	ds_write_b16_d16_hi v31, v16 offset:4464
	v_lshlrev_b32_e32 v16, 3, v61
	ds_read_b64 v[24:25], v16
	v_lshlrev_b32_e32 v26, 6, v62
	ds_read_b128 v[16:19], v26 offset:1024
	v_mul_lo_u32 v20, v62, s0
	v_lshlrev_b32_e32 v21, 1, v61
	v_add3_u32 v27, v26, v20, v21
	s_waitcnt vmcnt(3)
	v_lshlrev_b32_e32 v20, 16, v12
	s_waitcnt lgkmcnt(1)
	v_sub_f32_e32 v20, v20, v24
	v_and_b32_e32 v12, 0xffff0000, v12
	v_mul_f32_e32 v20, v25, v20
	v_sub_f32_e32 v12, v12, v24
	s_waitcnt lgkmcnt(0)
	v_fma_f32 v16, v16, v20, v17
	v_mul_f32_e32 v12, v25, v12
	v_bfe_u32 v17, v16, 16, 1
	v_fmac_f32_e32 v19, v12, v18
	v_add3_u32 v16, v16, v17, s33
	v_bfe_u32 v12, v19, 16, 1
	ds_write_b16_d16_hi v27, v16 offset:2560
	v_add3_u32 v12, v19, v12, s33
	ds_read_b128 v[16:19], v26 offset:1040
	ds_read_b128 v[20:23], v26 offset:1056
	ds_write_b16_d16_hi v27, v12 offset:2832
	v_lshlrev_b32_e32 v12, 16, v13
	v_sub_f32_e32 v12, v12, v24
	v_mul_f32_e32 v12, v25, v12
	s_waitcnt lgkmcnt(2)
	v_fma_f32 v12, v12, v16, v17
	v_bfe_u32 v16, v12, 16, 1
	v_add3_u32 v12, v12, v16, s33
	ds_write_b16_d16_hi v27, v12 offset:3104
	v_and_b32_e32 v12, 0xffff0000, v13
	v_sub_f32_e32 v12, v12, v24
	v_mul_f32_e32 v12, v25, v12
	v_fmac_f32_e32 v19, v12, v18
	v_bfe_u32 v12, v19, 16, 1
	v_add3_u32 v12, v19, v12, s33
	ds_write_b16_d16_hi v27, v12 offset:3376
	v_lshlrev_b32_e32 v12, 16, v14
	v_sub_f32_e32 v12, v12, v24
	v_mul_f32_e32 v12, v25, v12
	s_waitcnt lgkmcnt(3)
	v_fma_f32 v12, v12, v20, v21
	v_bfe_u32 v13, v12, 16, 1
	v_add3_u32 v12, v12, v13, s33
	ds_write_b16_d16_hi v27, v12 offset:3648
	v_and_b32_e32 v12, 0xffff0000, v14
	v_sub_f32_e32 v12, v12, v24
	v_mul_f32_e32 v12, v25, v12
	v_fmac_f32_e32 v23, v12, v22
	v_bfe_u32 v12, v23, 16, 1
	ds_read_b128 v[16:19], v26 offset:1072
	v_add3_u32 v12, v23, v12, s33
	ds_write_b16_d16_hi v27, v12 offset:3920
	v_lshlrev_b32_e32 v12, 16, v15
	v_sub_f32_e32 v12, v12, v24
	v_mul_f32_e32 v12, v25, v12
	v_lshlrev_b32_e32 v13, 3, v59
	ds_read_b64 v[20:21], v13
	s_waitcnt lgkmcnt(2)
	v_fma_f32 v12, v12, v16, v17
	v_bfe_u32 v13, v12, 16, 1
	v_add3_u32 v12, v12, v13, s33
	ds_write_b16_d16_hi v27, v12 offset:4192
	v_and_b32_e32 v12, 0xffff0000, v15
	v_sub_f32_e32 v12, v12, v24
	v_mul_f32_e32 v12, v25, v12
	v_fmac_f32_e32 v19, v12, v18
	v_bfe_u32 v12, v19, 16, 1
	v_add3_u32 v12, v19, v12, s33
	ds_write_b16_d16_hi v27, v12 offset:4464
	v_lshlrev_b32_e32 v22, 6, v60
	v_mul_lo_u32 v12, v60, s0
	v_lshlrev_b32_e32 v13, 1, v59
	v_add3_u32 v23, v22, v12, v13
	ds_read_b128 v[12:15], v22 offset:1024
	s_waitcnt vmcnt(2)
	v_lshlrev_b32_e32 v16, 16, v8
	v_and_b32_e32 v8, 0xffff0000, v8
	s_waitcnt lgkmcnt(3)
	v_sub_f32_e32 v8, v8, v20
	v_sub_f32_e32 v16, v16, v20
	v_mul_f32_e32 v8, v21, v8
	v_mul_f32_e32 v24, v21, v16
	ds_read_b128 v[16:19], v22 offset:1040
	s_waitcnt lgkmcnt(1)
	v_fmac_f32_e32 v15, v8, v14
	v_bfe_u32 v8, v15, 16, 1
	v_add3_u32 v8, v15, v8, s33
	ds_write_b16_d16_hi v23, v8 offset:2832
	v_lshlrev_b32_e32 v8, 16, v9
	v_fma_f32 v12, v12, v24, v13
	v_sub_f32_e32 v8, v8, v20
	v_bfe_u32 v13, v12, 16, 1
	v_mul_f32_e32 v8, v21, v8
	v_add3_u32 v12, v12, v13, s33
	s_waitcnt lgkmcnt(1)
	v_fma_f32 v8, v8, v16, v17
	ds_write_b16_d16_hi v23, v12 offset:2560
	v_bfe_u32 v12, v8, 16, 1
	v_add3_u32 v8, v8, v12, s33
	ds_write_b16_d16_hi v23, v8 offset:3104
	v_and_b32_e32 v8, 0xffff0000, v9
	v_sub_f32_e32 v8, v8, v20
	v_mul_f32_e32 v8, v21, v8
	v_fmac_f32_e32 v19, v8, v18
	v_bfe_u32 v8, v19, 16, 1
	ds_read_b128 v[12:15], v22 offset:1056
	v_add3_u32 v8, v19, v8, s33
	ds_write_b16_d16_hi v23, v8 offset:3376
	v_lshlrev_b32_e32 v8, 16, v10
	v_sub_f32_e32 v8, v8, v20
	v_mul_f32_e32 v8, v21, v8
	ds_read_b128 v[16:19], v22 offset:1072
	s_waitcnt lgkmcnt(2)
	v_fma_f32 v8, v8, v12, v13
	v_bfe_u32 v9, v8, 16, 1
	v_add3_u32 v8, v8, v9, s33
	ds_write_b16_d16_hi v23, v8 offset:3648
	v_and_b32_e32 v8, 0xffff0000, v10
	v_sub_f32_e32 v8, v8, v20
	v_mul_f32_e32 v8, v21, v8
	v_fmac_f32_e32 v15, v8, v14
	v_bfe_u32 v8, v15, 16, 1
	v_add3_u32 v8, v15, v8, s33
	ds_write_b16_d16_hi v23, v8 offset:3920
	v_lshlrev_b32_e32 v8, 16, v11
	v_sub_f32_e32 v8, v8, v20
	v_mul_f32_e32 v8, v21, v8
	s_waitcnt lgkmcnt(2)
	v_fma_f32 v8, v8, v16, v17
	v_bfe_u32 v9, v8, 16, 1
	v_add3_u32 v8, v8, v9, s33
	ds_write_b16_d16_hi v23, v8 offset:4192
	v_and_b32_e32 v8, 0xffff0000, v11
	v_sub_f32_e32 v8, v8, v20
	v_mul_f32_e32 v8, v21, v8
	v_fmac_f32_e32 v19, v8, v18
	v_bfe_u32 v8, v19, 16, 1
	v_add3_u32 v8, v19, v8, s33
	ds_write_b16_d16_hi v23, v8 offset:4464
	v_lshlrev_b32_e32 v8, 3, v57
	ds_read_b64 v[16:17], v8
	v_lshlrev_b32_e32 v18, 6, v58
	ds_read_b128 v[8:11], v18 offset:1024
	v_mul_lo_u32 v12, v58, s0
	v_lshlrev_b32_e32 v13, 1, v57
	v_add3_u32 v19, v18, v12, v13
	s_waitcnt vmcnt(1)
	v_lshlrev_b32_e32 v12, 16, v4
	s_waitcnt lgkmcnt(1)
	v_sub_f32_e32 v12, v12, v16
	v_and_b32_e32 v4, 0xffff0000, v4
	v_mul_f32_e32 v12, v17, v12
	v_sub_f32_e32 v4, v4, v16
	s_waitcnt lgkmcnt(0)
	v_fma_f32 v8, v8, v12, v9
	v_mul_f32_e32 v4, v17, v4
	v_bfe_u32 v9, v8, 16, 1
	v_fmac_f32_e32 v11, v4, v10
	v_add3_u32 v8, v8, v9, s33
	v_bfe_u32 v4, v11, 16, 1
	ds_write_b16_d16_hi v19, v8 offset:2560
	v_add3_u32 v4, v11, v4, s33
	ds_read_b128 v[8:11], v18 offset:1040
	ds_read_b128 v[12:15], v18 offset:1056
	ds_write_b16_d16_hi v19, v4 offset:2832
	v_lshlrev_b32_e32 v4, 16, v5
	v_sub_f32_e32 v4, v4, v16
	v_mul_f32_e32 v4, v17, v4
	s_waitcnt lgkmcnt(2)
	v_fma_f32 v4, v4, v8, v9
	v_bfe_u32 v8, v4, 16, 1
	v_add3_u32 v4, v4, v8, s33
	ds_write_b16_d16_hi v19, v4 offset:3104
	v_and_b32_e32 v4, 0xffff0000, v5
	v_sub_f32_e32 v4, v4, v16
	v_mul_f32_e32 v4, v17, v4
	v_fmac_f32_e32 v11, v4, v10
	v_bfe_u32 v4, v11, 16, 1
	v_add3_u32 v4, v11, v4, s33
	ds_write_b16_d16_hi v19, v4 offset:3376
	v_lshlrev_b32_e32 v4, 16, v6
	v_sub_f32_e32 v4, v4, v16
	v_mul_f32_e32 v4, v17, v4
	s_waitcnt lgkmcnt(3)
	v_fma_f32 v4, v4, v12, v13
	v_bfe_u32 v5, v4, 16, 1
	v_add3_u32 v4, v4, v5, s33
	ds_write_b16_d16_hi v19, v4 offset:3648
	v_and_b32_e32 v4, 0xffff0000, v6
	v_sub_f32_e32 v4, v4, v16
	v_mul_f32_e32 v4, v17, v4
	v_fmac_f32_e32 v15, v4, v14
	v_bfe_u32 v4, v15, 16, 1
	ds_read_b128 v[8:11], v18 offset:1072
	v_add3_u32 v4, v15, v4, s33
	ds_write_b16_d16_hi v19, v4 offset:3920
	v_lshlrev_b32_e32 v4, 16, v7
	v_sub_f32_e32 v4, v4, v16
	v_mul_f32_e32 v4, v17, v4
	v_lshlrev_b32_e32 v5, 3, v54
	ds_read_b64 v[12:13], v5
	s_waitcnt lgkmcnt(2)
	v_fma_f32 v4, v4, v8, v9
	v_bfe_u32 v5, v4, 16, 1
	v_add3_u32 v4, v4, v5, s33
	ds_write_b16_d16_hi v19, v4 offset:4192
	v_and_b32_e32 v4, 0xffff0000, v7
	v_sub_f32_e32 v4, v4, v16
	v_mul_f32_e32 v4, v17, v4
	v_fmac_f32_e32 v11, v4, v10
	v_bfe_u32 v4, v11, 16, 1
	v_add3_u32 v4, v11, v4, s33
	ds_write_b16_d16_hi v19, v4 offset:4464
	v_lshlrev_b32_e32 v14, 6, v55
	v_mul_lo_u32 v4, v55, s0
	v_lshlrev_b32_e32 v5, 1, v54
	v_add3_u32 v15, v14, v4, v5
	ds_read_b128 v[4:7], v14 offset:1024
	s_waitcnt vmcnt(0)
	v_lshlrev_b32_e32 v8, 16, v0
	v_and_b32_e32 v0, 0xffff0000, v0
	s_waitcnt lgkmcnt(3)
	v_sub_f32_e32 v0, v0, v12
	v_sub_f32_e32 v8, v8, v12
	v_mul_f32_e32 v0, v13, v0
	v_mul_f32_e32 v16, v13, v8
	ds_read_b128 v[8:11], v14 offset:1040
	s_waitcnt lgkmcnt(1)
	v_fmac_f32_e32 v7, v0, v6
	v_bfe_u32 v0, v7, 16, 1
	v_add3_u32 v0, v7, v0, s33
	ds_write_b16_d16_hi v15, v0 offset:2832
	v_lshlrev_b32_e32 v0, 16, v1
	v_fma_f32 v4, v4, v16, v5
	v_sub_f32_e32 v0, v0, v12
	v_bfe_u32 v5, v4, 16, 1
	v_mul_f32_e32 v0, v13, v0
	v_add3_u32 v4, v4, v5, s33
	s_waitcnt lgkmcnt(1)
	v_fma_f32 v0, v0, v8, v9
	ds_write_b16_d16_hi v15, v4 offset:2560
	v_bfe_u32 v4, v0, 16, 1
	v_add3_u32 v0, v0, v4, s33
	ds_write_b16_d16_hi v15, v0 offset:3104
	v_and_b32_e32 v0, 0xffff0000, v1
	v_sub_f32_e32 v0, v0, v12
	v_mul_f32_e32 v0, v13, v0
	v_fmac_f32_e32 v11, v0, v10
	v_bfe_u32 v0, v11, 16, 1
	ds_read_b128 v[4:7], v14 offset:1056
	v_add3_u32 v0, v11, v0, s33
	ds_write_b16_d16_hi v15, v0 offset:3376
	v_lshlrev_b32_e32 v0, 16, v2
	v_sub_f32_e32 v0, v0, v12
	v_mul_f32_e32 v0, v13, v0
	ds_read_b128 v[8:11], v14 offset:1072
	s_waitcnt lgkmcnt(2)
	v_fma_f32 v0, v0, v4, v5
	v_bfe_u32 v1, v0, 16, 1
	v_add3_u32 v0, v0, v1, s33
	ds_write_b16_d16_hi v15, v0 offset:3648
	v_and_b32_e32 v0, 0xffff0000, v2
	v_sub_f32_e32 v0, v0, v12
	v_mul_f32_e32 v0, v13, v0
	v_fmac_f32_e32 v7, v0, v6
	v_bfe_u32 v0, v7, 16, 1
	v_add3_u32 v0, v7, v0, s33
	ds_write_b16_d16_hi v15, v0 offset:3920
	v_lshlrev_b32_e32 v0, 16, v3
	v_sub_f32_e32 v0, v0, v12
	v_mul_f32_e32 v0, v13, v0
	s_waitcnt lgkmcnt(2)
	v_fma_f32 v0, v0, v8, v9
	v_bfe_u32 v1, v0, 16, 1
	v_add3_u32 v0, v0, v1, s33
	ds_write_b16_d16_hi v15, v0 offset:4192
	v_and_b32_e32 v0, 0xffff0000, v3
	v_sub_f32_e32 v0, v0, v12
	v_mul_f32_e32 v0, v13, v0
	v_fmac_f32_e32 v11, v0, v10
	v_bfe_u32 v0, v11, 16, 1
	v_readlane_b32 s6, v249, 30
	v_add3_u32 v0, v11, v0, s33
	v_readlane_b32 s7, v249, 31
	ds_write_b16_d16_hi v15, v0 offset:4464
	s_waitcnt lgkmcnt(0)
	s_barrier
	s_load_dwordx4 s[12:15], s[6:7], 0x60
	v_readlane_b32 s0, v248, 11
	s_or_b32 s0, s2, s0
	s_ashr_i32 s1, s0, 31
	s_lshl_b64 s[2:3], s[0:1], 16
	s_waitcnt lgkmcnt(0)
	s_add_u32 s2, s12, s2
	s_addc_u32 s3, s13, s3
	s_lshl_b32 s0, s0, 7
	s_ashr_i32 s1, s0, 31
	s_lshl_b64 s[0:1], s[0:1], 2
	s_add_u32 s0, s14, s0
	v_lshrrev_b32_e32 v53, 4, v52
	s_addc_u32 s1, s15, s1
	v_lshl_add_u64 v[58:59], s[4:5], 0, v[48:49]
	s_and_b32 s4, s16, 0x7fffffc
	v_lshlrev_b32_e32 v12, 3, v53
	v_lshlrev_b32_e32 v1, 2, v53
	v_add_u32_e32 v2, s4, v51
	v_or_b32_e32 v13, v50, v56
	v_lshl_or_b32 v8, v2, 5, v1
	v_lshlrev_b32_e32 v2, 7, v13
	v_cmp_gt_i32_e64 s[4:5], v12, v13
	v_ashrrev_i32_e32 v3, 31, v2
	v_lshl_add_u64 v[2:3], v[2:3], 2, s[2:3]
	v_writelane_b32 v249, s4, 63
	v_lshlrev_b32_e32 v4, 5, v53
	v_mov_b32_e32 v5, v80
	v_writelane_b32 v248, s5, 0
	v_cmp_lt_i32_e64 s[4:5], v12, v13
	v_lshl_add_u64 v[62:63], v[2:3], 0, v[4:5]
	v_or_b32_e32 v2, 2, v12
	v_writelane_b32 v248, s4, 1
	v_or_b32_e32 v14, 32, v12
	v_or_b32_e32 v15, 64, v12
	v_writelane_b32 v248, s5, 2
	v_cmp_gt_i32_e64 s[4:5], v2, v13
	v_or_b32_e32 v2, 3, v12
	v_or_b32_e32 v16, 0x60, v12
	v_writelane_b32 v248, s4, 3
	v_or_b32_e32 v0, v1, v50
	v_or_b32_e32 v1, 15, v50
	v_writelane_b32 v248, s5, 4
	v_cmp_gt_i32_e64 s[4:5], v2, v13
	v_or_b32_e32 v2, 4, v12
	s_movk_i32 s40, 0x5f
	v_writelane_b32 v248, s4, 5
	v_cmp_lt_i32_e64 s[24:25], 31, v1
	v_cmp_lt_i32_e64 s[44:45], 63, v1
	v_writelane_b32 v248, s5, 6
	v_cmp_gt_i32_e64 s[4:5], v2, v13
	v_or_b32_e32 v2, 5, v12
	v_cmp_lt_i32_e64 s[62:63], s40, v1
	v_writelane_b32 v248, s4, 7
	v_or_b32_e32 v1, 0x61, v12
	v_or_b32_e32 v18, 16, v13
	v_writelane_b32 v248, s5, 8
	v_cmp_gt_i32_e64 s[4:5], v2, v13
	v_or_b32_e32 v2, 6, v12
	s_load_dwordx2 s[6:7], s[6:7], 0x150
	v_writelane_b32 v249, s4, 59
	v_add_u32_e32 v41, s8, v0
	v_or_b32_e32 v10, 1, v8
	v_writelane_b32 v249, s5, 60
	v_cmp_gt_i32_e64 s[4:5], v2, v13
	v_or_b32_e32 v2, 7, v12
	v_ashrrev_i32_e32 v11, 31, v10
	v_writelane_b32 v249, s4, 57
	v_lshlrev_b64 v[76:77], 11, v[10:11]
	v_or_b32_e32 v10, 2, v8
	v_writelane_b32 v249, s5, 58
	v_cmp_gt_i32_e64 s[4:5], v2, v13
	v_or_b32_e32 v2, 33, v12
	v_add_u32_e32 v9, 1, v41
	v_writelane_b32 v249, s4, 61
	v_ashrrev_i32_e32 v11, 31, v10
	v_lshlrev_b64 v[78:79], 11, v[10:11]
	v_writelane_b32 v249, s5, 62
	v_cmp_gt_i32_e64 s[4:5], v14, v13
	v_or_b32_e32 v10, 3, v8
	v_ashrrev_i32_e32 v11, 31, v10
	v_writelane_b32 v249, s4, 55
	v_lshlrev_b64 v[84:85], 11, v[10:11]
	v_or_b32_e32 v10, 16, v8
	v_writelane_b32 v249, s5, 56
	v_cmp_gt_i32_e64 s[4:5], v2, v13
	v_or_b32_e32 v2, 34, v12
	v_ashrrev_i32_e32 v11, 31, v10
	v_writelane_b32 v248, s4, 15
	v_lshlrev_b64 v[94:95], 11, v[10:11]
	v_or_b32_e32 v10, 17, v8
	v_writelane_b32 v248, s5, 16
	v_cmp_gt_i32_e64 s[4:5], v2, v13
	v_or_b32_e32 v2, 35, v12
	v_ashrrev_i32_e32 v11, 31, v10
	v_writelane_b32 v248, s4, 17
	v_lshlrev_b64 v[96:97], 11, v[10:11]
	v_or_b32_e32 v10, 18, v8
	v_writelane_b32 v248, s5, 18
	v_cmp_gt_i32_e64 s[4:5], v2, v13
	v_or_b32_e32 v2, 36, v12
	v_or_b32_e32 v17, 31, v50
	v_writelane_b32 v248, s4, 19
	v_add_u32_e32 v19, 9, v13
	v_add_u32_e32 v20, 17, v12
	v_writelane_b32 v248, s5, 20
	v_cmp_gt_i32_e64 s[4:5], v2, v13
	v_or_b32_e32 v2, 37, v12
	v_add_u32_e32 v21, 18, v12
	v_writelane_b32 v248, s4, 21
	v_add_u32_e32 v22, 19, v12
	v_add_u32_e32 v23, 20, v12
	v_writelane_b32 v248, s5, 22
	v_cmp_gt_i32_e64 s[4:5], v2, v13
	v_or_b32_e32 v2, 38, v12
	v_add_u32_e32 v24, 21, v12
	v_writelane_b32 v248, s4, 23
	v_add_u32_e32 v25, 22, v12
	v_add_u32_e32 v26, 23, v12
	v_writelane_b32 v248, s5, 24
	v_cmp_gt_i32_e64 s[4:5], v2, v13
	v_or_b32_e32 v2, 39, v12
	v_add_u32_e32 v27, 49, v12
	v_writelane_b32 v248, s4, 25
	v_add_u32_e32 v28, 50, v12
	v_add_u32_e32 v29, 51, v12
	v_writelane_b32 v248, s5, 26
	v_cmp_gt_i32_e64 s[4:5], v2, v13
	v_or_b32_e32 v2, 0x41, v12
	v_add_u32_e32 v30, 52, v12
	v_writelane_b32 v248, s4, 27
	v_add_u32_e32 v31, 53, v12
	v_add_u32_e32 v32, 54, v12
	v_writelane_b32 v248, s5, 28
	v_cmp_gt_i32_e64 s[4:5], v15, v13
	v_add_u32_e32 v33, 55, v12
	v_add_u32_e32 v34, 0x51, v12
	v_writelane_b32 v248, s4, 29
	v_add_u32_e32 v35, 0x52, v12
	v_add_u32_e32 v36, 0x53, v12
	v_writelane_b32 v248, s5, 30
	v_cmp_gt_i32_e64 s[4:5], v2, v13
	v_or_b32_e32 v2, 0x42, v12
	v_add_u32_e32 v37, 0x54, v12
	v_writelane_b32 v248, s4, 31
	v_add_u32_e32 v38, 0x55, v12
	v_add_u32_e32 v39, 0x56, v12
	v_writelane_b32 v248, s5, 32
	v_cmp_gt_i32_e64 s[4:5], v2, v13
	v_or_b32_e32 v2, 0x43, v12
	v_add_u32_e32 v40, 0x57, v12
	v_writelane_b32 v248, s4, 33
	v_ashrrev_i32_e32 v11, 31, v10
	v_readlane_b32 s68, v249, 19
	v_writelane_b32 v248, s5, 34
	v_cmp_gt_i32_e64 s[4:5], v2, v13
	v_or_b32_e32 v2, 0x44, v12
	v_and_b32_e32 v57, 48, v52
	v_writelane_b32 v248, s4, 35
	s_waitcnt lgkmcnt(0)
	v_lshl_add_u64 v[60:61], s[6:7], 0, v[48:49]
	v_cmp_lt_i32_e64 s[6:7], -1, v51
	v_writelane_b32 v248, s5, 36
	v_cmp_gt_i32_e64 s[4:5], v2, v13
	v_or_b32_e32 v2, 0x45, v12
	v_cmp_gt_i32_e64 s[80:81], v12, v18
	v_writelane_b32 v248, s4, 37
	v_cmp_lt_i32_e64 s[82:83], v12, v18
	v_or_b32_e32 v104, 32, v56
	v_writelane_b32 v248, s5, 38
	v_cmp_gt_i32_e64 s[4:5], v2, v13
	v_or_b32_e32 v2, 0x46, v12
	v_or_b32_e32 v105, 48, v56
	v_writelane_b32 v248, s4, 39
	v_or_b32_e32 v106, 64, v56
	v_or_b32_e32 v107, 0x50, v56
	v_writelane_b32 v248, s5, 40
	v_cmp_gt_i32_e64 s[4:5], v2, v13
	v_or_b32_e32 v2, 0x47, v12
	v_lshlrev_b64 v[98:99], 11, v[10:11]
	v_writelane_b32 v248, s4, 41
	v_lshlrev_b32_e32 v102, 1, v56
	v_cmp_gt_i32_e64 s[94:95], v12, v19
	v_writelane_b32 v248, s5, 42
	v_cmp_gt_i32_e64 s[4:5], v2, v13
	v_lshlrev_b32_e32 v2, 7, v18
	v_ashrrev_i32_e32 v3, 31, v2
	v_writelane_b32 v248, s4, 43
	v_lshl_add_u64 v[2:3], v[2:3], 2, s[2:3]
	v_lshl_add_u64 v[64:65], v[2:3], 0, v[4:5]
	global_load_dwordx4 v[140:143], v[62:63], off
	global_load_dwordx4 v[144:147], v[62:63], off offset:16
	global_load_dwordx4 v[148:151], v[62:63], off offset:272
	global_load_dwordx4 v[152:155], v[62:63], off offset:256
	global_load_dwordx4 v[156:159], v[62:63], off offset:144
	global_load_dwordx4 v[160:163], v[62:63], off offset:128
	global_load_dwordx4 v[164:167], v[62:63], off offset:400
	global_load_dwordx4 v[168:171], v[62:63], off offset:384
	global_load_dwordx4 v[172:175], v[64:65], off
	global_load_dwordx4 v[176:179], v[64:65], off offset:16
	global_load_dwordx4 v[180:183], v[64:65], off offset:272
	global_load_dwordx4 v[184:187], v[64:65], off offset:256
	global_load_dwordx4 v[188:191], v[64:65], off offset:144
	global_load_dwordx4 v[192:195], v[64:65], off offset:128
	global_load_dwordx4 v[196:199], v[64:65], off offset:400
	global_load_dwordx4 v[200:203], v[64:65], off offset:384
	v_writelane_b32 v248, s5, 44
	v_cmp_gt_i32_e64 s[4:5], v16, v13
	v_add_u32_e32 v2, 10, v13
	v_cmp_gt_i32_e64 s[92:93], v12, v2
	v_writelane_b32 v248, s4, 45
	v_cmp_lt_i32_e64 s[96:97], 31, v17
	v_cmp_gt_i32_e64 s[60:61], v20, v13
	v_writelane_b32 v248, s5, 46
	v_cmp_gt_i32_e64 s[4:5], v1, v13
	v_or_b32_e32 v1, 0x62, v12
	v_cmp_gt_i32_e64 s[8:9], v21, v13
	v_writelane_b32 v248, s4, 47
	v_cmp_gt_i32_e64 s[10:11], v23, v13
	v_cmp_gt_i32_e64 s[12:13], v24, v13
	v_writelane_b32 v248, s5, 48
	v_cmp_gt_i32_e64 s[4:5], v1, v13
	v_or_b32_e32 v1, 0x63, v12
	v_cmp_gt_i32_e64 s[14:15], v25, v13
	v_writelane_b32 v248, s4, 49
	v_cmp_gt_i32_e64 s[16:17], v26, v13
	v_cmp_lt_i32_e64 s[18:19], 63, v17
	v_writelane_b32 v248, s5, 50
	v_cmp_gt_i32_e64 s[4:5], v1, v13
	v_or_b32_e32 v1, 0x64, v12
	v_cmp_gt_i32_e64 s[72:73], v1, v13
	v_or_b32_e32 v1, 0x65, v12
	v_cmp_gt_i32_e64 s[74:75], v1, v13
	v_or_b32_e32 v1, 0x66, v12
	v_cmp_gt_i32_e64 s[76:77], v1, v13
	v_or_b32_e32 v1, 0x67, v12
	v_cmp_gt_i32_e64 s[78:79], v1, v13
	v_add_u32_e32 v1, 14, v13
	v_cmp_gt_i32_e64 s[84:85], v12, v1
	v_add_u32_e32 v1, 13, v13
	v_cmp_gt_i32_e64 s[86:87], v12, v1
	v_add_u32_e32 v1, 12, v13
	v_cmp_gt_i32_e64 s[88:89], v12, v1
	v_add_u32_e32 v1, 11, v13
	v_cmp_gt_i32_e64 s[90:91], v12, v1
	v_ashrrev_i32_e32 v1, 31, v0
	v_lshl_add_u64 v[4:5], v[0:1], 2, s[0:1]
	global_load_dwordx4 v[0:3], v[4:5], off
	s_nop 0
	global_load_dwordx4 v[4:7], v[4:5], off offset:64
	v_mad_i64_i32 v[68:69], s[0:1], v9, s46, 0
	v_add_u32_e32 v9, 2, v41
	v_mad_i64_i32 v[70:71], s[0:1], v9, s46, 0
	v_add_u32_e32 v9, 3, v41
	v_mad_i64_i32 v[72:73], s[0:1], v9, s46, 0
	v_ashrrev_i32_e32 v9, 31, v8
	v_lshlrev_b64 v[74:75], 11, v[8:9]
	v_add_u32_e32 v9, 16, v41
	v_mad_i64_i32 v[86:87], s[0:1], v9, s46, 0
	v_add_u32_e32 v9, 17, v41
	v_mad_i64_i32 v[88:89], s[0:1], v9, s46, 0
	v_add_u32_e32 v9, 18, v41
	v_mad_i64_i32 v[90:91], s[0:1], v9, s46, 0
	v_add_u32_e32 v9, 19, v41
	v_or_b32_e32 v8, 19, v8
	v_writelane_b32 v248, s4, 51
	v_mad_i64_i32 v[66:67], s[0:1], v41, s46, 0
	v_mad_i64_i32 v[92:93], s[0:1], v9, s46, 0
	v_ashrrev_i32_e32 v9, 31, v8
	v_writelane_b32 v248, s5, 52
	v_lshlrev_b64 v[100:101], 11, v[8:9]
	v_cmp_gt_i32_e64 s[4:5], v14, v18
	v_cmp_gt_i32_e64 s[0:1], v22, v13
	v_cmp_gt_i32_e64 s[20:21], v15, v18
	v_cmp_gt_i32_e64 s[22:23], v27, v13
	v_cmp_gt_i32_e64 s[26:27], v28, v13
	v_cmp_gt_i32_e64 s[66:67], v29, v13
	v_cmp_gt_i32_e64 s[30:31], v30, v13
	v_cmp_gt_i32_e64 s[34:35], v31, v13
	v_cmp_gt_i32_e64 s[36:37], v32, v13
	v_cmp_gt_i32_e64 s[38:39], v33, v13
	v_cmp_lt_i32_e64 s[40:41], s40, v17
	v_cmp_gt_i32_e64 s[42:43], v16, v18
	v_cmp_gt_i32_e64 s[46:47], v34, v13
	v_cmp_gt_i32_e64 s[48:49], v35, v13
	v_cmp_gt_i32_e64 s[50:51], v36, v13
	v_cmp_gt_i32_e64 s[52:53], v37, v13
	v_cmp_gt_i32_e64 s[54:55], v38, v13
	v_cmp_gt_i32_e64 s[56:57], v39, v13
	v_cmp_gt_i32_e64 s[58:59], v40, v13
	v_readlane_b32 s69, v249, 20
	s_mov_b32 s68, 0
	s_mov_b64 s[64:65], -1
	s_waitcnt vmcnt(0)
	s_branch .LBB0_114

.LBB0_114:
	v_mov_b32_e32 v81, v80
	v_or_b32_e32 v8, s68, v56
	v_add_u32_e32 v9, s68, v104
	v_add_u32_e32 v10, s68, v105
	v_add_u32_e32 v11, s68, v106
	v_add_u32_e32 v12, s68, v107
	s_movk_i32 s2, 0x110
	v_mov_b32_e32 v82, v80
	v_mov_b32_e32 v83, v80
	v_mad_u32_u24 v111, v8, s2, v57
	v_mad_u32_u24 v110, v9, s2, v57
	v_mad_u32_u24 v109, v10, s2, v57
	v_mad_u32_u24 v108, v11, s2, v57
	v_mad_u32_u24 v103, v12, s2, v57
	v_mov_b64_e32 v[8:9], v[80:81]
	v_mov_b64_e32 v[12:13], v[80:81]
	v_mov_b64_e32 v[16:17], v[80:81]
	v_mov_b64_e32 v[20:21], v[80:81]
	v_mov_b64_e32 v[24:25], v[80:81]
	v_mov_b64_e32 v[28:29], v[80:81]
	s_mov_b64 s[70:71], s[68:69]
	v_mov_b64_e32 v[10:11], v[82:83]
	v_mov_b64_e32 v[14:15], v[82:83]
	v_mov_b64_e32 v[18:19], v[82:83]
	v_mov_b64_e32 v[22:23], v[82:83]
	v_mov_b64_e32 v[26:27], v[82:83]
	v_mov_b64_e32 v[30:31], v[82:83]
	s_and_saveexec_b64 s[2:3], s[6:7]
	s_cbranch_execz .LBB0_118
	v_mov_b32_e32 v8, v140
	v_mov_b32_e32 v9, v141
	v_mov_b32_e32 v10, v142
	v_mov_b32_e32 v11, v143
	v_mov_b32_e32 v12, v144
	v_mov_b32_e32 v13, v145
	v_mov_b32_e32 v14, v146
	v_mov_b32_e32 v15, v147
	v_readlane_b32 s68, v249, 63
	v_readlane_b32 s69, v248, 0
	s_nop 0
	s_nop 0
	v_cndmask_b32_e64 v8, v8, 0, s[68:69]
	v_readlane_b32 s68, v248, 1
	v_readlane_b32 s69, v248, 2
	v_bfe_u32 v16, v8, 16, 1
	v_add3_u32 v8, v8, v16, s33
	v_cndmask_b32_e64 v9, 0, v9, s[68:69]
	v_readlane_b32 s68, v248, 3
	v_readlane_b32 s69, v248, 4
	v_bfe_u32 v17, v9, 16, 1
	v_add3_u32 v9, v9, v17, s33
	v_cndmask_b32_e64 v10, v10, 0, s[68:69]
	v_readlane_b32 s68, v248, 5
	v_readlane_b32 s69, v248, 6
	v_bfe_u32 v18, v10, 16, 1
	v_add3_u32 v10, v10, v18, s33
	v_cndmask_b32_e64 v11, v11, 0, s[68:69]
	v_readlane_b32 s68, v248, 7
	v_readlane_b32 s69, v248, 8
	v_bfe_u32 v19, v11, 16, 1
	v_add3_u32 v11, v11, v19, s33
	s_nop 0
	v_cndmask_b32_e64 v12, v12, 0, s[68:69]
	v_readlane_b32 s68, v249, 59
	v_readlane_b32 s69, v249, 60
	v_bfe_u32 v20, v12, 16, 1
	v_add3_u32 v12, v12, v20, s33
	v_cndmask_b32_e64 v13, v13, 0, s[68:69]
	v_readlane_b32 s68, v249, 57
	v_readlane_b32 s69, v249, 58
	v_bfe_u32 v21, v13, 16, 1
	v_add3_u32 v13, v13, v21, s33
	v_cndmask_b32_e64 v14, v14, 0, s[68:69]
	v_readlane_b32 s68, v249, 61
	v_readlane_b32 s69, v249, 62
	v_bfe_u32 v22, v14, 16, 1
	v_add3_u32 v14, v14, v22, s33
	v_cndmask_b32_e64 v15, v15, 0, s[68:69]
	v_bfe_u32 v23, v15, 16, 1
	v_add3_u32 v15, v15, v23, s33
	v_lshrrev_b32_e32 v8, 16, v8
	v_lshrrev_b32_e32 v10, 16, v10
	v_lshrrev_b32_e32 v12, 16, v12
	v_lshrrev_b32_e32 v14, 16, v14
	v_and_or_b32 v8, v9, s29, v8
	v_and_or_b32 v9, v11, s29, v10
	v_and_or_b32 v10, v13, s29, v12
	v_and_or_b32 v11, v15, s29, v14
	ds_read_b128 v[12:15], v111 offset:2560
	ds_read_b128 v[16:19], v111 offset:6912
	s_waitcnt lgkmcnt(1)
	v_mfma_f32_16x16x32_bf16 v[28:31], v[8:11], v[12:15], 0
	s_waitcnt lgkmcnt(0)
	v_mfma_f32_16x16x32_bf16 v[24:27], v[8:11], v[16:19], 0
	ds_read_b128 v[12:15], v110 offset:2560
	ds_read_b128 v[16:19], v109 offset:2560
	s_waitcnt lgkmcnt(1)
	v_mfma_f32_16x16x32_bf16 v[20:23], v[8:11], v[12:15], 0
	ds_read_b128 v[12:15], v108 offset:2560
	ds_read_b128 v[32:35], v103 offset:2560
	s_waitcnt lgkmcnt(2)
	v_mfma_f32_16x16x32_bf16 v[16:19], v[8:11], v[16:19], 0
	s_waitcnt lgkmcnt(1)
	v_mfma_f32_16x16x32_bf16 v[12:15], v[8:11], v[12:15], 0
	s_waitcnt lgkmcnt(0)
	v_mfma_f32_16x16x32_bf16 v[8:11], v[8:11], v[32:35], 0
	s_or_b64 exec, exec, s[2:3]
	s_and_saveexec_b64 s[2:3], s[24:25]
	s_cbranch_execnz .LBB0_119

.LBB0_117:
	v_mov_b32_e32 v32, v148
	v_mov_b32_e32 v33, v149
	v_mov_b32_e32 v34, v150
	v_mov_b32_e32 v35, v151
	v_mov_b32_e32 v36, v152
	v_mov_b32_e32 v37, v153
	v_mov_b32_e32 v38, v154
	v_mov_b32_e32 v39, v155
	v_readlane_b32 s68, v248, 29
	v_readlane_b32 s69, v248, 30
	s_nop 0
	s_nop 0
	v_cndmask_b32_e64 v36, v36, 0, s[68:69]
	v_readlane_b32 s68, v248, 31
	v_readlane_b32 s69, v248, 32
	v_bfe_u32 v40, v36, 16, 1
	v_add3_u32 v36, v36, v40, s33
	v_cndmask_b32_e64 v37, v37, 0, s[68:69]
	v_bfe_u32 v40, v37, 16, 1
	v_readlane_b32 s68, v248, 33
	v_add3_u32 v37, v37, v40, s33
	v_lshrrev_b32_e32 v36, 16, v36
	v_readlane_b32 s69, v248, 34
	v_and_or_b32 v36, v37, s29, v36
	s_nop 0
	v_cndmask_b32_e64 v37, v38, 0, s[68:69]
	v_readlane_b32 s68, v248, 35
	v_readlane_b32 s69, v248, 36
	s_nop 1
	v_cndmask_b32_e64 v38, v39, 0, s[68:69]
	v_readlane_b32 s68, v248, 37
	v_bfe_u32 v39, v37, 16, 1
	v_readlane_b32 s69, v248, 38
	v_add3_u32 v37, v37, v39, s33
	v_bfe_u32 v39, v38, 16, 1
	v_cndmask_b32_e64 v32, v32, 0, s[68:69]
	v_readlane_b32 s68, v248, 39
	v_add3_u32 v38, v38, v39, s33
	v_lshrrev_b32_e32 v37, 16, v37
	v_readlane_b32 s69, v248, 40
	v_and_or_b32 v37, v38, s29, v37
	v_bfe_u32 v38, v32, 16, 1
	v_cndmask_b32_e64 v33, v33, 0, s[68:69]
	v_add3_u32 v32, v32, v38, s33
	v_bfe_u32 v38, v33, 16, 1
	v_readlane_b32 s68, v248, 41
	v_add3_u32 v33, v33, v38, s33
	v_lshrrev_b32_e32 v32, 16, v32
	v_readlane_b32 s69, v248, 42
	v_and_or_b32 v38, v33, s29, v32
	s_nop 0
	v_cndmask_b32_e64 v32, v34, 0, s[68:69]
	v_readlane_b32 s68, v248, 43
	v_readlane_b32 s69, v248, 44
	v_bfe_u32 v34, v32, 16, 1
	v_add3_u32 v32, v32, v34, s33
	v_cndmask_b32_e64 v33, v35, 0, s[68:69]
	v_bfe_u32 v34, v33, 16, 1
	v_add3_u32 v33, v33, v34, s33
	v_lshrrev_b32_e32 v32, 16, v32
	v_and_or_b32 v39, v33, s29, v32
	ds_read_b128 v[32:35], v111 offset:2688
	s_waitcnt lgkmcnt(0)
	v_mfma_f32_16x16x32_bf16 v[28:31], v[36:39], v[32:35], v[28:31]
	ds_read_b128 v[32:35], v111 offset:7040
	s_waitcnt lgkmcnt(0)
	v_mfma_f32_16x16x32_bf16 v[24:27], v[36:39], v[32:35], v[24:27]
	ds_read_b128 v[32:35], v110 offset:2688
	s_waitcnt lgkmcnt(0)
	v_mfma_f32_16x16x32_bf16 v[20:23], v[36:39], v[32:35], v[20:23]
	ds_read_b128 v[32:35], v109 offset:2688
	s_waitcnt lgkmcnt(0)
	v_mfma_f32_16x16x32_bf16 v[16:19], v[36:39], v[32:35], v[16:19]
	ds_read_b128 v[32:35], v108 offset:2688
	s_waitcnt lgkmcnt(0)
	v_mfma_f32_16x16x32_bf16 v[12:15], v[36:39], v[32:35], v[12:15]
	ds_read_b128 v[32:35], v103 offset:2688
	s_waitcnt lgkmcnt(0)
	v_mfma_f32_16x16x32_bf16 v[8:11], v[36:39], v[32:35], v[8:11]
	s_or_b64 exec, exec, s[2:3]
	s_and_saveexec_b64 s[2:3], s[62:63]
	s_cbranch_execnz .LBB0_121
	s_branch .LBB0_122

.LBB0_119:
	v_mov_b32_e32 v32, v156
	v_mov_b32_e32 v33, v157
	v_mov_b32_e32 v34, v158
	v_mov_b32_e32 v35, v159
	v_mov_b32_e32 v36, v160
	v_mov_b32_e32 v37, v161
	v_mov_b32_e32 v38, v162
	v_mov_b32_e32 v39, v163
	v_readlane_b32 s68, v249, 55
	v_readlane_b32 s69, v249, 56
	s_nop 0
	s_nop 0
	v_cndmask_b32_e64 v36, v36, 0, s[68:69]
	v_readlane_b32 s68, v248, 15
	v_readlane_b32 s69, v248, 16
	v_bfe_u32 v40, v36, 16, 1
	v_add3_u32 v36, v36, v40, s33
	v_cndmask_b32_e64 v37, v37, 0, s[68:69]
	v_bfe_u32 v40, v37, 16, 1
	v_readlane_b32 s68, v248, 17
	v_add3_u32 v37, v37, v40, s33
	v_lshrrev_b32_e32 v36, 16, v36
	v_readlane_b32 s69, v248, 18
	v_and_or_b32 v36, v37, s29, v36
	s_nop 0
	v_cndmask_b32_e64 v37, v38, 0, s[68:69]
	v_readlane_b32 s68, v248, 19
	v_readlane_b32 s69, v248, 20
	s_nop 1
	v_cndmask_b32_e64 v38, v39, 0, s[68:69]
	v_readlane_b32 s68, v248, 21
	v_bfe_u32 v39, v37, 16, 1
	v_readlane_b32 s69, v248, 22
	v_add3_u32 v37, v37, v39, s33
	v_bfe_u32 v39, v38, 16, 1
	v_cndmask_b32_e64 v32, v32, 0, s[68:69]
	v_readlane_b32 s68, v248, 23
	v_add3_u32 v38, v38, v39, s33
	v_lshrrev_b32_e32 v37, 16, v37
	v_readlane_b32 s69, v248, 24
	v_and_or_b32 v37, v38, s29, v37
	v_bfe_u32 v38, v32, 16, 1
	v_cndmask_b32_e64 v33, v33, 0, s[68:69]
	v_add3_u32 v32, v32, v38, s33
	v_bfe_u32 v38, v33, 16, 1
	v_readlane_b32 s68, v248, 25
	v_add3_u32 v33, v33, v38, s33
	v_lshrrev_b32_e32 v32, 16, v32
	v_readlane_b32 s69, v248, 26
	v_and_or_b32 v38, v33, s29, v32
	s_nop 0
	v_cndmask_b32_e64 v32, v34, 0, s[68:69]
	v_readlane_b32 s68, v248, 27
	v_readlane_b32 s69, v248, 28
	v_bfe_u32 v34, v32, 16, 1
	v_add3_u32 v32, v32, v34, s33
	v_cndmask_b32_e64 v33, v35, 0, s[68:69]
	v_bfe_u32 v34, v33, 16, 1
	v_add3_u32 v33, v33, v34, s33
	v_lshrrev_b32_e32 v32, 16, v32
	v_and_or_b32 v39, v33, s29, v32
	ds_read_b128 v[32:35], v111 offset:2624
	s_waitcnt lgkmcnt(0)
	v_mfma_f32_16x16x32_bf16 v[28:31], v[36:39], v[32:35], v[28:31]
	ds_read_b128 v[32:35], v111 offset:6976
	s_waitcnt lgkmcnt(0)
	v_mfma_f32_16x16x32_bf16 v[24:27], v[36:39], v[32:35], v[24:27]
	ds_read_b128 v[32:35], v110 offset:2624
	s_waitcnt lgkmcnt(0)
	v_mfma_f32_16x16x32_bf16 v[20:23], v[36:39], v[32:35], v[20:23]
	ds_read_b128 v[32:35], v109 offset:2624
	s_waitcnt lgkmcnt(0)
	v_mfma_f32_16x16x32_bf16 v[16:19], v[36:39], v[32:35], v[16:19]
	ds_read_b128 v[32:35], v108 offset:2624
	s_waitcnt lgkmcnt(0)
	v_mfma_f32_16x16x32_bf16 v[12:15], v[36:39], v[32:35], v[12:15]
	ds_read_b128 v[32:35], v103 offset:2624
	s_waitcnt lgkmcnt(0)
	v_mfma_f32_16x16x32_bf16 v[8:11], v[36:39], v[32:35], v[8:11]
	s_or_b64 exec, exec, s[2:3]
	s_and_saveexec_b64 s[2:3], s[44:45]
	s_cbranch_execnz .LBB0_117

.LBB0_121:
	v_mov_b32_e32 v32, v164
	v_mov_b32_e32 v33, v165
	v_mov_b32_e32 v34, v166
	v_mov_b32_e32 v35, v167
	v_mov_b32_e32 v36, v168
	v_mov_b32_e32 v37, v169
	v_mov_b32_e32 v38, v170
	v_mov_b32_e32 v39, v171
	v_readlane_b32 s68, v248, 45
	v_readlane_b32 s69, v248, 46
	s_nop 0
	v_cndmask_b32_e64 v32, v32, 0, s[72:73]
	s_nop 0
	v_cndmask_b32_e64 v36, v36, 0, s[68:69]
	v_readlane_b32 s68, v248, 47
	v_readlane_b32 s69, v248, 48
	v_bfe_u32 v40, v36, 16, 1
	v_add3_u32 v36, v36, v40, s33
	v_cndmask_b32_e64 v37, v37, 0, s[68:69]
	v_bfe_u32 v40, v37, 16, 1
	v_readlane_b32 s68, v248, 49
	v_add3_u32 v37, v37, v40, s33
	v_lshrrev_b32_e32 v36, 16, v36
	v_readlane_b32 s69, v248, 50
	v_and_or_b32 v36, v37, s29, v36
	v_cndmask_b32_e64 v33, v33, 0, s[74:75]
	v_cndmask_b32_e64 v37, v38, 0, s[68:69]
	v_readlane_b32 s68, v248, 51
	v_readlane_b32 s69, v248, 52
	s_nop 1
	v_cndmask_b32_e64 v38, v39, 0, s[68:69]
	v_bfe_u32 v39, v37, 16, 1
	v_add3_u32 v37, v37, v39, s33
	v_bfe_u32 v39, v38, 16, 1
	v_add3_u32 v38, v38, v39, s33
	v_lshrrev_b32_e32 v37, 16, v37
	v_and_or_b32 v37, v38, s29, v37
	v_bfe_u32 v38, v32, 16, 1
	v_add3_u32 v32, v32, v38, s33
	v_bfe_u32 v38, v33, 16, 1
	v_add3_u32 v33, v33, v38, s33
	v_lshrrev_b32_e32 v32, 16, v32
	v_and_or_b32 v38, v33, s29, v32
	v_cndmask_b32_e64 v32, v34, 0, s[76:77]
	v_cndmask_b32_e64 v33, v35, 0, s[78:79]
	v_bfe_u32 v34, v32, 16, 1
	v_add3_u32 v32, v32, v34, s33
	v_bfe_u32 v34, v33, 16, 1
	v_add3_u32 v33, v33, v34, s33
	v_lshrrev_b32_e32 v32, 16, v32
	v_and_or_b32 v39, v33, s29, v32
	ds_read_b128 v[32:35], v111 offset:2752
	s_waitcnt lgkmcnt(0)
	v_mfma_f32_16x16x32_bf16 v[28:31], v[36:39], v[32:35], v[28:31]
	ds_read_b128 v[32:35], v111 offset:7104
	s_waitcnt lgkmcnt(0)
	v_mfma_f32_16x16x32_bf16 v[24:27], v[36:39], v[32:35], v[24:27]
	ds_read_b128 v[32:35], v110 offset:2752
	s_waitcnt lgkmcnt(0)
	v_mfma_f32_16x16x32_bf16 v[20:23], v[36:39], v[32:35], v[20:23]
	ds_read_b128 v[32:35], v109 offset:2752
	s_waitcnt lgkmcnt(0)
	v_mfma_f32_16x16x32_bf16 v[16:19], v[36:39], v[32:35], v[16:19]
	ds_read_b128 v[32:35], v108 offset:2752
	s_waitcnt lgkmcnt(0)
	v_mfma_f32_16x16x32_bf16 v[12:15], v[36:39], v[32:35], v[12:15]
	ds_read_b128 v[32:35], v103 offset:2752
	s_waitcnt lgkmcnt(0)
	v_mfma_f32_16x16x32_bf16 v[8:11], v[36:39], v[32:35], v[8:11]
.LBB0_122:
	s_or_b64 exec, exec, s[2:3]
	v_mov_b32_e32 v81, v80
	v_mov_b32_e32 v82, v80
	v_mov_b32_e32 v83, v80
	v_mov_b64_e32 v[32:33], v[80:81]
	v_mov_b64_e32 v[36:37], v[80:81]
	v_mov_b64_e32 v[40:41], v[80:81]
	v_mov_b64_e32 v[44:45], v[80:81]
	v_mov_b64_e32 v[48:49], v[80:81]
	v_mov_b64_e32 v[52:53], v[80:81]
	v_mov_b64_e32 v[34:35], v[82:83]
	v_mov_b64_e32 v[38:39], v[82:83]
	v_mov_b64_e32 v[42:43], v[82:83]
	v_mov_b64_e32 v[46:47], v[82:83]
	v_mov_b64_e32 v[50:51], v[82:83]
	v_mov_b64_e32 v[54:55], v[82:83]
	s_and_saveexec_b64 s[2:3], s[6:7]
	s_cbranch_execz .LBB0_126
	v_mov_b32_e32 v32, v172
	v_mov_b32_e32 v33, v173
	v_mov_b32_e32 v34, v174
	v_mov_b32_e32 v35, v175
	v_mov_b32_e32 v36, v176
	v_mov_b32_e32 v37, v177
	v_mov_b32_e32 v38, v178
	v_mov_b32_e32 v39, v179
	s_nop 0
	v_cndmask_b32_e64 v32, v32, 0, s[80:81]
	v_cndmask_b32_e64 v34, v34, 0, s[84:85]
	s_nop 0
	v_cndmask_b32_e64 v36, v36, 0, s[88:89]
	v_cndmask_b32_e64 v38, v38, 0, s[92:93]
	v_cndmask_b32_e64 v33, 0, v33, s[82:83]
	v_cndmask_b32_e64 v35, v35, 0, s[86:87]
	v_cndmask_b32_e64 v37, v37, 0, s[90:91]
	v_cndmask_b32_e64 v39, v39, 0, s[94:95]
	v_bfe_u32 v40, v32, 16, 1
	v_bfe_u32 v42, v34, 16, 1
	v_bfe_u32 v44, v36, 16, 1
	v_bfe_u32 v46, v38, 16, 1
	v_bfe_u32 v41, v33, 16, 1
	v_bfe_u32 v43, v35, 16, 1
	v_bfe_u32 v45, v37, 16, 1
	v_bfe_u32 v47, v39, 16, 1
	v_add3_u32 v32, v32, v40, s33
	v_add3_u32 v34, v34, v42, s33
	v_add3_u32 v36, v36, v44, s33
	v_add3_u32 v38, v38, v46, s33
	v_add3_u32 v33, v33, v41, s33
	v_add3_u32 v35, v35, v43, s33
	v_add3_u32 v37, v37, v45, s33
	v_add3_u32 v39, v39, v47, s33
	v_lshrrev_b32_e32 v32, 16, v32
	v_lshrrev_b32_e32 v34, 16, v34
	v_lshrrev_b32_e32 v36, 16, v36
	v_lshrrev_b32_e32 v38, 16, v38
	v_and_or_b32 v32, v33, s29, v32
	v_and_or_b32 v33, v35, s29, v34
	v_and_or_b32 v34, v37, s29, v36
	v_and_or_b32 v35, v39, s29, v38
	ds_read_b128 v[36:39], v111 offset:2560
	ds_read_b128 v[40:43], v111 offset:6912
	s_waitcnt lgkmcnt(1)
	v_mfma_f32_16x16x32_bf16 v[52:55], v[32:35], v[36:39], 0
	s_waitcnt lgkmcnt(0)
	v_mfma_f32_16x16x32_bf16 v[48:51], v[32:35], v[40:43], 0
	ds_read_b128 v[36:39], v110 offset:2560
	ds_read_b128 v[40:43], v109 offset:2560
	s_waitcnt lgkmcnt(1)
	v_mfma_f32_16x16x32_bf16 v[44:47], v[32:35], v[36:39], 0
	ds_read_b128 v[36:39], v108 offset:2560
	ds_read_b128 v[116:119], v103 offset:2560
	s_waitcnt lgkmcnt(2)
	v_mfma_f32_16x16x32_bf16 v[40:43], v[32:35], v[40:43], 0
	s_waitcnt lgkmcnt(1)
	v_mfma_f32_16x16x32_bf16 v[36:39], v[32:35], v[36:39], 0
	s_waitcnt lgkmcnt(0)
	v_mfma_f32_16x16x32_bf16 v[32:35], v[32:35], v[116:119], 0
	s_or_b64 exec, exec, s[2:3]
	s_and_saveexec_b64 s[2:3], s[96:97]
	s_cbranch_execnz .LBB0_127

.LBB0_125:
	v_mov_b32_e32 v116, v180
	v_mov_b32_e32 v117, v181
	v_mov_b32_e32 v118, v182
	v_mov_b32_e32 v119, v183
	v_mov_b32_e32 v120, v184
	v_mov_b32_e32 v121, v185
	v_mov_b32_e32 v122, v186
	v_mov_b32_e32 v123, v187
	s_nop 0
	v_cndmask_b32_e64 v81, v120, 0, s[20:21]
	v_cndmask_b32_e64 v82, v121, 0, s[22:23]
	v_bfe_u32 v83, v81, 16, 1
	v_add3_u32 v81, v81, v83, s33
	v_bfe_u32 v83, v82, 16, 1
	v_add3_u32 v82, v82, v83, s33
	v_lshrrev_b32_e32 v81, 16, v81
	v_and_or_b32 v120, v82, s29, v81
	v_cndmask_b32_e64 v81, v122, 0, s[26:27]
	v_cndmask_b32_e64 v82, v123, 0, s[66:67]
	v_bfe_u32 v83, v81, 16, 1
	v_add3_u32 v81, v81, v83, s33
	v_bfe_u32 v83, v82, 16, 1
	v_add3_u32 v82, v82, v83, s33
	v_lshrrev_b32_e32 v81, 16, v81
	v_and_or_b32 v121, v82, s29, v81
	v_cndmask_b32_e64 v81, v116, 0, s[30:31]
	v_cndmask_b32_e64 v82, v117, 0, s[34:35]
	v_bfe_u32 v83, v81, 16, 1
	v_add3_u32 v81, v81, v83, s33
	v_bfe_u32 v83, v82, 16, 1
	v_add3_u32 v82, v82, v83, s33
	v_lshrrev_b32_e32 v81, 16, v81
	v_and_or_b32 v122, v82, s29, v81
	v_cndmask_b32_e64 v81, v118, 0, s[36:37]
	v_cndmask_b32_e64 v82, v119, 0, s[38:39]
	v_bfe_u32 v83, v81, 16, 1
	v_add3_u32 v81, v81, v83, s33
	v_bfe_u32 v83, v82, 16, 1
	v_add3_u32 v82, v82, v83, s33
	v_lshrrev_b32_e32 v81, 16, v81
	v_and_or_b32 v123, v82, s29, v81
	ds_read_b128 v[116:119], v111 offset:2688
	s_waitcnt lgkmcnt(0)
	v_mfma_f32_16x16x32_bf16 v[52:55], v[120:123], v[116:119], v[52:55]
	ds_read_b128 v[116:119], v111 offset:7040
	s_waitcnt lgkmcnt(0)
	v_mfma_f32_16x16x32_bf16 v[48:51], v[120:123], v[116:119], v[48:51]
	ds_read_b128 v[116:119], v110 offset:2688
	s_waitcnt lgkmcnt(0)
	v_mfma_f32_16x16x32_bf16 v[44:47], v[120:123], v[116:119], v[44:47]
	ds_read_b128 v[116:119], v109 offset:2688
	s_waitcnt lgkmcnt(0)
	v_mfma_f32_16x16x32_bf16 v[40:43], v[120:123], v[116:119], v[40:43]
	ds_read_b128 v[116:119], v108 offset:2688
	s_waitcnt lgkmcnt(0)
	v_mfma_f32_16x16x32_bf16 v[36:39], v[120:123], v[116:119], v[36:39]
	ds_read_b128 v[116:119], v103 offset:2688
	s_waitcnt lgkmcnt(0)
	v_mfma_f32_16x16x32_bf16 v[32:35], v[120:123], v[116:119], v[32:35]
	s_or_b64 exec, exec, s[2:3]
	s_and_saveexec_b64 s[2:3], s[40:41]
	s_cbranch_execz .LBB0_113
	s_branch .LBB0_129

.LBB0_127:
	v_mov_b32_e32 v116, v188
	v_mov_b32_e32 v117, v189
	v_mov_b32_e32 v118, v190
	v_mov_b32_e32 v119, v191
	v_mov_b32_e32 v120, v192
	v_mov_b32_e32 v121, v193
	v_mov_b32_e32 v122, v194
	v_mov_b32_e32 v123, v195
	s_nop 0
	v_cndmask_b32_e64 v81, v120, 0, s[4:5]
	v_cndmask_b32_e64 v82, v121, 0, s[60:61]
	v_bfe_u32 v83, v81, 16, 1
	v_add3_u32 v81, v81, v83, s33
	v_bfe_u32 v83, v82, 16, 1
	v_add3_u32 v82, v82, v83, s33
	v_lshrrev_b32_e32 v81, 16, v81
	v_and_or_b32 v120, v82, s29, v81
	v_cndmask_b32_e64 v81, v122, 0, s[8:9]
	v_cndmask_b32_e64 v82, v123, 0, s[0:1]
	v_bfe_u32 v83, v81, 16, 1
	v_add3_u32 v81, v81, v83, s33
	v_bfe_u32 v83, v82, 16, 1
	v_add3_u32 v82, v82, v83, s33
	v_lshrrev_b32_e32 v81, 16, v81
	v_and_or_b32 v121, v82, s29, v81
	v_cndmask_b32_e64 v81, v116, 0, s[10:11]
	v_cndmask_b32_e64 v82, v117, 0, s[12:13]
	v_bfe_u32 v83, v81, 16, 1
	v_add3_u32 v81, v81, v83, s33
	v_bfe_u32 v83, v82, 16, 1
	v_add3_u32 v82, v82, v83, s33
	v_lshrrev_b32_e32 v81, 16, v81
	v_and_or_b32 v122, v82, s29, v81
	v_cndmask_b32_e64 v81, v118, 0, s[14:15]
	v_cndmask_b32_e64 v82, v119, 0, s[16:17]
	v_bfe_u32 v83, v81, 16, 1
	v_add3_u32 v81, v81, v83, s33
	v_bfe_u32 v83, v82, 16, 1
	v_add3_u32 v82, v82, v83, s33
	v_lshrrev_b32_e32 v81, 16, v81
	v_and_or_b32 v123, v82, s29, v81
	ds_read_b128 v[116:119], v111 offset:2624
	s_waitcnt lgkmcnt(0)
	v_mfma_f32_16x16x32_bf16 v[52:55], v[120:123], v[116:119], v[52:55]
	ds_read_b128 v[116:119], v111 offset:6976
	s_waitcnt lgkmcnt(0)
	v_mfma_f32_16x16x32_bf16 v[48:51], v[120:123], v[116:119], v[48:51]
	ds_read_b128 v[116:119], v110 offset:2624
	s_waitcnt lgkmcnt(0)
	v_mfma_f32_16x16x32_bf16 v[44:47], v[120:123], v[116:119], v[44:47]
	ds_read_b128 v[116:119], v109 offset:2624
	s_waitcnt lgkmcnt(0)
	v_mfma_f32_16x16x32_bf16 v[40:43], v[120:123], v[116:119], v[40:43]
	ds_read_b128 v[116:119], v108 offset:2624
	s_waitcnt lgkmcnt(0)
	v_mfma_f32_16x16x32_bf16 v[36:39], v[120:123], v[116:119], v[36:39]
	ds_read_b128 v[116:119], v103 offset:2624
	s_waitcnt lgkmcnt(0)
	v_mfma_f32_16x16x32_bf16 v[32:35], v[120:123], v[116:119], v[32:35]
	s_or_b64 exec, exec, s[2:3]
	s_and_saveexec_b64 s[2:3], s[18:19]
	s_cbranch_execnz .LBB0_125

.LBB0_129:
	v_mov_b32_e32 v116, v196
	v_mov_b32_e32 v117, v197
	v_mov_b32_e32 v118, v198
	v_mov_b32_e32 v119, v199
	v_mov_b32_e32 v120, v200
	v_mov_b32_e32 v121, v201
	v_mov_b32_e32 v122, v202
	v_mov_b32_e32 v123, v203
	s_nop 0
	v_cndmask_b32_e64 v81, v120, 0, s[42:43]
	v_cndmask_b32_e64 v82, v121, 0, s[46:47]
	v_bfe_u32 v83, v81, 16, 1
	v_add3_u32 v81, v81, v83, s33
	v_bfe_u32 v83, v82, 16, 1
	v_add3_u32 v82, v82, v83, s33
	v_lshrrev_b32_e32 v81, 16, v81
	v_and_or_b32 v120, v82, s29, v81
	v_cndmask_b32_e64 v81, v122, 0, s[48:49]
	v_cndmask_b32_e64 v82, v123, 0, s[50:51]
	v_bfe_u32 v83, v81, 16, 1
	v_add3_u32 v81, v81, v83, s33
	v_bfe_u32 v83, v82, 16, 1
	v_add3_u32 v82, v82, v83, s33
	v_lshrrev_b32_e32 v81, 16, v81
	v_and_or_b32 v121, v82, s29, v81
	v_cndmask_b32_e64 v81, v116, 0, s[52:53]
	v_cndmask_b32_e64 v82, v117, 0, s[54:55]
	v_bfe_u32 v83, v81, 16, 1
	v_add3_u32 v81, v81, v83, s33
	v_bfe_u32 v83, v82, 16, 1
	v_add3_u32 v82, v82, v83, s33
	v_lshrrev_b32_e32 v81, 16, v81
	v_and_or_b32 v122, v82, s29, v81
	v_cndmask_b32_e64 v81, v118, 0, s[56:57]
	v_cndmask_b32_e64 v82, v119, 0, s[58:59]
	v_bfe_u32 v83, v81, 16, 1
	v_add3_u32 v81, v81, v83, s33
	v_bfe_u32 v83, v82, 16, 1
	v_add3_u32 v82, v82, v83, s33
	v_lshrrev_b32_e32 v81, 16, v81
	v_and_or_b32 v123, v82, s29, v81
	ds_read_b128 v[116:119], v111 offset:2752
	s_waitcnt lgkmcnt(0)
	v_mfma_f32_16x16x32_bf16 v[52:55], v[120:123], v[116:119], v[52:55]
	ds_read_b128 v[116:119], v111 offset:7104
	ds_read_b128 v[110:113], v110 offset:2752
	s_waitcnt lgkmcnt(0)
	v_mfma_f32_16x16x32_bf16 v[44:47], v[120:123], v[110:113], v[44:47]
	ds_read_b128 v[110:113], v109 offset:2752
	s_waitcnt lgkmcnt(0)
	v_mfma_f32_16x16x32_bf16 v[40:43], v[120:123], v[110:113], v[40:43]
	ds_read_b128 v[108:111], v108 offset:2752
	s_waitcnt lgkmcnt(0)
	v_mfma_f32_16x16x32_bf16 v[36:39], v[120:123], v[108:111], v[36:39]
	ds_read_b128 v[108:111], v103 offset:2752
	v_mfma_f32_16x16x32_bf16 v[48:51], v[120:123], v[116:119], v[48:51]
	s_waitcnt lgkmcnt(0)
	v_mfma_f32_16x16x32_bf16 v[32:35], v[120:123], v[108:111], v[32:35]
	s_branch .LBB0_113

.LBB0_360:
	s_cmp_gt_i32 s10, 11
	s_cselect_b64 s[2:3], -1, 0
	s_xor_b64 s[14:15], s[0:1], -1
	s_or_b64 s[2:3], s[14:15], s[2:3]
	s_and_b64 vcc, exec, s[2:3]
	s_cbranch_vccnz .LBB0_618
	s_mov_b32 s48, 0x378e98ab
	s_mov_b32 s49, 0x3b7cd369
	s_mov_b32 s50, 0xbcc618b2
	s_mov_b32 s51, 0x3dda74e4
	s_mov_b32 s52, 0x3f228afd
	s_mov_b32 s53, 0x3e03c728
	s_mov_b32 s54, 0xbfb8aa3b
	s_mov_b32 s55, 0x42ce8ed0
	s_mov_b32 s56, 0xc2b17218
	v_mul_f32_e32 v67, 0x3f3504f3, v48
	v_mul_f32_e32 v69, 0x3f3504f3, v49
	v_fma_f32 v68, |v67|, s48, v233
	v_fma_f32 v70, |v69|, s48, v233
	v_fma_f32 v68, |v67|, v68, s49
	v_fma_f32 v70, |v69|, v70, s49
	v_fma_f32 v68, |v67|, v68, s50
	v_fma_f32 v70, |v69|, v70, s50
	v_fma_f32 v68, |v67|, v68, s51
	v_fma_f32 v70, |v69|, v70, s51
	v_fma_f32 v68, |v67|, v68, s52
	v_fma_f32 v70, |v69|, v70, s52
	v_fma_f32 v68, |v67|, v68, s53
	v_fma_f32 v70, |v69|, v70, s53
	v_fma_f32 v68, |v67|, v68, |v67|
	v_fma_f32 v70, |v69|, v70, |v69|
	v_mul_f32_e32 v243, 0xbfb8aa3b, v68
	v_mul_f32_e32 v250, 0xbfb8aa3b, v70
	v_fma_f32 v244, v68, s54, -v243
	v_fma_f32 v251, v70, s54, -v250
	v_rndne_f32_e32 v245, v243
	v_rndne_f32_e32 v252, v250
	v_fmac_f32_e32 v244, 0xb2a5705f, v68
	v_fmac_f32_e32 v251, 0xb2a5705f, v70
	v_sub_f32_e32 v243, v243, v245
	v_sub_f32_e32 v250, v250, v252
	v_add_f32_e32 v243, v243, v244
	v_add_f32_e32 v250, v250, v251
	v_cvt_i32_f32_e32 v244, v245
	v_cvt_i32_f32_e32 v251, v252
	v_exp_f32_e32 v243, v243
	v_exp_f32_e32 v250, v250
	v_mul_f32_e32 v246, v67, v67
	v_mul_f32_e32 v253, v69, v69
	v_ldexp_f32 v243, v243, v244
	v_ldexp_f32 v250, v250, v251
	v_cmp_nlt_f32_e64 s[2:3], s55, v68
	v_cmp_nlt_f32_e64 s[14:15], s55, v70
	v_fmamk_f32 v247, v246, 0xba1345e1, v222
	v_fmamk_f32 v254, v253, 0xba1345e1, v222
	v_fmaak_f32 v247, v246, v247, 0xbcdac9b8
	v_fmaak_f32 v254, v253, v254, 0xbcdac9b8
	v_cndmask_b32_e64 v243, 0, v243, s[2:3]
	v_cndmask_b32_e64 v250, 0, v250, s[14:15]
	v_cmp_ngt_f32_e64 s[2:3], s56, v68
	v_cmp_ngt_f32_e64 s[14:15], s56, v70
	v_fmaak_f32 v247, v246, v247, 0x3de703be
	v_fmaak_f32 v254, v253, v254, 0x3de703be
	v_fmaak_f32 v247, v246, v247, 0xbec09330
	v_fmaak_f32 v254, v253, v254, 0xbec09330
	v_cndmask_b32_e64 v243, v234, v243, s[2:3]
	v_cndmask_b32_e64 v250, v234, v250, s[14:15]
	v_fmaak_f32 v246, v246, v247, 0x3e0375d0
	v_fmaak_f32 v253, v253, v254, 0x3e0375d0
	v_cmp_nlt_f32_e64 s[2:3], |v67|, 1.0
	v_cmp_nlt_f32_e64 s[14:15], |v69|, 1.0
	v_sub_f32_e32 v243, 1.0, v243
	v_sub_f32_e32 v250, 1.0, v250
	v_fma_f32 v246, |v67|, v246, |v67|
	v_fma_f32 v253, |v69|, v253, |v69|
	v_cndmask_b32_e64 v68, v246, v243, s[2:3]
	v_cndmask_b32_e64 v70, v253, v250, s[14:15]
	v_mul_f32_e32 v71, 0x3f3504f3, v50
	v_mul_f32_e32 v97, 0x3f3504f3, v51
	v_fma_f32 v96, |v71|, s48, v233
	v_fma_f32 v98, |v97|, s48, v233
	v_fma_f32 v96, |v71|, v96, s49
	v_fma_f32 v98, |v97|, v98, s49
	v_fma_f32 v96, |v71|, v96, s50
	v_fma_f32 v98, |v97|, v98, s50
	v_fma_f32 v96, |v71|, v96, s51
	v_fma_f32 v98, |v97|, v98, s51
	v_fma_f32 v96, |v71|, v96, s52
	v_fma_f32 v98, |v97|, v98, s52
	v_fma_f32 v96, |v71|, v96, s53
	v_fma_f32 v98, |v97|, v98, s53
	v_fma_f32 v96, |v71|, v96, |v71|
	v_fma_f32 v98, |v97|, v98, |v97|
	v_mul_f32_e32 v243, 0xbfb8aa3b, v96
	v_mul_f32_e32 v250, 0xbfb8aa3b, v98
	v_fma_f32 v244, v96, s54, -v243
	v_fma_f32 v251, v98, s54, -v250
	v_rndne_f32_e32 v245, v243
	v_rndne_f32_e32 v252, v250
	v_fmac_f32_e32 v244, 0xb2a5705f, v96
	v_fmac_f32_e32 v251, 0xb2a5705f, v98
	v_sub_f32_e32 v243, v243, v245
	v_sub_f32_e32 v250, v250, v252
	v_add_f32_e32 v243, v243, v244
	v_add_f32_e32 v250, v250, v251
	v_cvt_i32_f32_e32 v244, v245
	v_cvt_i32_f32_e32 v251, v252
	v_exp_f32_e32 v243, v243
	v_exp_f32_e32 v250, v250
	v_mul_f32_e32 v246, v71, v71
	v_mul_f32_e32 v253, v97, v97
	v_ldexp_f32 v243, v243, v244
	v_ldexp_f32 v250, v250, v251
	v_cmp_nlt_f32_e64 s[2:3], s55, v96
	v_cmp_nlt_f32_e64 s[14:15], s55, v98
	v_fmamk_f32 v247, v246, 0xba1345e1, v222
	v_fmamk_f32 v254, v253, 0xba1345e1, v222
	v_fmaak_f32 v247, v246, v247, 0xbcdac9b8
	v_fmaak_f32 v254, v253, v254, 0xbcdac9b8
	v_cndmask_b32_e64 v243, 0, v243, s[2:3]
	v_cndmask_b32_e64 v250, 0, v250, s[14:15]
	v_cmp_ngt_f32_e64 s[2:3], s56, v96
	v_cmp_ngt_f32_e64 s[14:15], s56, v98
	v_fmaak_f32 v247, v246, v247, 0x3de703be
	v_fmaak_f32 v254, v253, v254, 0x3de703be
	v_fmaak_f32 v247, v246, v247, 0xbec09330
	v_fmaak_f32 v254, v253, v254, 0xbec09330
	v_cndmask_b32_e64 v243, v234, v243, s[2:3]
	v_cndmask_b32_e64 v250, v234, v250, s[14:15]
	v_fmaak_f32 v246, v246, v247, 0x3e0375d0
	v_fmaak_f32 v253, v253, v254, 0x3e0375d0
	v_cmp_nlt_f32_e64 s[2:3], |v71|, 1.0
	v_cmp_nlt_f32_e64 s[14:15], |v97|, 1.0
	v_sub_f32_e32 v243, 1.0, v243
	v_sub_f32_e32 v250, 1.0, v250
	v_fma_f32 v246, |v71|, v246, |v71|
	v_fma_f32 v253, |v97|, v253, |v97|
	v_cndmask_b32_e64 v96, v246, v243, s[2:3]
	v_cndmask_b32_e64 v98, v253, v250, s[14:15]
	v_mul_f32_e32 v99, 0x3f3504f3, v52
	v_mul_f32_e32 v101, 0x3f3504f3, v53
	v_fma_f32 v100, |v99|, s48, v233
	v_fma_f32 v102, |v101|, s48, v233
	v_fma_f32 v100, |v99|, v100, s49
	v_fma_f32 v102, |v101|, v102, s49
	v_fma_f32 v100, |v99|, v100, s50
	v_fma_f32 v102, |v101|, v102, s50
	v_fma_f32 v100, |v99|, v100, s51
	v_fma_f32 v102, |v101|, v102, s51
	v_fma_f32 v100, |v99|, v100, s52
	v_fma_f32 v102, |v101|, v102, s52
	v_fma_f32 v100, |v99|, v100, s53
	v_fma_f32 v102, |v101|, v102, s53
	v_fma_f32 v100, |v99|, v100, |v99|
	v_fma_f32 v102, |v101|, v102, |v101|
	v_mul_f32_e32 v243, 0xbfb8aa3b, v100
	v_mul_f32_e32 v250, 0xbfb8aa3b, v102
	v_fma_f32 v244, v100, s54, -v243
	v_fma_f32 v251, v102, s54, -v250
	v_rndne_f32_e32 v245, v243
	v_rndne_f32_e32 v252, v250
	v_fmac_f32_e32 v244, 0xb2a5705f, v100
	v_fmac_f32_e32 v251, 0xb2a5705f, v102
	v_sub_f32_e32 v243, v243, v245
	v_sub_f32_e32 v250, v250, v252
	v_add_f32_e32 v243, v243, v244
	v_add_f32_e32 v250, v250, v251
	v_cvt_i32_f32_e32 v244, v245
	v_cvt_i32_f32_e32 v251, v252
	v_exp_f32_e32 v243, v243
	v_exp_f32_e32 v250, v250
	v_mul_f32_e32 v246, v99, v99
	v_mul_f32_e32 v253, v101, v101
	v_ldexp_f32 v243, v243, v244
	v_ldexp_f32 v250, v250, v251
	v_cmp_nlt_f32_e64 s[2:3], s55, v100
	v_cmp_nlt_f32_e64 s[14:15], s55, v102
	v_fmamk_f32 v247, v246, 0xba1345e1, v222
	v_fmamk_f32 v254, v253, 0xba1345e1, v222
	v_fmaak_f32 v247, v246, v247, 0xbcdac9b8
	v_fmaak_f32 v254, v253, v254, 0xbcdac9b8
	v_cndmask_b32_e64 v243, 0, v243, s[2:3]
	v_cndmask_b32_e64 v250, 0, v250, s[14:15]
	v_cmp_ngt_f32_e64 s[2:3], s56, v100
	v_cmp_ngt_f32_e64 s[14:15], s56, v102
	v_fmaak_f32 v247, v246, v247, 0x3de703be
	v_fmaak_f32 v254, v253, v254, 0x3de703be
	v_fmaak_f32 v247, v246, v247, 0xbec09330
	v_fmaak_f32 v254, v253, v254, 0xbec09330
	v_cndmask_b32_e64 v243, v234, v243, s[2:3]
	v_cndmask_b32_e64 v250, v234, v250, s[14:15]
	v_fmaak_f32 v246, v246, v247, 0x3e0375d0
	v_fmaak_f32 v253, v253, v254, 0x3e0375d0
	v_cmp_nlt_f32_e64 s[2:3], |v99|, 1.0
	v_cmp_nlt_f32_e64 s[14:15], |v101|, 1.0
	v_sub_f32_e32 v243, 1.0, v243
	v_sub_f32_e32 v250, 1.0, v250
	v_fma_f32 v246, |v99|, v246, |v99|
	v_fma_f32 v253, |v101|, v253, |v101|
	v_cndmask_b32_e64 v100, v246, v243, s[2:3]
	v_cndmask_b32_e64 v102, v253, v250, s[14:15]
	v_mul_f32_e32 v103, 0x3f3504f3, v54
	v_mul_f32_e32 v105, 0x3f3504f3, v55
	v_fma_f32 v104, |v103|, s48, v233
	v_fma_f32 v106, |v105|, s48, v233
	v_fma_f32 v104, |v103|, v104, s49
	v_fma_f32 v106, |v105|, v106, s49
	v_fma_f32 v104, |v103|, v104, s50
	v_fma_f32 v106, |v105|, v106, s50
	v_fma_f32 v104, |v103|, v104, s51
	v_fma_f32 v106, |v105|, v106, s51
	v_fma_f32 v104, |v103|, v104, s52
	v_fma_f32 v106, |v105|, v106, s52
	v_fma_f32 v104, |v103|, v104, s53
	v_fma_f32 v106, |v105|, v106, s53
	v_fma_f32 v104, |v103|, v104, |v103|
	v_fma_f32 v106, |v105|, v106, |v105|
	v_mul_f32_e32 v243, 0xbfb8aa3b, v104
	v_mul_f32_e32 v250, 0xbfb8aa3b, v106
	v_fma_f32 v244, v104, s54, -v243
	v_fma_f32 v251, v106, s54, -v250
	v_rndne_f32_e32 v245, v243
	v_rndne_f32_e32 v252, v250
	v_fmac_f32_e32 v244, 0xb2a5705f, v104
	v_fmac_f32_e32 v251, 0xb2a5705f, v106
	v_sub_f32_e32 v243, v243, v245
	v_sub_f32_e32 v250, v250, v252
	v_add_f32_e32 v243, v243, v244
	v_add_f32_e32 v250, v250, v251
	v_cvt_i32_f32_e32 v244, v245
	v_cvt_i32_f32_e32 v251, v252
	v_exp_f32_e32 v243, v243
	v_exp_f32_e32 v250, v250
	v_mul_f32_e32 v246, v103, v103
	v_mul_f32_e32 v253, v105, v105
	v_ldexp_f32 v243, v243, v244
	v_ldexp_f32 v250, v250, v251
	v_cmp_nlt_f32_e64 s[2:3], s55, v104
	v_cmp_nlt_f32_e64 s[14:15], s55, v106
	v_fmamk_f32 v247, v246, 0xba1345e1, v222
	v_fmamk_f32 v254, v253, 0xba1345e1, v222
	v_fmaak_f32 v247, v246, v247, 0xbcdac9b8
	v_fmaak_f32 v254, v253, v254, 0xbcdac9b8
	v_cndmask_b32_e64 v243, 0, v243, s[2:3]
	v_cndmask_b32_e64 v250, 0, v250, s[14:15]
	v_cmp_ngt_f32_e64 s[2:3], s56, v104
	v_cmp_ngt_f32_e64 s[14:15], s56, v106
	v_fmaak_f32 v247, v246, v247, 0x3de703be
	v_fmaak_f32 v254, v253, v254, 0x3de703be
	v_fmaak_f32 v247, v246, v247, 0xbec09330
	v_fmaak_f32 v254, v253, v254, 0xbec09330
	v_cndmask_b32_e64 v243, v234, v243, s[2:3]
	v_cndmask_b32_e64 v250, v234, v250, s[14:15]
	v_fmaak_f32 v246, v246, v247, 0x3e0375d0
	v_fmaak_f32 v253, v253, v254, 0x3e0375d0
	v_cmp_nlt_f32_e64 s[2:3], |v103|, 1.0
	v_cmp_nlt_f32_e64 s[14:15], |v105|, 1.0
	v_sub_f32_e32 v243, 1.0, v243
	v_sub_f32_e32 v250, 1.0, v250
	v_fma_f32 v246, |v103|, v246, |v103|
	v_fma_f32 v253, |v105|, v253, |v105|
	v_cndmask_b32_e64 v104, v246, v243, s[2:3]
	v_cndmask_b32_e64 v106, v253, v250, s[14:15]
	v_mul_f32_e32 v107, 0x3f3504f3, v56
	v_mul_f32_e32 v109, 0x3f3504f3, v57
	v_fma_f32 v108, |v107|, s48, v233
	v_fma_f32 v110, |v109|, s48, v233
	v_fma_f32 v108, |v107|, v108, s49
	v_fma_f32 v110, |v109|, v110, s49
	v_fma_f32 v108, |v107|, v108, s50
	v_fma_f32 v110, |v109|, v110, s50
	v_fma_f32 v108, |v107|, v108, s51
	v_fma_f32 v110, |v109|, v110, s51
	v_fma_f32 v108, |v107|, v108, s52
	v_fma_f32 v110, |v109|, v110, s52
	v_fma_f32 v108, |v107|, v108, s53
	v_fma_f32 v110, |v109|, v110, s53
	v_fma_f32 v108, |v107|, v108, |v107|
	v_fma_f32 v110, |v109|, v110, |v109|
	v_mul_f32_e32 v243, 0xbfb8aa3b, v108
	v_mul_f32_e32 v250, 0xbfb8aa3b, v110
	v_fma_f32 v244, v108, s54, -v243
	v_fma_f32 v251, v110, s54, -v250
	v_rndne_f32_e32 v245, v243
	v_rndne_f32_e32 v252, v250
	v_fmac_f32_e32 v244, 0xb2a5705f, v108
	v_fmac_f32_e32 v251, 0xb2a5705f, v110
	v_sub_f32_e32 v243, v243, v245
	v_sub_f32_e32 v250, v250, v252
	v_add_f32_e32 v243, v243, v244
	v_add_f32_e32 v250, v250, v251
	v_cvt_i32_f32_e32 v244, v245
	v_cvt_i32_f32_e32 v251, v252
	v_exp_f32_e32 v243, v243
	v_exp_f32_e32 v250, v250
	v_mul_f32_e32 v246, v107, v107
	v_mul_f32_e32 v253, v109, v109
	v_ldexp_f32 v243, v243, v244
	v_ldexp_f32 v250, v250, v251
	v_cmp_nlt_f32_e64 s[2:3], s55, v108
	v_cmp_nlt_f32_e64 s[14:15], s55, v110
	v_fmamk_f32 v247, v246, 0xba1345e1, v222
	v_fmamk_f32 v254, v253, 0xba1345e1, v222
	v_fmaak_f32 v247, v246, v247, 0xbcdac9b8
	v_fmaak_f32 v254, v253, v254, 0xbcdac9b8
	v_cndmask_b32_e64 v243, 0, v243, s[2:3]
	v_cndmask_b32_e64 v250, 0, v250, s[14:15]
	v_cmp_ngt_f32_e64 s[2:3], s56, v108
	v_cmp_ngt_f32_e64 s[14:15], s56, v110
	v_fmaak_f32 v247, v246, v247, 0x3de703be
	v_fmaak_f32 v254, v253, v254, 0x3de703be
	v_fmaak_f32 v247, v246, v247, 0xbec09330
	v_fmaak_f32 v254, v253, v254, 0xbec09330
	v_cndmask_b32_e64 v243, v234, v243, s[2:3]
	v_cndmask_b32_e64 v250, v234, v250, s[14:15]
	v_fmaak_f32 v246, v246, v247, 0x3e0375d0
	v_fmaak_f32 v253, v253, v254, 0x3e0375d0
	v_cmp_nlt_f32_e64 s[2:3], |v107|, 1.0
	v_cmp_nlt_f32_e64 s[14:15], |v109|, 1.0
	v_sub_f32_e32 v243, 1.0, v243
	v_sub_f32_e32 v250, 1.0, v250
	v_fma_f32 v246, |v107|, v246, |v107|
	v_fma_f32 v253, |v109|, v253, |v109|
	v_cndmask_b32_e64 v108, v246, v243, s[2:3]
	v_cndmask_b32_e64 v110, v253, v250, s[14:15]
	v_mul_f32_e32 v111, 0x3f3504f3, v58
	v_mul_f32_e32 v113, 0x3f3504f3, v59
	v_fma_f32 v112, |v111|, s48, v233
	v_fma_f32 v116, |v113|, s48, v233
	v_fma_f32 v112, |v111|, v112, s49
	v_fma_f32 v116, |v113|, v116, s49
	v_fma_f32 v112, |v111|, v112, s50
	v_fma_f32 v116, |v113|, v116, s50
	v_fma_f32 v112, |v111|, v112, s51
	v_fma_f32 v116, |v113|, v116, s51
	v_fma_f32 v112, |v111|, v112, s52
	v_fma_f32 v116, |v113|, v116, s52
	v_fma_f32 v112, |v111|, v112, s53
	v_fma_f32 v116, |v113|, v116, s53
	v_fma_f32 v112, |v111|, v112, |v111|
	v_fma_f32 v116, |v113|, v116, |v113|
	v_mul_f32_e32 v243, 0xbfb8aa3b, v112
	v_mul_f32_e32 v250, 0xbfb8aa3b, v116
	v_fma_f32 v244, v112, s54, -v243
	v_fma_f32 v251, v116, s54, -v250
	v_rndne_f32_e32 v245, v243
	v_rndne_f32_e32 v252, v250
	v_fmac_f32_e32 v244, 0xb2a5705f, v112
	v_fmac_f32_e32 v251, 0xb2a5705f, v116
	v_sub_f32_e32 v243, v243, v245
	v_sub_f32_e32 v250, v250, v252
	v_add_f32_e32 v243, v243, v244
	v_add_f32_e32 v250, v250, v251
	v_cvt_i32_f32_e32 v244, v245
	v_cvt_i32_f32_e32 v251, v252
	v_exp_f32_e32 v243, v243
	v_exp_f32_e32 v250, v250
	v_mul_f32_e32 v246, v111, v111
	v_mul_f32_e32 v253, v113, v113
	v_ldexp_f32 v243, v243, v244
	v_ldexp_f32 v250, v250, v251
	v_cmp_nlt_f32_e64 s[2:3], s55, v112
	v_cmp_nlt_f32_e64 s[14:15], s55, v116
	v_fmamk_f32 v247, v246, 0xba1345e1, v222
	v_fmamk_f32 v254, v253, 0xba1345e1, v222
	v_fmaak_f32 v247, v246, v247, 0xbcdac9b8
	v_fmaak_f32 v254, v253, v254, 0xbcdac9b8
	v_cndmask_b32_e64 v243, 0, v243, s[2:3]
	v_cndmask_b32_e64 v250, 0, v250, s[14:15]
	v_cmp_ngt_f32_e64 s[2:3], s56, v112
	v_cmp_ngt_f32_e64 s[14:15], s56, v116
	v_fmaak_f32 v247, v246, v247, 0x3de703be
	v_fmaak_f32 v254, v253, v254, 0x3de703be
	v_fmaak_f32 v247, v246, v247, 0xbec09330
	v_fmaak_f32 v254, v253, v254, 0xbec09330
	v_cndmask_b32_e64 v243, v234, v243, s[2:3]
	v_cndmask_b32_e64 v250, v234, v250, s[14:15]
	v_fmaak_f32 v246, v246, v247, 0x3e0375d0
	v_fmaak_f32 v253, v253, v254, 0x3e0375d0
	v_cmp_nlt_f32_e64 s[2:3], |v111|, 1.0
	v_cmp_nlt_f32_e64 s[14:15], |v113|, 1.0
	v_sub_f32_e32 v243, 1.0, v243
	v_sub_f32_e32 v250, 1.0, v250
	v_fma_f32 v246, |v111|, v246, |v111|
	v_fma_f32 v253, |v113|, v253, |v113|
	v_cndmask_b32_e64 v112, v246, v243, s[2:3]
	v_cndmask_b32_e64 v116, v253, v250, s[14:15]
	v_mul_f32_e32 v117, 0x3f3504f3, v60
	v_mul_f32_e32 v119, 0x3f3504f3, v61
	v_fma_f32 v118, |v117|, s48, v233
	v_fma_f32 v120, |v119|, s48, v233
	v_fma_f32 v118, |v117|, v118, s49
	v_fma_f32 v120, |v119|, v120, s49
	v_fma_f32 v118, |v117|, v118, s50
	v_fma_f32 v120, |v119|, v120, s50
	v_fma_f32 v118, |v117|, v118, s51
	v_fma_f32 v120, |v119|, v120, s51
	v_fma_f32 v118, |v117|, v118, s52
	v_fma_f32 v120, |v119|, v120, s52
	v_fma_f32 v118, |v117|, v118, s53
	v_fma_f32 v120, |v119|, v120, s53
	v_fma_f32 v118, |v117|, v118, |v117|
	v_fma_f32 v120, |v119|, v120, |v119|
	v_mul_f32_e32 v243, 0xbfb8aa3b, v118
	v_mul_f32_e32 v250, 0xbfb8aa3b, v120
	v_fma_f32 v244, v118, s54, -v243
	v_fma_f32 v251, v120, s54, -v250
	v_rndne_f32_e32 v245, v243
	v_rndne_f32_e32 v252, v250
	v_fmac_f32_e32 v244, 0xb2a5705f, v118
	v_fmac_f32_e32 v251, 0xb2a5705f, v120
	v_sub_f32_e32 v243, v243, v245
	v_sub_f32_e32 v250, v250, v252
	v_add_f32_e32 v243, v243, v244
	v_add_f32_e32 v250, v250, v251
	v_cvt_i32_f32_e32 v244, v245
	v_cvt_i32_f32_e32 v251, v252
	v_exp_f32_e32 v243, v243
	v_exp_f32_e32 v250, v250
	v_mul_f32_e32 v246, v117, v117
	v_mul_f32_e32 v253, v119, v119
	v_ldexp_f32 v243, v243, v244
	v_ldexp_f32 v250, v250, v251
	v_cmp_nlt_f32_e64 s[2:3], s55, v118
	v_cmp_nlt_f32_e64 s[14:15], s55, v120
	v_fmamk_f32 v247, v246, 0xba1345e1, v222
	v_fmamk_f32 v254, v253, 0xba1345e1, v222
	v_fmaak_f32 v247, v246, v247, 0xbcdac9b8
	v_fmaak_f32 v254, v253, v254, 0xbcdac9b8
	v_cndmask_b32_e64 v243, 0, v243, s[2:3]
	v_cndmask_b32_e64 v250, 0, v250, s[14:15]
	v_cmp_ngt_f32_e64 s[2:3], s56, v118
	v_cmp_ngt_f32_e64 s[14:15], s56, v120
	v_fmaak_f32 v247, v246, v247, 0x3de703be
	v_fmaak_f32 v254, v253, v254, 0x3de703be
	v_fmaak_f32 v247, v246, v247, 0xbec09330
	v_fmaak_f32 v254, v253, v254, 0xbec09330
	v_cndmask_b32_e64 v243, v234, v243, s[2:3]
	v_cndmask_b32_e64 v250, v234, v250, s[14:15]
	v_fmaak_f32 v246, v246, v247, 0x3e0375d0
	v_fmaak_f32 v253, v253, v254, 0x3e0375d0
	v_cmp_nlt_f32_e64 s[2:3], |v117|, 1.0
	v_cmp_nlt_f32_e64 s[14:15], |v119|, 1.0
	v_sub_f32_e32 v243, 1.0, v243
	v_sub_f32_e32 v250, 1.0, v250
	v_fma_f32 v246, |v117|, v246, |v117|
	v_fma_f32 v253, |v119|, v253, |v119|
	v_cndmask_b32_e64 v118, v246, v243, s[2:3]
	v_cndmask_b32_e64 v120, v253, v250, s[14:15]
	v_mul_f32_e32 v121, 0x3f3504f3, v62
	v_mul_f32_e32 v123, 0x3f3504f3, v63
	v_fma_f32 v122, |v121|, s48, v233
	v_fma_f32 v124, |v123|, s48, v233
	v_fma_f32 v122, |v121|, v122, s49
	v_fma_f32 v124, |v123|, v124, s49
	v_fma_f32 v122, |v121|, v122, s50
	v_fma_f32 v124, |v123|, v124, s50
	v_fma_f32 v122, |v121|, v122, s51
	v_fma_f32 v124, |v123|, v124, s51
	v_fma_f32 v122, |v121|, v122, s52
	v_fma_f32 v124, |v123|, v124, s52
	v_fma_f32 v122, |v121|, v122, s53
	v_fma_f32 v124, |v123|, v124, s53
	v_fma_f32 v122, |v121|, v122, |v121|
	v_fma_f32 v124, |v123|, v124, |v123|
	v_mul_f32_e32 v243, 0xbfb8aa3b, v122
	v_mul_f32_e32 v250, 0xbfb8aa3b, v124
	v_fma_f32 v244, v122, s54, -v243
	v_fma_f32 v251, v124, s54, -v250
	v_rndne_f32_e32 v245, v243
	v_rndne_f32_e32 v252, v250
	v_fmac_f32_e32 v244, 0xb2a5705f, v122
	v_fmac_f32_e32 v251, 0xb2a5705f, v124
	v_sub_f32_e32 v243, v243, v245
	v_sub_f32_e32 v250, v250, v252
	v_add_f32_e32 v243, v243, v244
	v_add_f32_e32 v250, v250, v251
	v_cvt_i32_f32_e32 v244, v245
	v_cvt_i32_f32_e32 v251, v252
	v_exp_f32_e32 v243, v243
	v_exp_f32_e32 v250, v250
	v_mul_f32_e32 v246, v121, v121
	v_mul_f32_e32 v253, v123, v123
	v_ldexp_f32 v243, v243, v244
	v_ldexp_f32 v250, v250, v251
	v_cmp_nlt_f32_e64 s[2:3], s55, v122
	v_cmp_nlt_f32_e64 s[14:15], s55, v124
	v_fmamk_f32 v247, v246, 0xba1345e1, v222
	v_fmamk_f32 v254, v253, 0xba1345e1, v222
	v_fmaak_f32 v247, v246, v247, 0xbcdac9b8
	v_fmaak_f32 v254, v253, v254, 0xbcdac9b8
	v_cndmask_b32_e64 v243, 0, v243, s[2:3]
	v_cndmask_b32_e64 v250, 0, v250, s[14:15]
	v_cmp_ngt_f32_e64 s[2:3], s56, v122
	v_cmp_ngt_f32_e64 s[14:15], s56, v124
	v_fmaak_f32 v247, v246, v247, 0x3de703be
	v_fmaak_f32 v254, v253, v254, 0x3de703be
	v_fmaak_f32 v247, v246, v247, 0xbec09330
	v_fmaak_f32 v254, v253, v254, 0xbec09330
	v_cndmask_b32_e64 v243, v234, v243, s[2:3]
	v_cndmask_b32_e64 v250, v234, v250, s[14:15]
	v_fmaak_f32 v246, v246, v247, 0x3e0375d0
	v_fmaak_f32 v253, v253, v254, 0x3e0375d0
	v_cmp_nlt_f32_e64 s[2:3], |v121|, 1.0
	v_cmp_nlt_f32_e64 s[14:15], |v123|, 1.0
	v_sub_f32_e32 v243, 1.0, v243
	v_sub_f32_e32 v250, 1.0, v250
	v_fma_f32 v246, |v121|, v246, |v121|
	v_fma_f32 v253, |v123|, v253, |v123|
	v_cndmask_b32_e64 v122, v246, v243, s[2:3]
	v_cndmask_b32_e64 v124, v253, v250, s[14:15]
	v_mul_f32_e32 v125, 0x3f3504f3, v32
	v_mul_f32_e32 v127, 0x3f3504f3, v33
	v_fma_f32 v126, |v125|, s48, v233
	v_fma_f32 v128, |v127|, s48, v233
	v_fma_f32 v126, |v125|, v126, s49
	v_fma_f32 v128, |v127|, v128, s49
	v_fma_f32 v126, |v125|, v126, s50
	v_fma_f32 v128, |v127|, v128, s50
	v_fma_f32 v126, |v125|, v126, s51
	v_fma_f32 v128, |v127|, v128, s51
	v_fma_f32 v126, |v125|, v126, s52
	v_fma_f32 v128, |v127|, v128, s52
	v_fma_f32 v126, |v125|, v126, s53
	v_fma_f32 v128, |v127|, v128, s53
	v_fma_f32 v126, |v125|, v126, |v125|
	v_fma_f32 v128, |v127|, v128, |v127|
	v_mul_f32_e32 v243, 0xbfb8aa3b, v126
	v_mul_f32_e32 v250, 0xbfb8aa3b, v128
	v_fma_f32 v244, v126, s54, -v243
	v_fma_f32 v251, v128, s54, -v250
	v_rndne_f32_e32 v245, v243
	v_rndne_f32_e32 v252, v250
	v_fmac_f32_e32 v244, 0xb2a5705f, v126
	v_fmac_f32_e32 v251, 0xb2a5705f, v128
	v_sub_f32_e32 v243, v243, v245
	v_sub_f32_e32 v250, v250, v252
	v_add_f32_e32 v243, v243, v244
	v_add_f32_e32 v250, v250, v251
	v_cvt_i32_f32_e32 v244, v245
	v_cvt_i32_f32_e32 v251, v252
	v_exp_f32_e32 v243, v243
	v_exp_f32_e32 v250, v250
	v_mul_f32_e32 v246, v125, v125
	v_mul_f32_e32 v253, v127, v127
	v_ldexp_f32 v243, v243, v244
	v_ldexp_f32 v250, v250, v251
	v_cmp_nlt_f32_e64 s[2:3], s55, v126
	v_cmp_nlt_f32_e64 s[14:15], s55, v128
	v_fmamk_f32 v247, v246, 0xba1345e1, v222
	v_fmamk_f32 v254, v253, 0xba1345e1, v222
	v_fmaak_f32 v247, v246, v247, 0xbcdac9b8
	v_fmaak_f32 v254, v253, v254, 0xbcdac9b8
	v_cndmask_b32_e64 v243, 0, v243, s[2:3]
	v_cndmask_b32_e64 v250, 0, v250, s[14:15]
	v_cmp_ngt_f32_e64 s[2:3], s56, v126
	v_cmp_ngt_f32_e64 s[14:15], s56, v128
	v_fmaak_f32 v247, v246, v247, 0x3de703be
	v_fmaak_f32 v254, v253, v254, 0x3de703be
	v_fmaak_f32 v247, v246, v247, 0xbec09330
	v_fmaak_f32 v254, v253, v254, 0xbec09330
	v_cndmask_b32_e64 v243, v234, v243, s[2:3]
	v_cndmask_b32_e64 v250, v234, v250, s[14:15]
	v_fmaak_f32 v246, v246, v247, 0x3e0375d0
	v_fmaak_f32 v253, v253, v254, 0x3e0375d0
	v_cmp_nlt_f32_e64 s[2:3], |v125|, 1.0
	v_cmp_nlt_f32_e64 s[14:15], |v127|, 1.0
	v_sub_f32_e32 v243, 1.0, v243
	v_sub_f32_e32 v250, 1.0, v250
	v_fma_f32 v246, |v125|, v246, |v125|
	v_fma_f32 v253, |v127|, v253, |v127|
	v_cndmask_b32_e64 v126, v246, v243, s[2:3]
	v_cndmask_b32_e64 v128, v253, v250, s[14:15]
	v_mul_f32_e32 v129, 0x3f3504f3, v34
	v_mul_f32_e32 v131, 0x3f3504f3, v35
	v_fma_f32 v130, |v129|, s48, v233
	v_fma_f32 v132, |v131|, s48, v233
	v_fma_f32 v130, |v129|, v130, s49
	v_fma_f32 v132, |v131|, v132, s49
	v_fma_f32 v130, |v129|, v130, s50
	v_fma_f32 v132, |v131|, v132, s50
	v_fma_f32 v130, |v129|, v130, s51
	v_fma_f32 v132, |v131|, v132, s51
	v_fma_f32 v130, |v129|, v130, s52
	v_fma_f32 v132, |v131|, v132, s52
	v_fma_f32 v130, |v129|, v130, s53
	v_fma_f32 v132, |v131|, v132, s53
	v_fma_f32 v130, |v129|, v130, |v129|
	v_fma_f32 v132, |v131|, v132, |v131|
	v_mul_f32_e32 v243, 0xbfb8aa3b, v130
	v_mul_f32_e32 v250, 0xbfb8aa3b, v132
	v_fma_f32 v244, v130, s54, -v243
	v_fma_f32 v251, v132, s54, -v250
	v_rndne_f32_e32 v245, v243
	v_rndne_f32_e32 v252, v250
	v_fmac_f32_e32 v244, 0xb2a5705f, v130
	v_fmac_f32_e32 v251, 0xb2a5705f, v132
	v_sub_f32_e32 v243, v243, v245
	v_sub_f32_e32 v250, v250, v252
	v_add_f32_e32 v243, v243, v244
	v_add_f32_e32 v250, v250, v251
	v_cvt_i32_f32_e32 v244, v245
	v_cvt_i32_f32_e32 v251, v252
	v_exp_f32_e32 v243, v243
	v_exp_f32_e32 v250, v250
	v_mul_f32_e32 v246, v129, v129
	v_mul_f32_e32 v253, v131, v131
	v_ldexp_f32 v243, v243, v244
	v_ldexp_f32 v250, v250, v251
	v_cmp_nlt_f32_e64 s[2:3], s55, v130
	v_cmp_nlt_f32_e64 s[14:15], s55, v132
	v_fmamk_f32 v247, v246, 0xba1345e1, v222
	v_fmamk_f32 v254, v253, 0xba1345e1, v222
	v_fmaak_f32 v247, v246, v247, 0xbcdac9b8
	v_fmaak_f32 v254, v253, v254, 0xbcdac9b8
	v_cndmask_b32_e64 v243, 0, v243, s[2:3]
	v_cndmask_b32_e64 v250, 0, v250, s[14:15]
	v_cmp_ngt_f32_e64 s[2:3], s56, v130
	v_cmp_ngt_f32_e64 s[14:15], s56, v132
	v_fmaak_f32 v247, v246, v247, 0x3de703be
	v_fmaak_f32 v254, v253, v254, 0x3de703be
	v_fmaak_f32 v247, v246, v247, 0xbec09330
	v_fmaak_f32 v254, v253, v254, 0xbec09330
	v_cndmask_b32_e64 v243, v234, v243, s[2:3]
	v_cndmask_b32_e64 v250, v234, v250, s[14:15]
	v_fmaak_f32 v246, v246, v247, 0x3e0375d0
	v_fmaak_f32 v253, v253, v254, 0x3e0375d0
	v_cmp_nlt_f32_e64 s[2:3], |v129|, 1.0
	v_cmp_nlt_f32_e64 s[14:15], |v131|, 1.0
	v_sub_f32_e32 v243, 1.0, v243
	v_sub_f32_e32 v250, 1.0, v250
	v_fma_f32 v246, |v129|, v246, |v129|
	v_fma_f32 v253, |v131|, v253, |v131|
	v_cndmask_b32_e64 v130, v246, v243, s[2:3]
	v_cndmask_b32_e64 v132, v253, v250, s[14:15]
	v_mul_f32_e32 v133, 0x3f3504f3, v36
	v_mul_f32_e32 v135, 0x3f3504f3, v37
	v_fma_f32 v134, |v133|, s48, v233
	v_fma_f32 v136, |v135|, s48, v233
	v_fma_f32 v134, |v133|, v134, s49
	v_fma_f32 v136, |v135|, v136, s49
	v_fma_f32 v134, |v133|, v134, s50
	v_fma_f32 v136, |v135|, v136, s50
	v_fma_f32 v134, |v133|, v134, s51
	v_fma_f32 v136, |v135|, v136, s51
	v_fma_f32 v134, |v133|, v134, s52
	v_fma_f32 v136, |v135|, v136, s52
	v_fma_f32 v134, |v133|, v134, s53
	v_fma_f32 v136, |v135|, v136, s53
	v_fma_f32 v134, |v133|, v134, |v133|
	v_fma_f32 v136, |v135|, v136, |v135|
	v_mul_f32_e32 v243, 0xbfb8aa3b, v134
	v_mul_f32_e32 v250, 0xbfb8aa3b, v136
	v_fma_f32 v244, v134, s54, -v243
	v_fma_f32 v251, v136, s54, -v250
	v_rndne_f32_e32 v245, v243
	v_rndne_f32_e32 v252, v250
	v_fmac_f32_e32 v244, 0xb2a5705f, v134
	v_fmac_f32_e32 v251, 0xb2a5705f, v136
	v_sub_f32_e32 v243, v243, v245
	v_sub_f32_e32 v250, v250, v252
	v_add_f32_e32 v243, v243, v244
	v_add_f32_e32 v250, v250, v251
	v_cvt_i32_f32_e32 v244, v245
	v_cvt_i32_f32_e32 v251, v252
	v_exp_f32_e32 v243, v243
	v_exp_f32_e32 v250, v250
	v_mul_f32_e32 v246, v133, v133
	v_mul_f32_e32 v253, v135, v135
	v_ldexp_f32 v243, v243, v244
	v_ldexp_f32 v250, v250, v251
	v_cmp_nlt_f32_e64 s[2:3], s55, v134
	v_cmp_nlt_f32_e64 s[14:15], s55, v136
	v_fmamk_f32 v247, v246, 0xba1345e1, v222
	v_fmamk_f32 v254, v253, 0xba1345e1, v222
	v_fmaak_f32 v247, v246, v247, 0xbcdac9b8
	v_fmaak_f32 v254, v253, v254, 0xbcdac9b8
	v_cndmask_b32_e64 v243, 0, v243, s[2:3]
	v_cndmask_b32_e64 v250, 0, v250, s[14:15]
	v_cmp_ngt_f32_e64 s[2:3], s56, v134
	v_cmp_ngt_f32_e64 s[14:15], s56, v136
	v_fmaak_f32 v247, v246, v247, 0x3de703be
	v_fmaak_f32 v254, v253, v254, 0x3de703be
	v_fmaak_f32 v247, v246, v247, 0xbec09330
	v_fmaak_f32 v254, v253, v254, 0xbec09330
	v_cndmask_b32_e64 v243, v234, v243, s[2:3]
	v_cndmask_b32_e64 v250, v234, v250, s[14:15]
	v_fmaak_f32 v246, v246, v247, 0x3e0375d0
	v_fmaak_f32 v253, v253, v254, 0x3e0375d0
	v_cmp_nlt_f32_e64 s[2:3], |v133|, 1.0
	v_cmp_nlt_f32_e64 s[14:15], |v135|, 1.0
	v_sub_f32_e32 v243, 1.0, v243
	v_sub_f32_e32 v250, 1.0, v250
	v_fma_f32 v246, |v133|, v246, |v133|
	v_fma_f32 v253, |v135|, v253, |v135|
	v_cndmask_b32_e64 v134, v246, v243, s[2:3]
	v_cndmask_b32_e64 v136, v253, v250, s[14:15]
	v_mul_f32_e32 v137, 0x3f3504f3, v38
	v_mul_f32_e32 v139, 0x3f3504f3, v39
	v_fma_f32 v138, |v137|, s48, v233
	v_fma_f32 v140, |v139|, s48, v233
	v_fma_f32 v138, |v137|, v138, s49
	v_fma_f32 v140, |v139|, v140, s49
	v_fma_f32 v138, |v137|, v138, s50
	v_fma_f32 v140, |v139|, v140, s50
	v_fma_f32 v138, |v137|, v138, s51
	v_fma_f32 v140, |v139|, v140, s51
	v_fma_f32 v138, |v137|, v138, s52
	v_fma_f32 v140, |v139|, v140, s52
	v_fma_f32 v138, |v137|, v138, s53
	v_fma_f32 v140, |v139|, v140, s53
	v_fma_f32 v138, |v137|, v138, |v137|
	v_fma_f32 v140, |v139|, v140, |v139|
	v_mul_f32_e32 v243, 0xbfb8aa3b, v138
	v_mul_f32_e32 v250, 0xbfb8aa3b, v140
	v_fma_f32 v244, v138, s54, -v243
	v_fma_f32 v251, v140, s54, -v250
	v_rndne_f32_e32 v245, v243
	v_rndne_f32_e32 v252, v250
	v_fmac_f32_e32 v244, 0xb2a5705f, v138
	v_fmac_f32_e32 v251, 0xb2a5705f, v140
	v_sub_f32_e32 v243, v243, v245
	v_sub_f32_e32 v250, v250, v252
	v_add_f32_e32 v243, v243, v244
	v_add_f32_e32 v250, v250, v251
	v_cvt_i32_f32_e32 v244, v245
	v_cvt_i32_f32_e32 v251, v252
	v_exp_f32_e32 v243, v243
	v_exp_f32_e32 v250, v250
	v_mul_f32_e32 v246, v137, v137
	v_mul_f32_e32 v253, v139, v139
	v_ldexp_f32 v243, v243, v244
	v_ldexp_f32 v250, v250, v251
	v_cmp_nlt_f32_e64 s[2:3], s55, v138
	v_cmp_nlt_f32_e64 s[14:15], s55, v140
	v_fmamk_f32 v247, v246, 0xba1345e1, v222
	v_fmamk_f32 v254, v253, 0xba1345e1, v222
	v_fmaak_f32 v247, v246, v247, 0xbcdac9b8
	v_fmaak_f32 v254, v253, v254, 0xbcdac9b8
	v_cndmask_b32_e64 v243, 0, v243, s[2:3]
	v_cndmask_b32_e64 v250, 0, v250, s[14:15]
	v_cmp_ngt_f32_e64 s[2:3], s56, v138
	v_cmp_ngt_f32_e64 s[14:15], s56, v140
	v_fmaak_f32 v247, v246, v247, 0x3de703be
	v_fmaak_f32 v254, v253, v254, 0x3de703be
	v_fmaak_f32 v247, v246, v247, 0xbec09330
	v_fmaak_f32 v254, v253, v254, 0xbec09330
	v_cndmask_b32_e64 v243, v234, v243, s[2:3]
	v_cndmask_b32_e64 v250, v234, v250, s[14:15]
	v_fmaak_f32 v246, v246, v247, 0x3e0375d0
	v_fmaak_f32 v253, v253, v254, 0x3e0375d0
	v_cmp_nlt_f32_e64 s[2:3], |v137|, 1.0
	v_cmp_nlt_f32_e64 s[14:15], |v139|, 1.0
	v_sub_f32_e32 v243, 1.0, v243
	v_sub_f32_e32 v250, 1.0, v250
	v_fma_f32 v246, |v137|, v246, |v137|
	v_fma_f32 v253, |v139|, v253, |v139|
	v_cndmask_b32_e64 v138, v246, v243, s[2:3]
	v_cndmask_b32_e64 v140, v253, v250, s[14:15]
	v_mul_f32_e32 v141, 0x3f3504f3, v40
	v_mul_f32_e32 v143, 0x3f3504f3, v41
	v_fma_f32 v142, |v141|, s48, v233
	v_fma_f32 v144, |v143|, s48, v233
	v_fma_f32 v142, |v141|, v142, s49
	v_fma_f32 v144, |v143|, v144, s49
	v_fma_f32 v142, |v141|, v142, s50
	v_fma_f32 v144, |v143|, v144, s50
	v_fma_f32 v142, |v141|, v142, s51
	v_fma_f32 v144, |v143|, v144, s51
	v_fma_f32 v142, |v141|, v142, s52
	v_fma_f32 v144, |v143|, v144, s52
	v_fma_f32 v142, |v141|, v142, s53
	v_fma_f32 v144, |v143|, v144, s53
	v_fma_f32 v142, |v141|, v142, |v141|
	v_fma_f32 v144, |v143|, v144, |v143|
	v_mul_f32_e32 v243, 0xbfb8aa3b, v142
	v_mul_f32_e32 v250, 0xbfb8aa3b, v144
	v_fma_f32 v244, v142, s54, -v243
	v_fma_f32 v251, v144, s54, -v250
	v_rndne_f32_e32 v245, v243
	v_rndne_f32_e32 v252, v250
	v_fmac_f32_e32 v244, 0xb2a5705f, v142
	v_fmac_f32_e32 v251, 0xb2a5705f, v144
	v_sub_f32_e32 v243, v243, v245
	v_sub_f32_e32 v250, v250, v252
	v_add_f32_e32 v243, v243, v244
	v_add_f32_e32 v250, v250, v251
	v_cvt_i32_f32_e32 v244, v245
	v_cvt_i32_f32_e32 v251, v252
	v_exp_f32_e32 v243, v243
	v_exp_f32_e32 v250, v250
	v_mul_f32_e32 v246, v141, v141
	v_mul_f32_e32 v253, v143, v143
	v_ldexp_f32 v243, v243, v244
	v_ldexp_f32 v250, v250, v251
	v_cmp_nlt_f32_e64 s[2:3], s55, v142
	v_cmp_nlt_f32_e64 s[14:15], s55, v144
	v_fmamk_f32 v247, v246, 0xba1345e1, v222
	v_fmamk_f32 v254, v253, 0xba1345e1, v222
	v_fmaak_f32 v247, v246, v247, 0xbcdac9b8
	v_fmaak_f32 v254, v253, v254, 0xbcdac9b8
	v_cndmask_b32_e64 v243, 0, v243, s[2:3]
	v_cndmask_b32_e64 v250, 0, v250, s[14:15]
	v_cmp_ngt_f32_e64 s[2:3], s56, v142
	v_cmp_ngt_f32_e64 s[14:15], s56, v144
	v_fmaak_f32 v247, v246, v247, 0x3de703be
	v_fmaak_f32 v254, v253, v254, 0x3de703be
	v_fmaak_f32 v247, v246, v247, 0xbec09330
	v_fmaak_f32 v254, v253, v254, 0xbec09330
	v_cndmask_b32_e64 v243, v234, v243, s[2:3]
	v_cndmask_b32_e64 v250, v234, v250, s[14:15]
	v_fmaak_f32 v246, v246, v247, 0x3e0375d0
	v_fmaak_f32 v253, v253, v254, 0x3e0375d0
	v_cmp_nlt_f32_e64 s[2:3], |v141|, 1.0
	v_cmp_nlt_f32_e64 s[14:15], |v143|, 1.0
	v_sub_f32_e32 v243, 1.0, v243
	v_sub_f32_e32 v250, 1.0, v250
	v_fma_f32 v246, |v141|, v246, |v141|
	v_fma_f32 v253, |v143|, v253, |v143|
	v_cndmask_b32_e64 v142, v246, v243, s[2:3]
	v_cndmask_b32_e64 v144, v253, v250, s[14:15]
	v_mul_f32_e32 v145, 0x3f3504f3, v42
	v_mul_f32_e32 v147, 0x3f3504f3, v43
	v_fma_f32 v146, |v145|, s48, v233
	v_fma_f32 v148, |v147|, s48, v233
	v_fma_f32 v146, |v145|, v146, s49
	v_fma_f32 v148, |v147|, v148, s49
	v_fma_f32 v146, |v145|, v146, s50
	v_fma_f32 v148, |v147|, v148, s50
	v_fma_f32 v146, |v145|, v146, s51
	v_fma_f32 v148, |v147|, v148, s51
	v_fma_f32 v146, |v145|, v146, s52
	v_fma_f32 v148, |v147|, v148, s52
	v_fma_f32 v146, |v145|, v146, s53
	v_fma_f32 v148, |v147|, v148, s53
	v_fma_f32 v146, |v145|, v146, |v145|
	v_fma_f32 v148, |v147|, v148, |v147|
	v_mul_f32_e32 v243, 0xbfb8aa3b, v146
	v_mul_f32_e32 v250, 0xbfb8aa3b, v148
	v_fma_f32 v244, v146, s54, -v243
	v_fma_f32 v251, v148, s54, -v250
	v_rndne_f32_e32 v245, v243
	v_rndne_f32_e32 v252, v250
	v_fmac_f32_e32 v244, 0xb2a5705f, v146
	v_fmac_f32_e32 v251, 0xb2a5705f, v148
	v_sub_f32_e32 v243, v243, v245
	v_sub_f32_e32 v250, v250, v252
	v_add_f32_e32 v243, v243, v244
	v_add_f32_e32 v250, v250, v251
	v_cvt_i32_f32_e32 v244, v245
	v_cvt_i32_f32_e32 v251, v252
	v_exp_f32_e32 v243, v243
	v_exp_f32_e32 v250, v250
	v_mul_f32_e32 v246, v145, v145
	v_mul_f32_e32 v253, v147, v147
	v_ldexp_f32 v243, v243, v244
	v_ldexp_f32 v250, v250, v251
	v_cmp_nlt_f32_e64 s[2:3], s55, v146
	v_cmp_nlt_f32_e64 s[14:15], s55, v148
	v_fmamk_f32 v247, v246, 0xba1345e1, v222
	v_fmamk_f32 v254, v253, 0xba1345e1, v222
	v_fmaak_f32 v247, v246, v247, 0xbcdac9b8
	v_fmaak_f32 v254, v253, v254, 0xbcdac9b8
	v_cndmask_b32_e64 v243, 0, v243, s[2:3]
	v_cndmask_b32_e64 v250, 0, v250, s[14:15]
	v_cmp_ngt_f32_e64 s[2:3], s56, v146
	v_cmp_ngt_f32_e64 s[14:15], s56, v148
	v_fmaak_f32 v247, v246, v247, 0x3de703be
	v_fmaak_f32 v254, v253, v254, 0x3de703be
	v_fmaak_f32 v247, v246, v247, 0xbec09330
	v_fmaak_f32 v254, v253, v254, 0xbec09330
	v_cndmask_b32_e64 v243, v234, v243, s[2:3]
	v_cndmask_b32_e64 v250, v234, v250, s[14:15]
	v_fmaak_f32 v246, v246, v247, 0x3e0375d0
	v_fmaak_f32 v253, v253, v254, 0x3e0375d0
	v_cmp_nlt_f32_e64 s[2:3], |v145|, 1.0
	v_cmp_nlt_f32_e64 s[14:15], |v147|, 1.0
	v_sub_f32_e32 v243, 1.0, v243
	v_sub_f32_e32 v250, 1.0, v250
	v_fma_f32 v246, |v145|, v246, |v145|
	v_fma_f32 v253, |v147|, v253, |v147|
	v_cndmask_b32_e64 v146, v246, v243, s[2:3]
	v_cndmask_b32_e64 v148, v253, v250, s[14:15]
	v_mul_f32_e32 v149, 0x3f3504f3, v44
	v_mul_f32_e32 v151, 0x3f3504f3, v45
	v_fma_f32 v150, |v149|, s48, v233
	v_fma_f32 v152, |v151|, s48, v233
	v_fma_f32 v150, |v149|, v150, s49
	v_fma_f32 v152, |v151|, v152, s49
	v_fma_f32 v150, |v149|, v150, s50
	v_fma_f32 v152, |v151|, v152, s50
	v_fma_f32 v150, |v149|, v150, s51
	v_fma_f32 v152, |v151|, v152, s51
	v_fma_f32 v150, |v149|, v150, s52
	v_fma_f32 v152, |v151|, v152, s52
	v_fma_f32 v150, |v149|, v150, s53
	v_fma_f32 v152, |v151|, v152, s53
	v_fma_f32 v150, |v149|, v150, |v149|
	v_fma_f32 v152, |v151|, v152, |v151|
	v_mul_f32_e32 v243, 0xbfb8aa3b, v150
	v_mul_f32_e32 v250, 0xbfb8aa3b, v152
	v_fma_f32 v244, v150, s54, -v243
	v_fma_f32 v251, v152, s54, -v250
	v_rndne_f32_e32 v245, v243
	v_rndne_f32_e32 v252, v250
	v_fmac_f32_e32 v244, 0xb2a5705f, v150
	v_fmac_f32_e32 v251, 0xb2a5705f, v152
	v_sub_f32_e32 v243, v243, v245
	v_sub_f32_e32 v250, v250, v252
	v_add_f32_e32 v243, v243, v244
	v_add_f32_e32 v250, v250, v251
	v_cvt_i32_f32_e32 v244, v245
	v_cvt_i32_f32_e32 v251, v252
	v_exp_f32_e32 v243, v243
	v_exp_f32_e32 v250, v250
	v_mul_f32_e32 v246, v149, v149
	v_mul_f32_e32 v253, v151, v151
	v_ldexp_f32 v243, v243, v244
	v_ldexp_f32 v250, v250, v251
	v_cmp_nlt_f32_e64 s[2:3], s55, v150
	v_cmp_nlt_f32_e64 s[14:15], s55, v152
	v_fmamk_f32 v247, v246, 0xba1345e1, v222
	v_fmamk_f32 v254, v253, 0xba1345e1, v222
	v_fmaak_f32 v247, v246, v247, 0xbcdac9b8
	v_fmaak_f32 v254, v253, v254, 0xbcdac9b8
	v_cndmask_b32_e64 v243, 0, v243, s[2:3]
	v_cndmask_b32_e64 v250, 0, v250, s[14:15]
	v_cmp_ngt_f32_e64 s[2:3], s56, v150
	v_cmp_ngt_f32_e64 s[14:15], s56, v152
	v_fmaak_f32 v247, v246, v247, 0x3de703be
	v_fmaak_f32 v254, v253, v254, 0x3de703be
	v_fmaak_f32 v247, v246, v247, 0xbec09330
	v_fmaak_f32 v254, v253, v254, 0xbec09330
	v_cndmask_b32_e64 v243, v234, v243, s[2:3]
	v_cndmask_b32_e64 v250, v234, v250, s[14:15]
	v_fmaak_f32 v246, v246, v247, 0x3e0375d0
	v_fmaak_f32 v253, v253, v254, 0x3e0375d0
	v_cmp_nlt_f32_e64 s[2:3], |v149|, 1.0
	v_cmp_nlt_f32_e64 s[14:15], |v151|, 1.0
	v_sub_f32_e32 v243, 1.0, v243
	v_sub_f32_e32 v250, 1.0, v250
	v_fma_f32 v246, |v149|, v246, |v149|
	v_fma_f32 v253, |v151|, v253, |v151|
	v_cndmask_b32_e64 v150, v246, v243, s[2:3]
	v_cndmask_b32_e64 v152, v253, v250, s[14:15]
	v_mul_f32_e32 v153, 0x3f3504f3, v46
	v_mul_f32_e32 v155, 0x3f3504f3, v47
	v_fma_f32 v154, |v153|, s48, v233
	v_fma_f32 v156, |v155|, s48, v233
	v_fma_f32 v154, |v153|, v154, s49
	v_fma_f32 v156, |v155|, v156, s49
	v_fma_f32 v154, |v153|, v154, s50
	v_fma_f32 v156, |v155|, v156, s50
	v_fma_f32 v154, |v153|, v154, s51
	v_fma_f32 v156, |v155|, v156, s51
	v_fma_f32 v154, |v153|, v154, s52
	v_fma_f32 v156, |v155|, v156, s52
	v_fma_f32 v154, |v153|, v154, s53
	v_fma_f32 v156, |v155|, v156, s53
	v_fma_f32 v154, |v153|, v154, |v153|
	v_fma_f32 v156, |v155|, v156, |v155|
	v_mul_f32_e32 v243, 0xbfb8aa3b, v154
	v_mul_f32_e32 v250, 0xbfb8aa3b, v156
	v_fma_f32 v244, v154, s54, -v243
	v_fma_f32 v251, v156, s54, -v250
	v_rndne_f32_e32 v245, v243
	v_rndne_f32_e32 v252, v250
	v_fmac_f32_e32 v244, 0xb2a5705f, v154
	v_fmac_f32_e32 v251, 0xb2a5705f, v156
	v_sub_f32_e32 v243, v243, v245
	v_sub_f32_e32 v250, v250, v252
	v_add_f32_e32 v243, v243, v244
	v_add_f32_e32 v250, v250, v251
	v_cvt_i32_f32_e32 v244, v245
	v_cvt_i32_f32_e32 v251, v252
	v_exp_f32_e32 v243, v243
	v_exp_f32_e32 v250, v250
	v_mul_f32_e32 v246, v153, v153
	v_mul_f32_e32 v253, v155, v155
	v_ldexp_f32 v243, v243, v244
	v_ldexp_f32 v250, v250, v251
	v_cmp_nlt_f32_e64 s[2:3], s55, v154
	v_cmp_nlt_f32_e64 s[14:15], s55, v156
	v_fmamk_f32 v247, v246, 0xba1345e1, v222
	v_fmamk_f32 v254, v253, 0xba1345e1, v222
	v_fmaak_f32 v247, v246, v247, 0xbcdac9b8
	v_fmaak_f32 v254, v253, v254, 0xbcdac9b8
	v_cndmask_b32_e64 v243, 0, v243, s[2:3]
	v_cndmask_b32_e64 v250, 0, v250, s[14:15]
	v_cmp_ngt_f32_e64 s[2:3], s56, v154
	v_cmp_ngt_f32_e64 s[14:15], s56, v156
	v_fmaak_f32 v247, v246, v247, 0x3de703be
	v_fmaak_f32 v254, v253, v254, 0x3de703be
	v_fmaak_f32 v247, v246, v247, 0xbec09330
	v_fmaak_f32 v254, v253, v254, 0xbec09330
	v_cndmask_b32_e64 v243, v234, v243, s[2:3]
	v_cndmask_b32_e64 v250, v234, v250, s[14:15]
	v_fmaak_f32 v246, v246, v247, 0x3e0375d0
	v_fmaak_f32 v253, v253, v254, 0x3e0375d0
	v_cmp_nlt_f32_e64 s[2:3], |v153|, 1.0
	v_cmp_nlt_f32_e64 s[14:15], |v155|, 1.0
	v_sub_f32_e32 v243, 1.0, v243
	v_sub_f32_e32 v250, 1.0, v250
	v_fma_f32 v246, |v153|, v246, |v153|
	v_fma_f32 v253, |v155|, v253, |v155|
	v_cndmask_b32_e64 v154, v246, v243, s[2:3]
	v_cndmask_b32_e64 v156, v253, v250, s[14:15]
	v_mul_f32_e32 v157, 0x3f3504f3, v16
	v_mul_f32_e32 v159, 0x3f3504f3, v17
	v_fma_f32 v158, |v157|, s48, v233
	v_fma_f32 v160, |v159|, s48, v233
	v_fma_f32 v158, |v157|, v158, s49
	v_fma_f32 v160, |v159|, v160, s49
	v_fma_f32 v158, |v157|, v158, s50
	v_fma_f32 v160, |v159|, v160, s50
	v_fma_f32 v158, |v157|, v158, s51
	v_fma_f32 v160, |v159|, v160, s51
	v_fma_f32 v158, |v157|, v158, s52
	v_fma_f32 v160, |v159|, v160, s52
	v_fma_f32 v158, |v157|, v158, s53
	v_fma_f32 v160, |v159|, v160, s53
	v_fma_f32 v158, |v157|, v158, |v157|
	v_fma_f32 v160, |v159|, v160, |v159|
	v_mul_f32_e32 v243, 0xbfb8aa3b, v158
	v_mul_f32_e32 v250, 0xbfb8aa3b, v160
	v_fma_f32 v244, v158, s54, -v243
	v_fma_f32 v251, v160, s54, -v250
	v_rndne_f32_e32 v245, v243
	v_rndne_f32_e32 v252, v250
	v_fmac_f32_e32 v244, 0xb2a5705f, v158
	v_fmac_f32_e32 v251, 0xb2a5705f, v160
	v_sub_f32_e32 v243, v243, v245
	v_sub_f32_e32 v250, v250, v252
	v_add_f32_e32 v243, v243, v244
	v_add_f32_e32 v250, v250, v251
	v_cvt_i32_f32_e32 v244, v245
	v_cvt_i32_f32_e32 v251, v252
	v_exp_f32_e32 v243, v243
	v_exp_f32_e32 v250, v250
	v_mul_f32_e32 v246, v157, v157
	v_mul_f32_e32 v253, v159, v159
	v_ldexp_f32 v243, v243, v244
	v_ldexp_f32 v250, v250, v251
	v_cmp_nlt_f32_e64 s[2:3], s55, v158
	v_cmp_nlt_f32_e64 s[14:15], s55, v160
	v_fmamk_f32 v247, v246, 0xba1345e1, v222
	v_fmamk_f32 v254, v253, 0xba1345e1, v222
	v_fmaak_f32 v247, v246, v247, 0xbcdac9b8
	v_fmaak_f32 v254, v253, v254, 0xbcdac9b8
	v_cndmask_b32_e64 v243, 0, v243, s[2:3]
	v_cndmask_b32_e64 v250, 0, v250, s[14:15]
	v_cmp_ngt_f32_e64 s[2:3], s56, v158
	v_cmp_ngt_f32_e64 s[14:15], s56, v160
	v_fmaak_f32 v247, v246, v247, 0x3de703be
	v_fmaak_f32 v254, v253, v254, 0x3de703be
	v_fmaak_f32 v247, v246, v247, 0xbec09330
	v_fmaak_f32 v254, v253, v254, 0xbec09330
	v_cndmask_b32_e64 v243, v234, v243, s[2:3]
	v_cndmask_b32_e64 v250, v234, v250, s[14:15]
	v_fmaak_f32 v246, v246, v247, 0x3e0375d0
	v_fmaak_f32 v253, v253, v254, 0x3e0375d0
	v_cmp_nlt_f32_e64 s[2:3], |v157|, 1.0
	v_cmp_nlt_f32_e64 s[14:15], |v159|, 1.0
	v_sub_f32_e32 v243, 1.0, v243
	v_sub_f32_e32 v250, 1.0, v250
	v_fma_f32 v246, |v157|, v246, |v157|
	v_fma_f32 v253, |v159|, v253, |v159|
	v_cndmask_b32_e64 v158, v246, v243, s[2:3]
	v_cndmask_b32_e64 v160, v253, v250, s[14:15]
	v_mul_f32_e32 v161, 0x3f3504f3, v18
	v_mul_f32_e32 v163, 0x3f3504f3, v19
	v_fma_f32 v162, |v161|, s48, v233
	v_fma_f32 v164, |v163|, s48, v233
	v_fma_f32 v162, |v161|, v162, s49
	v_fma_f32 v164, |v163|, v164, s49
	v_fma_f32 v162, |v161|, v162, s50
	v_fma_f32 v164, |v163|, v164, s50
	v_fma_f32 v162, |v161|, v162, s51
	v_fma_f32 v164, |v163|, v164, s51
	v_fma_f32 v162, |v161|, v162, s52
	v_fma_f32 v164, |v163|, v164, s52
	v_fma_f32 v162, |v161|, v162, s53
	v_fma_f32 v164, |v163|, v164, s53
	v_fma_f32 v162, |v161|, v162, |v161|
	v_fma_f32 v164, |v163|, v164, |v163|
	v_mul_f32_e32 v243, 0xbfb8aa3b, v162
	v_mul_f32_e32 v250, 0xbfb8aa3b, v164
	v_fma_f32 v244, v162, s54, -v243
	v_fma_f32 v251, v164, s54, -v250
	v_rndne_f32_e32 v245, v243
	v_rndne_f32_e32 v252, v250
	v_fmac_f32_e32 v244, 0xb2a5705f, v162
	v_fmac_f32_e32 v251, 0xb2a5705f, v164
	v_sub_f32_e32 v243, v243, v245
	v_sub_f32_e32 v250, v250, v252
	v_add_f32_e32 v243, v243, v244
	v_add_f32_e32 v250, v250, v251
	v_cvt_i32_f32_e32 v244, v245
	v_cvt_i32_f32_e32 v251, v252
	v_exp_f32_e32 v243, v243
	v_exp_f32_e32 v250, v250
	v_mul_f32_e32 v246, v161, v161
	v_mul_f32_e32 v253, v163, v163
	v_ldexp_f32 v243, v243, v244
	v_ldexp_f32 v250, v250, v251
	v_cmp_nlt_f32_e64 s[2:3], s55, v162
	v_cmp_nlt_f32_e64 s[14:15], s55, v164
	v_fmamk_f32 v247, v246, 0xba1345e1, v222
	v_fmamk_f32 v254, v253, 0xba1345e1, v222
	v_fmaak_f32 v247, v246, v247, 0xbcdac9b8
	v_fmaak_f32 v254, v253, v254, 0xbcdac9b8
	v_cndmask_b32_e64 v243, 0, v243, s[2:3]
	v_cndmask_b32_e64 v250, 0, v250, s[14:15]
	v_cmp_ngt_f32_e64 s[2:3], s56, v162
	v_cmp_ngt_f32_e64 s[14:15], s56, v164
	v_fmaak_f32 v247, v246, v247, 0x3de703be
	v_fmaak_f32 v254, v253, v254, 0x3de703be
	v_fmaak_f32 v247, v246, v247, 0xbec09330
	v_fmaak_f32 v254, v253, v254, 0xbec09330
	v_cndmask_b32_e64 v243, v234, v243, s[2:3]
	v_cndmask_b32_e64 v250, v234, v250, s[14:15]
	v_fmaak_f32 v246, v246, v247, 0x3e0375d0
	v_fmaak_f32 v253, v253, v254, 0x3e0375d0
	v_cmp_nlt_f32_e64 s[2:3], |v161|, 1.0
	v_cmp_nlt_f32_e64 s[14:15], |v163|, 1.0
	v_sub_f32_e32 v243, 1.0, v243
	v_sub_f32_e32 v250, 1.0, v250
	v_fma_f32 v246, |v161|, v246, |v161|
	v_fma_f32 v253, |v163|, v253, |v163|
	v_cndmask_b32_e64 v162, v246, v243, s[2:3]
	v_cndmask_b32_e64 v164, v253, v250, s[14:15]
	v_mul_f32_e32 v165, 0x3f3504f3, v20
	v_mul_f32_e32 v167, 0x3f3504f3, v21
	v_fma_f32 v166, |v165|, s48, v233
	v_fma_f32 v168, |v167|, s48, v233
	v_fma_f32 v166, |v165|, v166, s49
	v_fma_f32 v168, |v167|, v168, s49
	v_fma_f32 v166, |v165|, v166, s50
	v_fma_f32 v168, |v167|, v168, s50
	v_fma_f32 v166, |v165|, v166, s51
	v_fma_f32 v168, |v167|, v168, s51
	v_fma_f32 v166, |v165|, v166, s52
	v_fma_f32 v168, |v167|, v168, s52
	v_fma_f32 v166, |v165|, v166, s53
	v_fma_f32 v168, |v167|, v168, s53
	v_fma_f32 v166, |v165|, v166, |v165|
	v_fma_f32 v168, |v167|, v168, |v167|
	v_mul_f32_e32 v243, 0xbfb8aa3b, v166
	v_mul_f32_e32 v250, 0xbfb8aa3b, v168
	v_fma_f32 v244, v166, s54, -v243
	v_fma_f32 v251, v168, s54, -v250
	v_rndne_f32_e32 v245, v243
	v_rndne_f32_e32 v252, v250
	v_fmac_f32_e32 v244, 0xb2a5705f, v166
	v_fmac_f32_e32 v251, 0xb2a5705f, v168
	v_sub_f32_e32 v243, v243, v245
	v_sub_f32_e32 v250, v250, v252
	v_add_f32_e32 v243, v243, v244
	v_add_f32_e32 v250, v250, v251
	v_cvt_i32_f32_e32 v244, v245
	v_cvt_i32_f32_e32 v251, v252
	v_exp_f32_e32 v243, v243
	v_exp_f32_e32 v250, v250
	v_mul_f32_e32 v246, v165, v165
	v_mul_f32_e32 v253, v167, v167
	v_ldexp_f32 v243, v243, v244
	v_ldexp_f32 v250, v250, v251
	v_cmp_nlt_f32_e64 s[2:3], s55, v166
	v_cmp_nlt_f32_e64 s[14:15], s55, v168
	v_fmamk_f32 v247, v246, 0xba1345e1, v222
	v_fmamk_f32 v254, v253, 0xba1345e1, v222
	v_fmaak_f32 v247, v246, v247, 0xbcdac9b8
	v_fmaak_f32 v254, v253, v254, 0xbcdac9b8
	v_cndmask_b32_e64 v243, 0, v243, s[2:3]
	v_cndmask_b32_e64 v250, 0, v250, s[14:15]
	v_cmp_ngt_f32_e64 s[2:3], s56, v166
	v_cmp_ngt_f32_e64 s[14:15], s56, v168
	v_fmaak_f32 v247, v246, v247, 0x3de703be
	v_fmaak_f32 v254, v253, v254, 0x3de703be
	v_fmaak_f32 v247, v246, v247, 0xbec09330
	v_fmaak_f32 v254, v253, v254, 0xbec09330
	v_cndmask_b32_e64 v243, v234, v243, s[2:3]
	v_cndmask_b32_e64 v250, v234, v250, s[14:15]
	v_fmaak_f32 v246, v246, v247, 0x3e0375d0
	v_fmaak_f32 v253, v253, v254, 0x3e0375d0
	v_cmp_nlt_f32_e64 s[2:3], |v165|, 1.0
	v_cmp_nlt_f32_e64 s[14:15], |v167|, 1.0
	v_sub_f32_e32 v243, 1.0, v243
	v_sub_f32_e32 v250, 1.0, v250
	v_fma_f32 v246, |v165|, v246, |v165|
	v_fma_f32 v253, |v167|, v253, |v167|
	v_cndmask_b32_e64 v166, v246, v243, s[2:3]
	v_cndmask_b32_e64 v168, v253, v250, s[14:15]
	v_mul_f32_e32 v169, 0x3f3504f3, v22
	v_mul_f32_e32 v171, 0x3f3504f3, v23
	v_fma_f32 v170, |v169|, s48, v233
	v_fma_f32 v172, |v171|, s48, v233
	v_fma_f32 v170, |v169|, v170, s49
	v_fma_f32 v172, |v171|, v172, s49
	v_fma_f32 v170, |v169|, v170, s50
	v_fma_f32 v172, |v171|, v172, s50
	v_fma_f32 v170, |v169|, v170, s51
	v_fma_f32 v172, |v171|, v172, s51
	v_fma_f32 v170, |v169|, v170, s52
	v_fma_f32 v172, |v171|, v172, s52
	v_fma_f32 v170, |v169|, v170, s53
	v_fma_f32 v172, |v171|, v172, s53
	v_fma_f32 v170, |v169|, v170, |v169|
	v_fma_f32 v172, |v171|, v172, |v171|
	v_mul_f32_e32 v243, 0xbfb8aa3b, v170
	v_mul_f32_e32 v250, 0xbfb8aa3b, v172
	v_fma_f32 v244, v170, s54, -v243
	v_fma_f32 v251, v172, s54, -v250
	v_rndne_f32_e32 v245, v243
	v_rndne_f32_e32 v252, v250
	v_fmac_f32_e32 v244, 0xb2a5705f, v170
	v_fmac_f32_e32 v251, 0xb2a5705f, v172
	v_sub_f32_e32 v243, v243, v245
	v_sub_f32_e32 v250, v250, v252
	v_add_f32_e32 v243, v243, v244
	v_add_f32_e32 v250, v250, v251
	v_cvt_i32_f32_e32 v244, v245
	v_cvt_i32_f32_e32 v251, v252
	v_exp_f32_e32 v243, v243
	v_exp_f32_e32 v250, v250
	v_mul_f32_e32 v246, v169, v169
	v_mul_f32_e32 v253, v171, v171
	v_ldexp_f32 v243, v243, v244
	v_ldexp_f32 v250, v250, v251
	v_cmp_nlt_f32_e64 s[2:3], s55, v170
	v_cmp_nlt_f32_e64 s[14:15], s55, v172
	v_fmamk_f32 v247, v246, 0xba1345e1, v222
	v_fmamk_f32 v254, v253, 0xba1345e1, v222
	v_fmaak_f32 v247, v246, v247, 0xbcdac9b8
	v_fmaak_f32 v254, v253, v254, 0xbcdac9b8
	v_cndmask_b32_e64 v243, 0, v243, s[2:3]
	v_cndmask_b32_e64 v250, 0, v250, s[14:15]
	v_cmp_ngt_f32_e64 s[2:3], s56, v170
	v_cmp_ngt_f32_e64 s[14:15], s56, v172
	v_fmaak_f32 v247, v246, v247, 0x3de703be
	v_fmaak_f32 v254, v253, v254, 0x3de703be
	v_fmaak_f32 v247, v246, v247, 0xbec09330
	v_fmaak_f32 v254, v253, v254, 0xbec09330
	v_cndmask_b32_e64 v243, v234, v243, s[2:3]
	v_cndmask_b32_e64 v250, v234, v250, s[14:15]
	v_fmaak_f32 v246, v246, v247, 0x3e0375d0
	v_fmaak_f32 v253, v253, v254, 0x3e0375d0
	v_cmp_nlt_f32_e64 s[2:3], |v169|, 1.0
	v_cmp_nlt_f32_e64 s[14:15], |v171|, 1.0
	v_sub_f32_e32 v243, 1.0, v243
	v_sub_f32_e32 v250, 1.0, v250
	v_fma_f32 v246, |v169|, v246, |v169|
	v_fma_f32 v253, |v171|, v253, |v171|
	v_cndmask_b32_e64 v170, v246, v243, s[2:3]
	v_cndmask_b32_e64 v172, v253, v250, s[14:15]
	v_mul_f32_e32 v173, 0x3f3504f3, v24
	v_mul_f32_e32 v175, 0x3f3504f3, v25
	v_fma_f32 v174, |v173|, s48, v233
	v_fma_f32 v176, |v175|, s48, v233
	v_fma_f32 v174, |v173|, v174, s49
	v_fma_f32 v176, |v175|, v176, s49
	v_fma_f32 v174, |v173|, v174, s50
	v_fma_f32 v176, |v175|, v176, s50
	v_fma_f32 v174, |v173|, v174, s51
	v_fma_f32 v176, |v175|, v176, s51
	v_fma_f32 v174, |v173|, v174, s52
	v_fma_f32 v176, |v175|, v176, s52
	v_fma_f32 v174, |v173|, v174, s53
	v_fma_f32 v176, |v175|, v176, s53
	v_fma_f32 v174, |v173|, v174, |v173|
	v_fma_f32 v176, |v175|, v176, |v175|
	v_mul_f32_e32 v243, 0xbfb8aa3b, v174
	v_mul_f32_e32 v250, 0xbfb8aa3b, v176
	v_fma_f32 v244, v174, s54, -v243
	v_fma_f32 v251, v176, s54, -v250
	v_rndne_f32_e32 v245, v243
	v_rndne_f32_e32 v252, v250
	v_fmac_f32_e32 v244, 0xb2a5705f, v174
	v_fmac_f32_e32 v251, 0xb2a5705f, v176
	v_sub_f32_e32 v243, v243, v245
	v_sub_f32_e32 v250, v250, v252
	v_add_f32_e32 v243, v243, v244
	v_add_f32_e32 v250, v250, v251
	v_cvt_i32_f32_e32 v244, v245
	v_cvt_i32_f32_e32 v251, v252
	v_exp_f32_e32 v243, v243
	v_exp_f32_e32 v250, v250
	v_mul_f32_e32 v246, v173, v173
	v_mul_f32_e32 v253, v175, v175
	v_ldexp_f32 v243, v243, v244
	v_ldexp_f32 v250, v250, v251
	v_cmp_nlt_f32_e64 s[2:3], s55, v174
	v_cmp_nlt_f32_e64 s[14:15], s55, v176
	v_fmamk_f32 v247, v246, 0xba1345e1, v222
	v_fmamk_f32 v254, v253, 0xba1345e1, v222
	v_fmaak_f32 v247, v246, v247, 0xbcdac9b8
	v_fmaak_f32 v254, v253, v254, 0xbcdac9b8
	v_cndmask_b32_e64 v243, 0, v243, s[2:3]
	v_cndmask_b32_e64 v250, 0, v250, s[14:15]
	v_cmp_ngt_f32_e64 s[2:3], s56, v174
	v_cmp_ngt_f32_e64 s[14:15], s56, v176
	v_fmaak_f32 v247, v246, v247, 0x3de703be
	v_fmaak_f32 v254, v253, v254, 0x3de703be
	v_fmaak_f32 v247, v246, v247, 0xbec09330
	v_fmaak_f32 v254, v253, v254, 0xbec09330
	v_cndmask_b32_e64 v243, v234, v243, s[2:3]
	v_cndmask_b32_e64 v250, v234, v250, s[14:15]
	v_fmaak_f32 v246, v246, v247, 0x3e0375d0
	v_fmaak_f32 v253, v253, v254, 0x3e0375d0
	v_cmp_nlt_f32_e64 s[2:3], |v173|, 1.0
	v_cmp_nlt_f32_e64 s[14:15], |v175|, 1.0
	v_sub_f32_e32 v243, 1.0, v243
	v_sub_f32_e32 v250, 1.0, v250
	v_fma_f32 v246, |v173|, v246, |v173|
	v_fma_f32 v253, |v175|, v253, |v175|
	v_cndmask_b32_e64 v174, v246, v243, s[2:3]
	v_cndmask_b32_e64 v176, v253, v250, s[14:15]
	v_mul_f32_e32 v177, 0x3f3504f3, v26
	v_mul_f32_e32 v179, 0x3f3504f3, v27
	v_fma_f32 v178, |v177|, s48, v233
	v_fma_f32 v180, |v179|, s48, v233
	v_fma_f32 v178, |v177|, v178, s49
	v_fma_f32 v180, |v179|, v180, s49
	v_fma_f32 v178, |v177|, v178, s50
	v_fma_f32 v180, |v179|, v180, s50
	v_fma_f32 v178, |v177|, v178, s51
	v_fma_f32 v180, |v179|, v180, s51
	v_fma_f32 v178, |v177|, v178, s52
	v_fma_f32 v180, |v179|, v180, s52
	v_fma_f32 v178, |v177|, v178, s53
	v_fma_f32 v180, |v179|, v180, s53
	v_fma_f32 v178, |v177|, v178, |v177|
	v_fma_f32 v180, |v179|, v180, |v179|
	v_mul_f32_e32 v243, 0xbfb8aa3b, v178
	v_mul_f32_e32 v250, 0xbfb8aa3b, v180
	v_fma_f32 v244, v178, s54, -v243
	v_fma_f32 v251, v180, s54, -v250
	v_rndne_f32_e32 v245, v243
	v_rndne_f32_e32 v252, v250
	v_fmac_f32_e32 v244, 0xb2a5705f, v178
	v_fmac_f32_e32 v251, 0xb2a5705f, v180
	v_sub_f32_e32 v243, v243, v245
	v_sub_f32_e32 v250, v250, v252
	v_add_f32_e32 v243, v243, v244
	v_add_f32_e32 v250, v250, v251
	v_cvt_i32_f32_e32 v244, v245
	v_cvt_i32_f32_e32 v251, v252
	v_exp_f32_e32 v243, v243
	v_exp_f32_e32 v250, v250
	v_mul_f32_e32 v246, v177, v177
	v_mul_f32_e32 v253, v179, v179
	v_ldexp_f32 v243, v243, v244
	v_ldexp_f32 v250, v250, v251
	v_cmp_nlt_f32_e64 s[2:3], s55, v178
	v_cmp_nlt_f32_e64 s[14:15], s55, v180
	v_fmamk_f32 v247, v246, 0xba1345e1, v222
	v_fmamk_f32 v254, v253, 0xba1345e1, v222
	v_fmaak_f32 v247, v246, v247, 0xbcdac9b8
	v_fmaak_f32 v254, v253, v254, 0xbcdac9b8
	v_cndmask_b32_e64 v243, 0, v243, s[2:3]
	v_cndmask_b32_e64 v250, 0, v250, s[14:15]
	v_cmp_ngt_f32_e64 s[2:3], s56, v178
	v_cmp_ngt_f32_e64 s[14:15], s56, v180
	v_fmaak_f32 v247, v246, v247, 0x3de703be
	v_fmaak_f32 v254, v253, v254, 0x3de703be
	v_fmaak_f32 v247, v246, v247, 0xbec09330
	v_fmaak_f32 v254, v253, v254, 0xbec09330
	v_cndmask_b32_e64 v243, v234, v243, s[2:3]
	v_cndmask_b32_e64 v250, v234, v250, s[14:15]
	v_fmaak_f32 v246, v246, v247, 0x3e0375d0
	v_fmaak_f32 v253, v253, v254, 0x3e0375d0
	v_cmp_nlt_f32_e64 s[2:3], |v177|, 1.0
	v_cmp_nlt_f32_e64 s[14:15], |v179|, 1.0
	v_sub_f32_e32 v243, 1.0, v243
	v_sub_f32_e32 v250, 1.0, v250
	v_fma_f32 v246, |v177|, v246, |v177|
	v_fma_f32 v253, |v179|, v253, |v179|
	v_cndmask_b32_e64 v178, v246, v243, s[2:3]
	v_cndmask_b32_e64 v180, v253, v250, s[14:15]
	v_mul_f32_e32 v181, 0x3f3504f3, v28
	v_mul_f32_e32 v183, 0x3f3504f3, v29
	v_fma_f32 v182, |v181|, s48, v233
	v_fma_f32 v184, |v183|, s48, v233
	v_fma_f32 v182, |v181|, v182, s49
	v_fma_f32 v184, |v183|, v184, s49
	v_fma_f32 v182, |v181|, v182, s50
	v_fma_f32 v184, |v183|, v184, s50
	v_fma_f32 v182, |v181|, v182, s51
	v_fma_f32 v184, |v183|, v184, s51
	v_fma_f32 v182, |v181|, v182, s52
	v_fma_f32 v184, |v183|, v184, s52
	v_fma_f32 v182, |v181|, v182, s53
	v_fma_f32 v184, |v183|, v184, s53
	v_fma_f32 v182, |v181|, v182, |v181|
	v_fma_f32 v184, |v183|, v184, |v183|
	v_mul_f32_e32 v243, 0xbfb8aa3b, v182
	v_mul_f32_e32 v250, 0xbfb8aa3b, v184
	v_fma_f32 v244, v182, s54, -v243
	v_fma_f32 v251, v184, s54, -v250
	v_rndne_f32_e32 v245, v243
	v_rndne_f32_e32 v252, v250
	v_fmac_f32_e32 v244, 0xb2a5705f, v182
	v_fmac_f32_e32 v251, 0xb2a5705f, v184
	v_sub_f32_e32 v243, v243, v245
	v_sub_f32_e32 v250, v250, v252
	v_add_f32_e32 v243, v243, v244
	v_add_f32_e32 v250, v250, v251
	v_cvt_i32_f32_e32 v244, v245
	v_cvt_i32_f32_e32 v251, v252
	v_exp_f32_e32 v243, v243
	v_exp_f32_e32 v250, v250
	v_mul_f32_e32 v246, v181, v181
	v_mul_f32_e32 v253, v183, v183
	v_ldexp_f32 v243, v243, v244
	v_ldexp_f32 v250, v250, v251
	v_cmp_nlt_f32_e64 s[2:3], s55, v182
	v_cmp_nlt_f32_e64 s[14:15], s55, v184
	v_fmamk_f32 v247, v246, 0xba1345e1, v222
	v_fmamk_f32 v254, v253, 0xba1345e1, v222
	v_fmaak_f32 v247, v246, v247, 0xbcdac9b8
	v_fmaak_f32 v254, v253, v254, 0xbcdac9b8
	v_cndmask_b32_e64 v243, 0, v243, s[2:3]
	v_cndmask_b32_e64 v250, 0, v250, s[14:15]
	v_cmp_ngt_f32_e64 s[2:3], s56, v182
	v_cmp_ngt_f32_e64 s[14:15], s56, v184
	v_fmaak_f32 v247, v246, v247, 0x3de703be
	v_fmaak_f32 v254, v253, v254, 0x3de703be
	v_fmaak_f32 v247, v246, v247, 0xbec09330
	v_fmaak_f32 v254, v253, v254, 0xbec09330
	v_cndmask_b32_e64 v243, v234, v243, s[2:3]
	v_cndmask_b32_e64 v250, v234, v250, s[14:15]
	v_fmaak_f32 v246, v246, v247, 0x3e0375d0
	v_fmaak_f32 v253, v253, v254, 0x3e0375d0
	v_cmp_nlt_f32_e64 s[2:3], |v181|, 1.0
	v_cmp_nlt_f32_e64 s[14:15], |v183|, 1.0
	v_sub_f32_e32 v243, 1.0, v243
	v_sub_f32_e32 v250, 1.0, v250
	v_fma_f32 v246, |v181|, v246, |v181|
	v_fma_f32 v253, |v183|, v253, |v183|
	v_cndmask_b32_e64 v182, v246, v243, s[2:3]
	v_cndmask_b32_e64 v184, v253, v250, s[14:15]
	v_mul_f32_e32 v185, 0x3f3504f3, v30
	v_mul_f32_e32 v187, 0x3f3504f3, v31
	v_fma_f32 v186, |v185|, s48, v233
	v_fma_f32 v188, |v187|, s48, v233
	v_fma_f32 v186, |v185|, v186, s49
	v_fma_f32 v188, |v187|, v188, s49
	v_fma_f32 v186, |v185|, v186, s50
	v_fma_f32 v188, |v187|, v188, s50
	v_fma_f32 v186, |v185|, v186, s51
	v_fma_f32 v188, |v187|, v188, s51
	v_fma_f32 v186, |v185|, v186, s52
	v_fma_f32 v188, |v187|, v188, s52
	v_fma_f32 v186, |v185|, v186, s53
	v_fma_f32 v188, |v187|, v188, s53
	v_fma_f32 v186, |v185|, v186, |v185|
	v_fma_f32 v188, |v187|, v188, |v187|
	v_mul_f32_e32 v243, 0xbfb8aa3b, v186
	v_mul_f32_e32 v250, 0xbfb8aa3b, v188
	v_fma_f32 v244, v186, s54, -v243
	v_fma_f32 v251, v188, s54, -v250
	v_rndne_f32_e32 v245, v243
	v_rndne_f32_e32 v252, v250
	v_fmac_f32_e32 v244, 0xb2a5705f, v186
	v_fmac_f32_e32 v251, 0xb2a5705f, v188
	v_sub_f32_e32 v243, v243, v245
	v_sub_f32_e32 v250, v250, v252
	v_add_f32_e32 v243, v243, v244
	v_add_f32_e32 v250, v250, v251
	v_cvt_i32_f32_e32 v244, v245
	v_cvt_i32_f32_e32 v251, v252
	v_exp_f32_e32 v243, v243
	v_exp_f32_e32 v250, v250
	v_mul_f32_e32 v246, v185, v185
	v_mul_f32_e32 v253, v187, v187
	v_ldexp_f32 v243, v243, v244
	v_ldexp_f32 v250, v250, v251
	v_cmp_nlt_f32_e64 s[2:3], s55, v186
	v_cmp_nlt_f32_e64 s[14:15], s55, v188
	v_fmamk_f32 v247, v246, 0xba1345e1, v222
	v_fmamk_f32 v254, v253, 0xba1345e1, v222
	v_fmaak_f32 v247, v246, v247, 0xbcdac9b8
	v_fmaak_f32 v254, v253, v254, 0xbcdac9b8
	v_cndmask_b32_e64 v243, 0, v243, s[2:3]
	v_cndmask_b32_e64 v250, 0, v250, s[14:15]
	v_cmp_ngt_f32_e64 s[2:3], s56, v186
	v_cmp_ngt_f32_e64 s[14:15], s56, v188
	v_fmaak_f32 v247, v246, v247, 0x3de703be
	v_fmaak_f32 v254, v253, v254, 0x3de703be
	v_fmaak_f32 v247, v246, v247, 0xbec09330
	v_fmaak_f32 v254, v253, v254, 0xbec09330
	v_cndmask_b32_e64 v243, v234, v243, s[2:3]
	v_cndmask_b32_e64 v250, v234, v250, s[14:15]
	v_fmaak_f32 v246, v246, v247, 0x3e0375d0
	v_fmaak_f32 v253, v253, v254, 0x3e0375d0
	v_cmp_nlt_f32_e64 s[2:3], |v185|, 1.0
	v_cmp_nlt_f32_e64 s[14:15], |v187|, 1.0
	v_sub_f32_e32 v243, 1.0, v243
	v_sub_f32_e32 v250, 1.0, v250
	v_fma_f32 v246, |v185|, v246, |v185|
	v_fma_f32 v253, |v187|, v253, |v187|
	v_cndmask_b32_e64 v186, v246, v243, s[2:3]
	v_cndmask_b32_e64 v188, v253, v250, s[14:15]
	v_mul_f32_e32 v189, 0x3f3504f3, v0
	v_mul_f32_e32 v191, 0x3f3504f3, v1
	v_fma_f32 v190, |v189|, s48, v233
	v_fma_f32 v192, |v191|, s48, v233
	v_fma_f32 v190, |v189|, v190, s49
	v_fma_f32 v192, |v191|, v192, s49
	v_fma_f32 v190, |v189|, v190, s50
	v_fma_f32 v192, |v191|, v192, s50
	v_fma_f32 v190, |v189|, v190, s51
	v_fma_f32 v192, |v191|, v192, s51
	v_fma_f32 v190, |v189|, v190, s52
	v_fma_f32 v192, |v191|, v192, s52
	v_fma_f32 v190, |v189|, v190, s53
	v_fma_f32 v192, |v191|, v192, s53
	v_fma_f32 v190, |v189|, v190, |v189|
	v_fma_f32 v192, |v191|, v192, |v191|
	v_mul_f32_e32 v243, 0xbfb8aa3b, v190
	v_mul_f32_e32 v250, 0xbfb8aa3b, v192
	v_fma_f32 v244, v190, s54, -v243
	v_fma_f32 v251, v192, s54, -v250
	v_rndne_f32_e32 v245, v243
	v_rndne_f32_e32 v252, v250
	v_fmac_f32_e32 v244, 0xb2a5705f, v190
	v_fmac_f32_e32 v251, 0xb2a5705f, v192
	v_sub_f32_e32 v243, v243, v245
	v_sub_f32_e32 v250, v250, v252
	v_add_f32_e32 v243, v243, v244
	v_add_f32_e32 v250, v250, v251
	v_cvt_i32_f32_e32 v244, v245
	v_cvt_i32_f32_e32 v251, v252
	v_exp_f32_e32 v243, v243
	v_exp_f32_e32 v250, v250
	v_mul_f32_e32 v246, v189, v189
	v_mul_f32_e32 v253, v191, v191
	v_ldexp_f32 v243, v243, v244
	v_ldexp_f32 v250, v250, v251
	v_cmp_nlt_f32_e64 s[2:3], s55, v190
	v_cmp_nlt_f32_e64 s[14:15], s55, v192
	v_fmamk_f32 v247, v246, 0xba1345e1, v222
	v_fmamk_f32 v254, v253, 0xba1345e1, v222
	v_fmaak_f32 v247, v246, v247, 0xbcdac9b8
	v_fmaak_f32 v254, v253, v254, 0xbcdac9b8
	v_cndmask_b32_e64 v243, 0, v243, s[2:3]
	v_cndmask_b32_e64 v250, 0, v250, s[14:15]
	v_cmp_ngt_f32_e64 s[2:3], s56, v190
	v_cmp_ngt_f32_e64 s[14:15], s56, v192
	v_fmaak_f32 v247, v246, v247, 0x3de703be
	v_fmaak_f32 v254, v253, v254, 0x3de703be
	v_fmaak_f32 v247, v246, v247, 0xbec09330
	v_fmaak_f32 v254, v253, v254, 0xbec09330
	v_cndmask_b32_e64 v243, v234, v243, s[2:3]
	v_cndmask_b32_e64 v250, v234, v250, s[14:15]
	v_fmaak_f32 v246, v246, v247, 0x3e0375d0
	v_fmaak_f32 v253, v253, v254, 0x3e0375d0
	v_cmp_nlt_f32_e64 s[2:3], |v189|, 1.0
	v_cmp_nlt_f32_e64 s[14:15], |v191|, 1.0
	v_sub_f32_e32 v243, 1.0, v243
	v_sub_f32_e32 v250, 1.0, v250
	v_fma_f32 v246, |v189|, v246, |v189|
	v_fma_f32 v253, |v191|, v253, |v191|
	v_cndmask_b32_e64 v190, v246, v243, s[2:3]
	v_cndmask_b32_e64 v192, v253, v250, s[14:15]
	v_mul_f32_e32 v193, 0x3f3504f3, v2
	v_mul_f32_e32 v195, 0x3f3504f3, v3
	v_fma_f32 v194, |v193|, s48, v233
	v_fma_f32 v196, |v195|, s48, v233
	v_fma_f32 v194, |v193|, v194, s49
	v_fma_f32 v196, |v195|, v196, s49
	v_fma_f32 v194, |v193|, v194, s50
	v_fma_f32 v196, |v195|, v196, s50
	v_fma_f32 v194, |v193|, v194, s51
	v_fma_f32 v196, |v195|, v196, s51
	v_fma_f32 v194, |v193|, v194, s52
	v_fma_f32 v196, |v195|, v196, s52
	v_fma_f32 v194, |v193|, v194, s53
	v_fma_f32 v196, |v195|, v196, s53
	v_fma_f32 v194, |v193|, v194, |v193|
	v_fma_f32 v196, |v195|, v196, |v195|
	v_mul_f32_e32 v243, 0xbfb8aa3b, v194
	v_mul_f32_e32 v250, 0xbfb8aa3b, v196
	v_fma_f32 v244, v194, s54, -v243
	v_fma_f32 v251, v196, s54, -v250
	v_rndne_f32_e32 v245, v243
	v_rndne_f32_e32 v252, v250
	v_fmac_f32_e32 v244, 0xb2a5705f, v194
	v_fmac_f32_e32 v251, 0xb2a5705f, v196
	v_sub_f32_e32 v243, v243, v245
	v_sub_f32_e32 v250, v250, v252
	v_add_f32_e32 v243, v243, v244
	v_add_f32_e32 v250, v250, v251
	v_cvt_i32_f32_e32 v244, v245
	v_cvt_i32_f32_e32 v251, v252
	v_exp_f32_e32 v243, v243
	v_exp_f32_e32 v250, v250
	v_mul_f32_e32 v246, v193, v193
	v_mul_f32_e32 v253, v195, v195
	v_ldexp_f32 v243, v243, v244
	v_ldexp_f32 v250, v250, v251
	v_cmp_nlt_f32_e64 s[2:3], s55, v194
	v_cmp_nlt_f32_e64 s[14:15], s55, v196
	v_fmamk_f32 v247, v246, 0xba1345e1, v222
	v_fmamk_f32 v254, v253, 0xba1345e1, v222
	v_fmaak_f32 v247, v246, v247, 0xbcdac9b8
	v_fmaak_f32 v254, v253, v254, 0xbcdac9b8
	v_cndmask_b32_e64 v243, 0, v243, s[2:3]
	v_cndmask_b32_e64 v250, 0, v250, s[14:15]
	v_cmp_ngt_f32_e64 s[2:3], s56, v194
	v_cmp_ngt_f32_e64 s[14:15], s56, v196
	v_fmaak_f32 v247, v246, v247, 0x3de703be
	v_fmaak_f32 v254, v253, v254, 0x3de703be
	v_fmaak_f32 v247, v246, v247, 0xbec09330
	v_fmaak_f32 v254, v253, v254, 0xbec09330
	v_cndmask_b32_e64 v243, v234, v243, s[2:3]
	v_cndmask_b32_e64 v250, v234, v250, s[14:15]
	v_fmaak_f32 v246, v246, v247, 0x3e0375d0
	v_fmaak_f32 v253, v253, v254, 0x3e0375d0
	v_cmp_nlt_f32_e64 s[2:3], |v193|, 1.0
	v_cmp_nlt_f32_e64 s[14:15], |v195|, 1.0
	v_sub_f32_e32 v243, 1.0, v243
	v_sub_f32_e32 v250, 1.0, v250
	v_fma_f32 v246, |v193|, v246, |v193|
	v_fma_f32 v253, |v195|, v253, |v195|
	v_cndmask_b32_e64 v194, v246, v243, s[2:3]
	v_cndmask_b32_e64 v196, v253, v250, s[14:15]
	v_mul_f32_e32 v197, 0x3f3504f3, v4
	v_mul_f32_e32 v199, 0x3f3504f3, v5
	v_fma_f32 v198, |v197|, s48, v233
	v_fma_f32 v200, |v199|, s48, v233
	v_fma_f32 v198, |v197|, v198, s49
	v_fma_f32 v200, |v199|, v200, s49
	v_fma_f32 v198, |v197|, v198, s50
	v_fma_f32 v200, |v199|, v200, s50
	v_fma_f32 v198, |v197|, v198, s51
	v_fma_f32 v200, |v199|, v200, s51
	v_fma_f32 v198, |v197|, v198, s52
	v_fma_f32 v200, |v199|, v200, s52
	v_fma_f32 v198, |v197|, v198, s53
	v_fma_f32 v200, |v199|, v200, s53
	v_fma_f32 v198, |v197|, v198, |v197|
	v_fma_f32 v200, |v199|, v200, |v199|
	v_mul_f32_e32 v243, 0xbfb8aa3b, v198
	v_mul_f32_e32 v250, 0xbfb8aa3b, v200
	v_fma_f32 v244, v198, s54, -v243
	v_fma_f32 v251, v200, s54, -v250
	v_rndne_f32_e32 v245, v243
	v_rndne_f32_e32 v252, v250
	v_fmac_f32_e32 v244, 0xb2a5705f, v198
	v_fmac_f32_e32 v251, 0xb2a5705f, v200
	v_sub_f32_e32 v243, v243, v245
	v_sub_f32_e32 v250, v250, v252
	v_add_f32_e32 v243, v243, v244
	v_add_f32_e32 v250, v250, v251
	v_cvt_i32_f32_e32 v244, v245
	v_cvt_i32_f32_e32 v251, v252
	v_exp_f32_e32 v243, v243
	v_exp_f32_e32 v250, v250
	v_mul_f32_e32 v246, v197, v197
	v_mul_f32_e32 v253, v199, v199
	v_ldexp_f32 v243, v243, v244
	v_ldexp_f32 v250, v250, v251
	v_cmp_nlt_f32_e64 s[2:3], s55, v198
	v_cmp_nlt_f32_e64 s[14:15], s55, v200
	v_fmamk_f32 v247, v246, 0xba1345e1, v222
	v_fmamk_f32 v254, v253, 0xba1345e1, v222
	v_fmaak_f32 v247, v246, v247, 0xbcdac9b8
	v_fmaak_f32 v254, v253, v254, 0xbcdac9b8
	v_cndmask_b32_e64 v243, 0, v243, s[2:3]
	v_cndmask_b32_e64 v250, 0, v250, s[14:15]
	v_cmp_ngt_f32_e64 s[2:3], s56, v198
	v_cmp_ngt_f32_e64 s[14:15], s56, v200
	v_fmaak_f32 v247, v246, v247, 0x3de703be
	v_fmaak_f32 v254, v253, v254, 0x3de703be
	v_fmaak_f32 v247, v246, v247, 0xbec09330
	v_fmaak_f32 v254, v253, v254, 0xbec09330
	v_cndmask_b32_e64 v243, v234, v243, s[2:3]
	v_cndmask_b32_e64 v250, v234, v250, s[14:15]
	v_fmaak_f32 v246, v246, v247, 0x3e0375d0
	v_fmaak_f32 v253, v253, v254, 0x3e0375d0
	v_cmp_nlt_f32_e64 s[2:3], |v197|, 1.0
	v_cmp_nlt_f32_e64 s[14:15], |v199|, 1.0
	v_sub_f32_e32 v243, 1.0, v243
	v_sub_f32_e32 v250, 1.0, v250
	v_fma_f32 v246, |v197|, v246, |v197|
	v_fma_f32 v253, |v199|, v253, |v199|
	v_cndmask_b32_e64 v198, v246, v243, s[2:3]
	v_cndmask_b32_e64 v200, v253, v250, s[14:15]
	v_mul_f32_e32 v201, 0x3f3504f3, v6
	v_mul_f32_e32 v203, 0x3f3504f3, v7
	v_fma_f32 v202, |v201|, s48, v233
	v_fma_f32 v204, |v203|, s48, v233
	v_fma_f32 v202, |v201|, v202, s49
	v_fma_f32 v204, |v203|, v204, s49
	v_fma_f32 v202, |v201|, v202, s50
	v_fma_f32 v204, |v203|, v204, s50
	v_fma_f32 v202, |v201|, v202, s51
	v_fma_f32 v204, |v203|, v204, s51
	v_fma_f32 v202, |v201|, v202, s52
	v_fma_f32 v204, |v203|, v204, s52
	v_fma_f32 v202, |v201|, v202, s53
	v_fma_f32 v204, |v203|, v204, s53
	v_fma_f32 v202, |v201|, v202, |v201|
	v_fma_f32 v204, |v203|, v204, |v203|
	v_mul_f32_e32 v243, 0xbfb8aa3b, v202
	v_mul_f32_e32 v250, 0xbfb8aa3b, v204
	v_fma_f32 v244, v202, s54, -v243
	v_fma_f32 v251, v204, s54, -v250
	v_rndne_f32_e32 v245, v243
	v_rndne_f32_e32 v252, v250
	v_fmac_f32_e32 v244, 0xb2a5705f, v202
	v_fmac_f32_e32 v251, 0xb2a5705f, v204
	v_sub_f32_e32 v243, v243, v245
	v_sub_f32_e32 v250, v250, v252
	v_add_f32_e32 v243, v243, v244
	v_add_f32_e32 v250, v250, v251
	v_cvt_i32_f32_e32 v244, v245
	v_cvt_i32_f32_e32 v251, v252
	v_exp_f32_e32 v243, v243
	v_exp_f32_e32 v250, v250
	v_mul_f32_e32 v246, v201, v201
	v_mul_f32_e32 v253, v203, v203
	v_ldexp_f32 v243, v243, v244
	v_ldexp_f32 v250, v250, v251
	v_cmp_nlt_f32_e64 s[2:3], s55, v202
	v_cmp_nlt_f32_e64 s[14:15], s55, v204
	v_fmamk_f32 v247, v246, 0xba1345e1, v222
	v_fmamk_f32 v254, v253, 0xba1345e1, v222
	v_fmaak_f32 v247, v246, v247, 0xbcdac9b8
	v_fmaak_f32 v254, v253, v254, 0xbcdac9b8
	v_cndmask_b32_e64 v243, 0, v243, s[2:3]
	v_cndmask_b32_e64 v250, 0, v250, s[14:15]
	v_cmp_ngt_f32_e64 s[2:3], s56, v202
	v_cmp_ngt_f32_e64 s[14:15], s56, v204
	v_fmaak_f32 v247, v246, v247, 0x3de703be
	v_fmaak_f32 v254, v253, v254, 0x3de703be
	v_fmaak_f32 v247, v246, v247, 0xbec09330
	v_fmaak_f32 v254, v253, v254, 0xbec09330
	v_cndmask_b32_e64 v243, v234, v243, s[2:3]
	v_cndmask_b32_e64 v250, v234, v250, s[14:15]
	v_fmaak_f32 v246, v246, v247, 0x3e0375d0
	v_fmaak_f32 v253, v253, v254, 0x3e0375d0
	v_cmp_nlt_f32_e64 s[2:3], |v201|, 1.0
	v_cmp_nlt_f32_e64 s[14:15], |v203|, 1.0
	v_sub_f32_e32 v243, 1.0, v243
	v_sub_f32_e32 v250, 1.0, v250
	v_fma_f32 v246, |v201|, v246, |v201|
	v_fma_f32 v253, |v203|, v253, |v203|
	v_cndmask_b32_e64 v202, v246, v243, s[2:3]
	v_cndmask_b32_e64 v204, v253, v250, s[14:15]
	v_mul_f32_e32 v205, 0x3f3504f3, v8
	v_mul_f32_e32 v207, 0x3f3504f3, v9
	v_fma_f32 v206, |v205|, s48, v233
	v_fma_f32 v208, |v207|, s48, v233
	v_fma_f32 v206, |v205|, v206, s49
	v_fma_f32 v208, |v207|, v208, s49
	v_fma_f32 v206, |v205|, v206, s50
	v_fma_f32 v208, |v207|, v208, s50
	v_fma_f32 v206, |v205|, v206, s51
	v_fma_f32 v208, |v207|, v208, s51
	v_fma_f32 v206, |v205|, v206, s52
	v_fma_f32 v208, |v207|, v208, s52
	v_fma_f32 v206, |v205|, v206, s53
	v_fma_f32 v208, |v207|, v208, s53
	v_fma_f32 v206, |v205|, v206, |v205|
	v_fma_f32 v208, |v207|, v208, |v207|
	v_mul_f32_e32 v243, 0xbfb8aa3b, v206
	v_mul_f32_e32 v250, 0xbfb8aa3b, v208
	v_fma_f32 v244, v206, s54, -v243
	v_fma_f32 v251, v208, s54, -v250
	v_rndne_f32_e32 v245, v243
	v_rndne_f32_e32 v252, v250
	v_fmac_f32_e32 v244, 0xb2a5705f, v206
	v_fmac_f32_e32 v251, 0xb2a5705f, v208
	v_sub_f32_e32 v243, v243, v245
	v_sub_f32_e32 v250, v250, v252
	v_add_f32_e32 v243, v243, v244
	v_add_f32_e32 v250, v250, v251
	v_cvt_i32_f32_e32 v244, v245
	v_cvt_i32_f32_e32 v251, v252
	v_exp_f32_e32 v243, v243
	v_exp_f32_e32 v250, v250
	v_mul_f32_e32 v246, v205, v205
	v_mul_f32_e32 v253, v207, v207
	v_ldexp_f32 v243, v243, v244
	v_ldexp_f32 v250, v250, v251
	v_cmp_nlt_f32_e64 s[2:3], s55, v206
	v_cmp_nlt_f32_e64 s[14:15], s55, v208
	v_fmamk_f32 v247, v246, 0xba1345e1, v222
	v_fmamk_f32 v254, v253, 0xba1345e1, v222
	v_fmaak_f32 v247, v246, v247, 0xbcdac9b8
	v_fmaak_f32 v254, v253, v254, 0xbcdac9b8
	v_cndmask_b32_e64 v243, 0, v243, s[2:3]
	v_cndmask_b32_e64 v250, 0, v250, s[14:15]
	v_cmp_ngt_f32_e64 s[2:3], s56, v206
	v_cmp_ngt_f32_e64 s[14:15], s56, v208
	v_fmaak_f32 v247, v246, v247, 0x3de703be
	v_fmaak_f32 v254, v253, v254, 0x3de703be
	v_fmaak_f32 v247, v246, v247, 0xbec09330
	v_fmaak_f32 v254, v253, v254, 0xbec09330
	v_cndmask_b32_e64 v243, v234, v243, s[2:3]
	v_cndmask_b32_e64 v250, v234, v250, s[14:15]
	v_fmaak_f32 v246, v246, v247, 0x3e0375d0
	v_fmaak_f32 v253, v253, v254, 0x3e0375d0
	v_cmp_nlt_f32_e64 s[2:3], |v205|, 1.0
	v_cmp_nlt_f32_e64 s[14:15], |v207|, 1.0
	v_sub_f32_e32 v243, 1.0, v243
	v_sub_f32_e32 v250, 1.0, v250
	v_fma_f32 v246, |v205|, v246, |v205|
	v_fma_f32 v253, |v207|, v253, |v207|
	v_cndmask_b32_e64 v206, v246, v243, s[2:3]
	v_cndmask_b32_e64 v208, v253, v250, s[14:15]
	v_mul_f32_e32 v209, 0x3f3504f3, v10
	v_mul_f32_e32 v213, 0x3f3504f3, v11
	v_fma_f32 v211, |v209|, s48, v233
	v_fma_f32 v214, |v213|, s48, v233
	v_fma_f32 v211, |v209|, v211, s49
	v_fma_f32 v214, |v213|, v214, s49
	v_fma_f32 v211, |v209|, v211, s50
	v_fma_f32 v214, |v213|, v214, s50
	v_fma_f32 v211, |v209|, v211, s51
	v_fma_f32 v214, |v213|, v214, s51
	v_fma_f32 v211, |v209|, v211, s52
	v_fma_f32 v214, |v213|, v214, s52
	v_fma_f32 v211, |v209|, v211, s53
	v_fma_f32 v214, |v213|, v214, s53
	v_fma_f32 v211, |v209|, v211, |v209|
	v_fma_f32 v214, |v213|, v214, |v213|
	v_mul_f32_e32 v243, 0xbfb8aa3b, v211
	v_mul_f32_e32 v250, 0xbfb8aa3b, v214
	v_fma_f32 v244, v211, s54, -v243
	v_fma_f32 v251, v214, s54, -v250
	v_rndne_f32_e32 v245, v243
	v_rndne_f32_e32 v252, v250
	v_fmac_f32_e32 v244, 0xb2a5705f, v211
	v_fmac_f32_e32 v251, 0xb2a5705f, v214
	v_sub_f32_e32 v243, v243, v245
	v_sub_f32_e32 v250, v250, v252
	v_add_f32_e32 v243, v243, v244
	v_add_f32_e32 v250, v250, v251
	v_cvt_i32_f32_e32 v244, v245
	v_cvt_i32_f32_e32 v251, v252
	v_exp_f32_e32 v243, v243
	v_exp_f32_e32 v250, v250
	v_mul_f32_e32 v246, v209, v209
	v_mul_f32_e32 v253, v213, v213
	v_ldexp_f32 v243, v243, v244
	v_ldexp_f32 v250, v250, v251
	v_cmp_nlt_f32_e64 s[2:3], s55, v211
	v_cmp_nlt_f32_e64 s[14:15], s55, v214
	v_fmamk_f32 v247, v246, 0xba1345e1, v222
	v_fmamk_f32 v254, v253, 0xba1345e1, v222
	v_fmaak_f32 v247, v246, v247, 0xbcdac9b8
	v_fmaak_f32 v254, v253, v254, 0xbcdac9b8
	v_cndmask_b32_e64 v243, 0, v243, s[2:3]
	v_cndmask_b32_e64 v250, 0, v250, s[14:15]
	v_cmp_ngt_f32_e64 s[2:3], s56, v211
	v_cmp_ngt_f32_e64 s[14:15], s56, v214
	v_fmaak_f32 v247, v246, v247, 0x3de703be
	v_fmaak_f32 v254, v253, v254, 0x3de703be
	v_fmaak_f32 v247, v246, v247, 0xbec09330
	v_fmaak_f32 v254, v253, v254, 0xbec09330
	v_cndmask_b32_e64 v243, v234, v243, s[2:3]
	v_cndmask_b32_e64 v250, v234, v250, s[14:15]
	v_fmaak_f32 v246, v246, v247, 0x3e0375d0
	v_fmaak_f32 v253, v253, v254, 0x3e0375d0
	v_cmp_nlt_f32_e64 s[2:3], |v209|, 1.0
	v_cmp_nlt_f32_e64 s[14:15], |v213|, 1.0
	v_sub_f32_e32 v243, 1.0, v243
	v_sub_f32_e32 v250, 1.0, v250
	v_fma_f32 v246, |v209|, v246, |v209|
	v_fma_f32 v253, |v213|, v253, |v213|
	v_cndmask_b32_e64 v211, v246, v243, s[2:3]
	v_cndmask_b32_e64 v214, v253, v250, s[14:15]
	v_mul_f32_e32 v215, 0x3f3504f3, v12
	v_mul_f32_e32 v217, 0x3f3504f3, v13
	v_fma_f32 v216, |v215|, s48, v233
	v_fma_f32 v218, |v217|, s48, v233
	v_fma_f32 v216, |v215|, v216, s49
	v_fma_f32 v218, |v217|, v218, s49
	v_fma_f32 v216, |v215|, v216, s50
	v_fma_f32 v218, |v217|, v218, s50
	v_fma_f32 v216, |v215|, v216, s51
	v_fma_f32 v218, |v217|, v218, s51
	v_fma_f32 v216, |v215|, v216, s52
	v_fma_f32 v218, |v217|, v218, s52
	v_fma_f32 v216, |v215|, v216, s53
	v_fma_f32 v218, |v217|, v218, s53
	v_fma_f32 v216, |v215|, v216, |v215|
	v_fma_f32 v218, |v217|, v218, |v217|
	v_mul_f32_e32 v243, 0xbfb8aa3b, v216
	v_mul_f32_e32 v250, 0xbfb8aa3b, v218
	v_fma_f32 v244, v216, s54, -v243
	v_fma_f32 v251, v218, s54, -v250
	v_rndne_f32_e32 v245, v243
	v_rndne_f32_e32 v252, v250
	v_fmac_f32_e32 v244, 0xb2a5705f, v216
	v_fmac_f32_e32 v251, 0xb2a5705f, v218
	v_sub_f32_e32 v243, v243, v245
	v_sub_f32_e32 v250, v250, v252
	v_add_f32_e32 v243, v243, v244
	v_add_f32_e32 v250, v250, v251
	v_cvt_i32_f32_e32 v244, v245
	v_cvt_i32_f32_e32 v251, v252
	v_exp_f32_e32 v243, v243
	v_exp_f32_e32 v250, v250
	v_mul_f32_e32 v246, v215, v215
	v_mul_f32_e32 v253, v217, v217
	v_ldexp_f32 v243, v243, v244
	v_ldexp_f32 v250, v250, v251
	v_cmp_nlt_f32_e64 s[2:3], s55, v216
	v_cmp_nlt_f32_e64 s[14:15], s55, v218
	v_fmamk_f32 v247, v246, 0xba1345e1, v222
	v_fmamk_f32 v254, v253, 0xba1345e1, v222
	v_fmaak_f32 v247, v246, v247, 0xbcdac9b8
	v_fmaak_f32 v254, v253, v254, 0xbcdac9b8
	v_cndmask_b32_e64 v243, 0, v243, s[2:3]
	v_cndmask_b32_e64 v250, 0, v250, s[14:15]
	v_cmp_ngt_f32_e64 s[2:3], s56, v216
	v_cmp_ngt_f32_e64 s[14:15], s56, v218
	v_fmaak_f32 v247, v246, v247, 0x3de703be
	v_fmaak_f32 v254, v253, v254, 0x3de703be
	v_fmaak_f32 v247, v246, v247, 0xbec09330
	v_fmaak_f32 v254, v253, v254, 0xbec09330
	v_cndmask_b32_e64 v243, v234, v243, s[2:3]
	v_cndmask_b32_e64 v250, v234, v250, s[14:15]
	v_fmaak_f32 v246, v246, v247, 0x3e0375d0
	v_fmaak_f32 v253, v253, v254, 0x3e0375d0
	v_cmp_nlt_f32_e64 s[2:3], |v215|, 1.0
	v_cmp_nlt_f32_e64 s[14:15], |v217|, 1.0
	v_sub_f32_e32 v243, 1.0, v243
	v_sub_f32_e32 v250, 1.0, v250
	v_fma_f32 v246, |v215|, v246, |v215|
	v_fma_f32 v253, |v217|, v253, |v217|
	v_cndmask_b32_e64 v216, v246, v243, s[2:3]
	v_cndmask_b32_e64 v218, v253, v250, s[14:15]
	v_mul_f32_e32 v219, 0x3f3504f3, v14
	v_mul_f32_e32 v210, 0x3f3504f3, v15
	v_fma_f32 v239, |v219|, s48, v233
	v_fma_f32 v212, |v210|, s48, v233
	v_fma_f32 v239, |v219|, v239, s49
	v_fma_f32 v212, |v210|, v212, s49
	v_fma_f32 v239, |v219|, v239, s50
	v_fma_f32 v212, |v210|, v212, s50
	v_fma_f32 v239, |v219|, v239, s51
	v_fma_f32 v212, |v210|, v212, s51
	v_fma_f32 v239, |v219|, v239, s52
	v_fma_f32 v212, |v210|, v212, s52
	v_fma_f32 v239, |v219|, v239, s53
	v_fma_f32 v212, |v210|, v212, s53
	v_fma_f32 v239, |v219|, v239, |v219|
	v_fma_f32 v212, |v210|, v212, |v210|
	v_mul_f32_e32 v243, 0xbfb8aa3b, v239
	v_mul_f32_e32 v250, 0xbfb8aa3b, v212
	v_fma_f32 v244, v239, s54, -v243
	v_fma_f32 v251, v212, s54, -v250
	v_rndne_f32_e32 v245, v243
	v_rndne_f32_e32 v252, v250
	v_fmac_f32_e32 v244, 0xb2a5705f, v239
	v_fmac_f32_e32 v251, 0xb2a5705f, v212
	v_sub_f32_e32 v243, v243, v245
	v_sub_f32_e32 v250, v250, v252
	v_add_f32_e32 v243, v243, v244
	v_add_f32_e32 v250, v250, v251
	v_cvt_i32_f32_e32 v244, v245
	v_cvt_i32_f32_e32 v251, v252
	v_exp_f32_e32 v243, v243
	v_exp_f32_e32 v250, v250
	v_mul_f32_e32 v246, v219, v219
	v_mul_f32_e32 v253, v210, v210
	v_ldexp_f32 v243, v243, v244
	v_ldexp_f32 v250, v250, v251
	v_cmp_nlt_f32_e64 s[2:3], s55, v239
	v_cmp_nlt_f32_e64 s[14:15], s55, v212
	v_fmamk_f32 v247, v246, 0xba1345e1, v222
	v_fmamk_f32 v254, v253, 0xba1345e1, v222
	v_fmaak_f32 v247, v246, v247, 0xbcdac9b8
	v_fmaak_f32 v254, v253, v254, 0xbcdac9b8
	v_cndmask_b32_e64 v243, 0, v243, s[2:3]
	v_cndmask_b32_e64 v250, 0, v250, s[14:15]
	v_cmp_ngt_f32_e64 s[2:3], s56, v239
	v_cmp_ngt_f32_e64 s[14:15], s56, v212
	v_fmaak_f32 v247, v246, v247, 0x3de703be
	v_fmaak_f32 v254, v253, v254, 0x3de703be
	v_fmaak_f32 v247, v246, v247, 0xbec09330
	v_fmaak_f32 v254, v253, v254, 0xbec09330
	v_cndmask_b32_e64 v243, v234, v243, s[2:3]
	v_cndmask_b32_e64 v250, v234, v250, s[14:15]
	v_fmaak_f32 v246, v246, v247, 0x3e0375d0
	v_fmaak_f32 v253, v253, v254, 0x3e0375d0
	v_cmp_nlt_f32_e64 s[2:3], |v219|, 1.0
	v_cmp_nlt_f32_e64 s[14:15], |v210|, 1.0
	v_sub_f32_e32 v243, 1.0, v243
	v_sub_f32_e32 v250, 1.0, v250
	v_fma_f32 v246, |v219|, v246, |v219|
	v_fma_f32 v253, |v210|, v253, |v210|
	v_cndmask_b32_e64 v239, v246, v243, s[2:3]
	v_cndmask_b32_e64 v212, v253, v250, s[14:15]
	s_brev_b32 s2, -2
	v_bfi_b32 v67, s2, v68, v67
	v_mul_f32_e32 v48, 0.5, v48
	v_add_f32_e32 v67, 1.0, v67
	v_bfi_b32 v205, s2, v206, v205
	v_bfi_b32 v197, s2, v198, v197
	v_bfi_b32 v189, s2, v190, v189
	v_bfi_b32 v181, s2, v182, v181
	v_bfi_b32 v173, s2, v174, v173
	v_bfi_b32 v165, s2, v166, v165
	v_bfi_b32 v157, s2, v158, v157
	v_bfi_b32 v149, s2, v150, v149
	v_bfi_b32 v141, s2, v142, v141
	v_bfi_b32 v133, s2, v134, v133
	v_bfi_b32 v125, s2, v126, v125
	v_bfi_b32 v117, s2, v118, v117
	v_bfi_b32 v107, s2, v108, v107
	v_bfi_b32 v99, s2, v100, v99
	v_mul_f32_e32 v48, v48, v67
	v_bfi_b32 v67, s2, v70, v69
	v_mul_f32_e32 v8, 0.5, v8
	v_add_f32_e32 v205, 1.0, v205
	v_mul_f32_e32 v4, 0.5, v4
	v_add_f32_e32 v197, 1.0, v197
	v_mul_f32_e32 v0, 0.5, v0
	v_add_f32_e32 v189, 1.0, v189
	v_mul_f32_e32 v28, 0.5, v28
	v_add_f32_e32 v181, 1.0, v181
	v_mul_f32_e32 v24, 0.5, v24
	v_add_f32_e32 v173, 1.0, v173
	v_mul_f32_e32 v20, 0.5, v20
	v_add_f32_e32 v165, 1.0, v165
	v_mul_f32_e32 v16, 0.5, v16
	v_add_f32_e32 v157, 1.0, v157
	v_mul_f32_e32 v44, 0.5, v44
	v_add_f32_e32 v149, 1.0, v149
	v_mul_f32_e32 v40, 0.5, v40
	v_add_f32_e32 v141, 1.0, v141
	v_mul_f32_e32 v36, 0.5, v36
	v_add_f32_e32 v133, 1.0, v133
	v_mul_f32_e32 v32, 0.5, v32
	v_add_f32_e32 v125, 1.0, v125
	v_mul_f32_e32 v60, 0.5, v60
	v_add_f32_e32 v117, 1.0, v117
	v_mul_f32_e32 v56, 0.5, v56
	v_add_f32_e32 v107, 1.0, v107
	v_mul_f32_e32 v52, 0.5, v52
	v_add_f32_e32 v99, 1.0, v99
	v_mul_f32_e32 v49, 0.5, v49
	v_add_f32_e32 v67, 1.0, v67
	v_bfi_b32 v215, s2, v216, v215
	v_mul_f32_e32 v8, v8, v205
	v_bfi_b32 v205, s2, v208, v207
	v_mul_f32_e32 v4, v4, v197
	v_bfi_b32 v197, s2, v200, v199
	v_mul_f32_e32 v0, v0, v189
	v_bfi_b32 v189, s2, v192, v191
	v_mul_f32_e32 v28, v28, v181
	v_bfi_b32 v181, s2, v184, v183
	v_mul_f32_e32 v24, v24, v173
	v_bfi_b32 v173, s2, v176, v175
	v_mul_f32_e32 v20, v20, v165
	v_bfi_b32 v165, s2, v168, v167
	v_mul_f32_e32 v16, v16, v157
	v_bfi_b32 v157, s2, v160, v159
	v_mul_f32_e32 v44, v44, v149
	v_bfi_b32 v149, s2, v152, v151
	v_mul_f32_e32 v40, v40, v141
	v_bfi_b32 v141, s2, v144, v143
	v_mul_f32_e32 v36, v36, v133
	v_bfi_b32 v133, s2, v136, v135
	v_mul_f32_e32 v32, v32, v125
	v_bfi_b32 v125, s2, v128, v127
	v_mul_f32_e32 v60, v60, v117
	v_bfi_b32 v117, s2, v120, v119
	v_mul_f32_e32 v56, v56, v107
	v_bfi_b32 v107, s2, v110, v109
	v_mul_f32_e32 v52, v52, v99
	v_bfi_b32 v99, s2, v102, v101
	v_mul_f32_e32 v49, v49, v67
	v_bfi_b32 v67, s2, v96, v71
	v_mul_f32_e32 v12, 0.5, v12
	v_add_f32_e32 v215, 1.0, v215
	v_mul_f32_e32 v9, 0.5, v9
	v_add_f32_e32 v205, 1.0, v205
	v_mul_f32_e32 v5, 0.5, v5
	v_add_f32_e32 v197, 1.0, v197
	v_mul_f32_e32 v1, 0.5, v1
	v_add_f32_e32 v189, 1.0, v189
	v_mul_f32_e32 v29, 0.5, v29
	v_add_f32_e32 v181, 1.0, v181
	v_mul_f32_e32 v25, 0.5, v25
	v_add_f32_e32 v173, 1.0, v173
	v_mul_f32_e32 v21, 0.5, v21
	v_add_f32_e32 v165, 1.0, v165
	v_mul_f32_e32 v17, 0.5, v17
	v_add_f32_e32 v157, 1.0, v157
	v_mul_f32_e32 v45, 0.5, v45
	v_add_f32_e32 v149, 1.0, v149
	v_mul_f32_e32 v41, 0.5, v41
	v_add_f32_e32 v141, 1.0, v141
	v_mul_f32_e32 v37, 0.5, v37
	v_add_f32_e32 v133, 1.0, v133
	v_mul_f32_e32 v33, 0.5, v33
	v_add_f32_e32 v125, 1.0, v125
	v_mul_f32_e32 v61, 0.5, v61
	v_add_f32_e32 v117, 1.0, v117
	v_mul_f32_e32 v57, 0.5, v57
	v_add_f32_e32 v107, 1.0, v107
	v_mul_f32_e32 v53, 0.5, v53
	v_add_f32_e32 v99, 1.0, v99
	v_mul_f32_e32 v50, 0.5, v50
	v_add_f32_e32 v67, 1.0, v67
	v_mul_f32_e32 v12, v12, v215
	v_bfi_b32 v215, s2, v218, v217
	v_mul_f32_e32 v9, v9, v205
	v_bfi_b32 v205, s2, v211, v209
	v_mul_f32_e32 v5, v5, v197
	v_bfi_b32 v197, s2, v202, v201
	v_mul_f32_e32 v1, v1, v189
	v_bfi_b32 v189, s2, v194, v193
	v_mul_f32_e32 v29, v29, v181
	v_bfi_b32 v181, s2, v186, v185
	v_mul_f32_e32 v25, v25, v173
	v_bfi_b32 v173, s2, v178, v177
	v_mul_f32_e32 v21, v21, v165
	v_bfi_b32 v165, s2, v170, v169
	v_mul_f32_e32 v17, v17, v157
	v_bfi_b32 v157, s2, v162, v161
	v_mul_f32_e32 v45, v45, v149
	v_bfi_b32 v149, s2, v154, v153
	v_mul_f32_e32 v41, v41, v141
	v_bfi_b32 v141, s2, v146, v145
	v_mul_f32_e32 v37, v37, v133
	v_bfi_b32 v133, s2, v138, v137
	v_mul_f32_e32 v33, v33, v125
	v_bfi_b32 v125, s2, v130, v129
	v_mul_f32_e32 v61, v61, v117
	v_bfi_b32 v117, s2, v122, v121
	v_mul_f32_e32 v57, v57, v107
	v_bfi_b32 v107, s2, v112, v111
	v_mul_f32_e32 v53, v53, v99
	v_bfi_b32 v99, s2, v104, v103
	v_mul_f32_e32 v50, v50, v67
	v_bfi_b32 v67, s2, v98, v97
	v_mul_f32_e32 v13, 0.5, v13
	v_add_f32_e32 v215, 1.0, v215
	v_mul_f32_e32 v10, 0.5, v10
	v_add_f32_e32 v205, 1.0, v205
	v_mul_f32_e32 v6, 0.5, v6
	v_add_f32_e32 v197, 1.0, v197
	v_mul_f32_e32 v2, 0.5, v2
	v_add_f32_e32 v189, 1.0, v189
	v_mul_f32_e32 v30, 0.5, v30
	v_add_f32_e32 v181, 1.0, v181
	v_mul_f32_e32 v26, 0.5, v26
	v_add_f32_e32 v173, 1.0, v173
	v_mul_f32_e32 v22, 0.5, v22
	v_add_f32_e32 v165, 1.0, v165
	v_mul_f32_e32 v18, 0.5, v18
	v_add_f32_e32 v157, 1.0, v157
	v_mul_f32_e32 v46, 0.5, v46
	v_add_f32_e32 v149, 1.0, v149
	v_mul_f32_e32 v42, 0.5, v42
	v_add_f32_e32 v141, 1.0, v141
	v_mul_f32_e32 v38, 0.5, v38
	v_add_f32_e32 v133, 1.0, v133
	v_mul_f32_e32 v34, 0.5, v34
	v_add_f32_e32 v125, 1.0, v125
	v_mul_f32_e32 v62, 0.5, v62
	v_add_f32_e32 v117, 1.0, v117
	v_mul_f32_e32 v58, 0.5, v58
	v_add_f32_e32 v107, 1.0, v107
	v_mul_f32_e32 v54, 0.5, v54
	v_add_f32_e32 v99, 1.0, v99
	v_mul_f32_e32 v51, 0.5, v51
	v_add_f32_e32 v67, 1.0, v67
	v_mul_f32_e32 v13, v13, v215
	v_bfi_b32 v215, s2, v239, v219
	v_mul_f32_e32 v10, v10, v205
	v_bfi_b32 v205, s2, v214, v213
	v_mul_f32_e32 v6, v6, v197
	v_bfi_b32 v197, s2, v204, v203
	v_mul_f32_e32 v2, v2, v189
	v_bfi_b32 v189, s2, v196, v195
	v_mul_f32_e32 v30, v30, v181
	v_bfi_b32 v181, s2, v188, v187
	v_mul_f32_e32 v26, v26, v173
	v_bfi_b32 v173, s2, v180, v179
	v_mul_f32_e32 v22, v22, v165
	v_bfi_b32 v165, s2, v172, v171
	v_mul_f32_e32 v18, v18, v157
	v_bfi_b32 v157, s2, v164, v163
	v_mul_f32_e32 v46, v46, v149
	v_bfi_b32 v149, s2, v156, v155
	v_mul_f32_e32 v42, v42, v141
	v_bfi_b32 v141, s2, v148, v147
	v_mul_f32_e32 v38, v38, v133
	v_bfi_b32 v133, s2, v140, v139
	v_mul_f32_e32 v34, v34, v125
	v_bfi_b32 v125, s2, v132, v131
	v_mul_f32_e32 v62, v62, v117
	v_bfi_b32 v117, s2, v124, v123
	v_mul_f32_e32 v58, v58, v107
	v_bfi_b32 v107, s2, v116, v113
	v_mul_f32_e32 v54, v54, v99
	v_bfi_b32 v99, s2, v106, v105
	v_mul_f32_e32 v51, v51, v67
	v_bfi_b32 v67, s2, v212, v210
	v_mul_f32_e32 v14, 0.5, v14
	v_add_f32_e32 v215, 1.0, v215
	v_mul_f32_e32 v11, 0.5, v11
	v_add_f32_e32 v205, 1.0, v205
	v_mul_f32_e32 v7, 0.5, v7
	v_add_f32_e32 v197, 1.0, v197
	v_mul_f32_e32 v3, 0.5, v3
	v_add_f32_e32 v189, 1.0, v189
	v_mul_f32_e32 v31, 0.5, v31
	v_add_f32_e32 v181, 1.0, v181
	v_mul_f32_e32 v27, 0.5, v27
	v_add_f32_e32 v173, 1.0, v173
	v_mul_f32_e32 v23, 0.5, v23
	v_add_f32_e32 v165, 1.0, v165
	v_mul_f32_e32 v19, 0.5, v19
	v_add_f32_e32 v157, 1.0, v157
	v_mul_f32_e32 v47, 0.5, v47
	v_add_f32_e32 v149, 1.0, v149
	v_mul_f32_e32 v43, 0.5, v43
	v_add_f32_e32 v141, 1.0, v141
	v_mul_f32_e32 v39, 0.5, v39
	v_add_f32_e32 v133, 1.0, v133
	v_mul_f32_e32 v35, 0.5, v35
	v_add_f32_e32 v125, 1.0, v125
	v_mul_f32_e32 v63, 0.5, v63
	v_add_f32_e32 v117, 1.0, v117
	v_mul_f32_e32 v59, 0.5, v59
	v_add_f32_e32 v107, 1.0, v107
	v_mul_f32_e32 v55, 0.5, v55
	v_add_f32_e32 v99, 1.0, v99
	v_mul_f32_e32 v15, 0.5, v15
	v_add_f32_e32 v67, 1.0, v67
	v_mul_f32_e32 v14, v14, v215
	v_mul_f32_e32 v11, v11, v205
	v_mul_f32_e32 v7, v7, v197
	v_mul_f32_e32 v3, v3, v189
	v_mul_f32_e32 v31, v31, v181
	v_mul_f32_e32 v27, v27, v173
	v_mul_f32_e32 v23, v23, v165
	v_mul_f32_e32 v19, v19, v157
	v_mul_f32_e32 v47, v47, v149
	v_mul_f32_e32 v43, v43, v141
	v_mul_f32_e32 v39, v39, v133
	v_mul_f32_e32 v35, v35, v125
	v_mul_f32_e32 v63, v63, v117
	v_mul_f32_e32 v59, v59, v107
	v_mul_f32_e32 v55, v55, v99
	v_mul_f32_e32 v15, v15, v67
